# adds: same transposed-read read-ahead in the D / B / C mixer PV blocks
# baseline (speedup 1.0000x reference)
; template <int KIND>
; __device__ __forceinline__ void softmax_tile(f32x16& s0, f32x16& s1, float& l, int t, int k0, int h, int qlo, const LAS float* lut, const LAS float* cb, int W, int dmask, float rowshift) {
;     ...
; #pragma unroll
;         for (int i = 0; i < 16; ++i) {
;             const int j0 = k0 + (i & 3) + 8 * (i >> 2) + 4 * h, n0 = t - j0, n1 = n0 - 32;
;             const float b0 = lut[min(max(n0, 0), 128)], b1 = lut[min(max(n1, 0), 128)];
;             const bool v0 = (n0 >= 0) && (n0 <= W) && ((n0 & dmask) == 0), v1 = (n1 >= 0) && (n1 <= W) && ((n1 & dmask) == 0);
;             s0[i] = v0 ? s0[i] + b0 : NINF; s1[i] = v1 ? s1[i] + b1 : NINF;
;         }
.LBB0_537:
	v_add_u32_e32 v0, 64, v114
	v_cmp_le_i32_e32 vcc, v0, v109
	v_add_u32_e32 v0, 0x7f, v114
	v_cmp_ge_i32_e64 s[20:21], v0, v110
	s_and_b64 vcc, vcc, s[20:21]
	s_and_saveexec_b64 s[20:21], vcc
	s_cbranch_execz .LBB0_539
	v_add_u32_e32 v0, 0, v199
	ds_read_b128 v[10:13], v0
	ds_read_b128 v[116:119], v0 offset:32
	v_add_u32_e32 v14, 59, v113
	v_max_i32_e32 v15, 32, v14
	v_subrev_u32_e32 v15, 32, v15
	s_waitcnt lgkmcnt(1)
	v_mfma_f32_32x32x16_bf16 v[48:63], v[10:13], v[80:83], 0
	ds_read_b128 v[10:13], v0 offset:4608
	ds_read_b128 v[120:123], v0 offset:4640
	v_min_u32_e32 v15, 0x80, v15
	v_lshl_add_u32 v15, v15, 2, s67
	v_cmp_gt_u32_e32 vcc, s0, v14
	s_waitcnt lgkmcnt(1)
	v_mfma_f32_32x32x16_bf16 v[64:79], v[10:13], v[80:83], 0
	ds_read_b128 v[10:13], v0 offset:64
	ds_read_b128 v[124:127], v0 offset:96
	ds_read_b128 v[128:131], v0 offset:4672
	ds_read_b128 v[132:135], v0 offset:4704
	v_med3_i32 v0, v14, 0, v237
	v_lshl_add_u32 v0, v0, 2, s67
	v_mfma_f32_32x32x16_bf16 v[48:63], v[116:119], v[84:87], v[48:63]
	v_add_u32_e32 v117, 58, v113
	v_max_i32_e32 v119, 32, v117
	v_subrev_u32_e32 v119, 32, v119
	v_med3_i32 v118, v117, 0, v237
	v_min_u32_e32 v119, 0x80, v119
	v_lshl_add_u32 v118, v118, 2, s67
	v_lshl_add_u32 v119, v119, 2, s67
	s_waitcnt lgkmcnt(4)
	v_mfma_f32_32x32x16_bf16 v[64:79], v[120:123], v[84:87], v[64:79]
	v_add_u32_e32 v116, 27, v113
	s_waitcnt lgkmcnt(3)
	v_mfma_f32_32x32x16_bf16 v[48:63], v[10:13], v[88:91], v[48:63]
	v_add_u32_e32 v10, 57, v113
	v_add_u32_e32 v13, 56, v113
	v_max_i32_e32 v12, 32, v10
	v_max_i32_e32 v121, 32, v13
	v_subrev_u32_e32 v12, 32, v12
	v_subrev_u32_e32 v121, 32, v121
	v_med3_i32 v11, v10, 0, v237
	s_waitcnt lgkmcnt(1)
	v_mfma_f32_32x32x16_bf16 v[64:79], v[128:131], v[88:91], v[64:79]
	v_min_u32_e32 v12, 0x80, v12
	v_med3_i32 v120, v13, 0, v237
	v_min_u32_e32 v121, 0x80, v121
	v_lshl_add_u32 v11, v11, 2, s67
	v_lshl_add_u32 v12, v12, 2, s67
	v_lshl_add_u32 v120, v120, 2, s67
	v_lshl_add_u32 v121, v121, 2, s67
	v_mfma_f32_32x32x16_bf16 v[48:63], v[124:127], v[92:95], v[48:63]
	ds_read_b32 v0, v0
	ds_read_b32 v15, v15
	ds_read_b32 v118, v118
	ds_read_b32 v119, v119
	ds_read_b32 v11, v11
	ds_read_b32 v12, v12
	ds_read_b32 v120, v120
	ds_read_b32 v121, v121
	s_waitcnt lgkmcnt(7)
	s_nop 2
	v_add_f32_e32 v0, v48, v0
	v_mfma_f32_32x32x16_bf16 v[64:79], v[132:135], v[92:95], v[64:79]
	v_cndmask_b32_e32 v0, v238, v0, vcc
	v_cmp_gt_u32_e32 vcc, s0, v116
	s_waitcnt lgkmcnt(5)
	v_add_f32_e32 v48, v49, v118
	s_waitcnt lgkmcnt(3)
	v_add_f32_e32 v11, v50, v11
	v_add_u32_e32 v116, 49, v113
	v_max_i32_e32 v118, 32, v116
	v_subrev_u32_e32 v118, 32, v118
	s_nop 2
	v_add_f32_e32 v14, v64, v15
	v_cndmask_b32_e32 v14, v238, v14, vcc
	v_add_u32_e32 v15, 26, v113
	v_cmp_gt_u32_e32 vcc, s0, v117
	v_add_f32_e32 v49, v65, v119
	v_add_u32_e32 v65, 50, v113
	v_cndmask_b32_e32 v48, v238, v48, vcc
	v_cmp_gt_u32_e32 vcc, s0, v15
	v_add_u32_e32 v15, 25, v113
	v_add_u32_e32 v119, 48, v113
	v_cndmask_b32_e32 v49, v238, v49, vcc
	v_cmp_gt_u32_e32 vcc, s0, v10
	v_med3_i32 v117, v116, 0, v237
	v_min_u32_e32 v118, 0x80, v118
	v_cndmask_b32_e32 v10, v238, v11, vcc
	s_waitcnt lgkmcnt(2)
	v_add_f32_e32 v11, v66, v12
	v_cmp_gt_u32_e32 vcc, s0, v15
	v_add_u32_e32 v12, 24, v113
	s_waitcnt lgkmcnt(1)
	v_add_f32_e32 v15, v51, v120
	v_cndmask_b32_e32 v11, v238, v11, vcc
	v_cmp_gt_u32_e32 vcc, s0, v13
	v_med3_i32 v66, v65, 0, v237
	v_med3_i32 v120, v119, 0, v237
	v_cndmask_b32_e32 v13, v238, v15, vcc
	s_waitcnt lgkmcnt(0)
	v_add_f32_e32 v15, v67, v121
	v_cmp_gt_u32_e32 vcc, s0, v12
	v_max_i32_e32 v67, 32, v65
	v_max_i32_e32 v121, 32, v119
	v_cndmask_b32_e32 v12, v238, v15, vcc
	v_add_u32_e32 v15, 51, v113
	v_max_i32_e32 v51, 32, v15
	v_subrev_u32_e32 v51, 32, v51
	v_subrev_u32_e32 v67, 32, v67
	v_subrev_u32_e32 v121, 32, v121
	v_med3_i32 v50, v15, 0, v237
	v_min_u32_e32 v51, 0x80, v51
	v_min_u32_e32 v67, 0x80, v67
	v_min_u32_e32 v121, 0x80, v121
	v_lshl_add_u32 v50, v50, 2, s67
	v_lshl_add_u32 v51, v51, 2, s67
	v_lshl_add_u32 v66, v66, 2, s67
	v_lshl_add_u32 v67, v67, 2, s67
	v_lshl_add_u32 v117, v117, 2, s67
	v_lshl_add_u32 v118, v118, 2, s67
	v_lshl_add_u32 v120, v120, 2, s67
	v_lshl_add_u32 v121, v121, 2, s67
	ds_read_b32 v50, v50
	ds_read_b32 v51, v51
	ds_read_b32 v66, v66
	ds_read_b32 v67, v67
	ds_read_b32 v117, v117
	ds_read_b32 v118, v118
	ds_read_b32 v120, v120
	ds_read_b32 v121, v121
	v_add_u32_e32 v64, 19, v113
	s_waitcnt lgkmcnt(7)
	v_add_f32_e32 v50, v52, v50
	v_cmp_gt_u32_e32 vcc, s0, v15
	s_waitcnt lgkmcnt(6)
	v_add_f32_e32 v15, v68, v51
	s_waitcnt lgkmcnt(5)
	v_add_f32_e32 v52, v53, v66
	v_cndmask_b32_e32 v50, v238, v50, vcc
	v_cmp_gt_u32_e32 vcc, s0, v64
	s_waitcnt lgkmcnt(4)
	v_add_f32_e32 v53, v69, v67
	s_waitcnt lgkmcnt(3)
	v_add_f32_e32 v54, v54, v117
	v_cndmask_b32_e32 v51, v238, v15, vcc
	v_add_u32_e32 v15, 18, v113
	v_cmp_gt_u32_e32 vcc, s0, v65
	s_waitcnt lgkmcnt(2)
	v_add_f32_e32 v64, v70, v118
	s_waitcnt lgkmcnt(1)
	v_add_f32_e32 v55, v55, v120
	v_cndmask_b32_e32 v52, v238, v52, vcc
	v_cmp_gt_u32_e32 vcc, s0, v15
	v_add_u32_e32 v15, 17, v113
	v_add_u32_e32 v69, 42, v113
	v_cndmask_b32_e32 v53, v238, v53, vcc
	v_cmp_gt_u32_e32 vcc, s0, v116
	v_add_u32_e32 v116, 41, v113
	s_waitcnt lgkmcnt(0)
; __device__ __forceinline__ float fexp2(float x) { return __builtin_amdgcn_exp2f(x); }
; template <int KIND>
; __device__ __forceinline__ void softmax_tile(f32x16& s0, f32x16& s1, float& l, int t, int k0, int h, int qlo, const LAS float* lut, const LAS float* cb, int W, int dmask, float rowshift) {
;     ...
; #pragma unroll
;         for (int i = 0; i < 16; ++i) {
;             const int j0 = k0 + (i & 3) + 8 * (i >> 2) + 4 * h, n0 = t - j0, n1 = n0 - 32;
;             const float b0 = lut[min(max(n0, 0), 128)], b1 = lut[min(max(n1, 0), 128)];
;             const bool v0 = (n0 >= 0) && (n0 <= W) && ((n0 & dmask) == 0), v1 = (n1 >= 0) && (n1 <= W) && ((n1 & dmask) == 0);
;             s0[i] = v0 ? s0[i] + b0 : NINF; s1[i] = v1 ? s1[i] + b1 : NINF;
;         }
;     }
;     float ps = 0.f;
; #pragma unroll
;     for (int i = 0; i < 16; ++i) { s0[i] = fexp2(s0[i]); s1[i] = fexp2(s1[i]); ps += s0[i] + s1[i]; }
;     l += ps;
	v_add_f32_e32 v65, v71, v121
	v_cndmask_b32_e32 v54, v238, v54, vcc
	v_cmp_gt_u32_e32 vcc, s0, v15
	v_add_u32_e32 v15, 16, v113
	v_max_i32_e32 v71, 32, v69
	v_cndmask_b32_e32 v64, v238, v64, vcc
	v_cmp_gt_u32_e32 vcc, s0, v119
	v_add_u32_e32 v119, 40, v113
	v_max_i32_e32 v118, 32, v116
	v_cndmask_b32_e32 v55, v238, v55, vcc
	v_cmp_gt_u32_e32 vcc, s0, v15
	v_add_u32_e32 v15, 43, v113
	v_max_i32_e32 v67, 32, v15
	v_max_i32_e32 v121, 32, v119
	v_subrev_u32_e32 v67, 32, v67
	v_subrev_u32_e32 v71, 32, v71
	v_subrev_u32_e32 v118, 32, v118
	v_subrev_u32_e32 v121, 32, v121
	v_med3_i32 v66, v15, 0, v237
	v_min_u32_e32 v67, 0x80, v67
	v_med3_i32 v70, v69, 0, v237
	v_min_u32_e32 v71, 0x80, v71
	v_med3_i32 v117, v116, 0, v237
	v_min_u32_e32 v118, 0x80, v118
	v_med3_i32 v120, v119, 0, v237
	v_min_u32_e32 v121, 0x80, v121
	v_lshl_add_u32 v66, v66, 2, s67
	v_lshl_add_u32 v67, v67, 2, s67
	v_lshl_add_u32 v70, v70, 2, s67
	v_lshl_add_u32 v71, v71, 2, s67
	v_lshl_add_u32 v117, v117, 2, s67
	v_lshl_add_u32 v118, v118, 2, s67
	v_lshl_add_u32 v120, v120, 2, s67
	v_lshl_add_u32 v121, v121, 2, s67
	v_cndmask_b32_e32 v65, v238, v65, vcc
	v_add_u32_e32 v68, 11, v113
	ds_read_b32 v66, v66
	ds_read_b32 v67, v67
	ds_read_b32 v70, v70
	ds_read_b32 v71, v71
	ds_read_b32 v117, v117
	ds_read_b32 v118, v118
	ds_read_b32 v120, v120
	ds_read_b32 v121, v121
	s_waitcnt lgkmcnt(7)
	v_add_f32_e32 v56, v56, v66
	v_cmp_gt_u32_e32 vcc, s0, v15
	s_waitcnt lgkmcnt(6)
	v_add_f32_e32 v15, v72, v67
	v_exp_f32_e32 v0, v0
	v_cndmask_b32_e32 v66, v238, v56, vcc
	v_cmp_gt_u32_e32 vcc, s0, v68
	s_waitcnt lgkmcnt(5)
	v_add_f32_e32 v56, v57, v70
	v_exp_f32_e32 v50, v50
	v_cndmask_b32_e32 v67, v238, v15, vcc
	v_add_u32_e32 v15, 10, v113
	v_cmp_gt_u32_e32 vcc, s0, v69
	s_nop 1
	v_cndmask_b32_e32 v68, v238, v56, vcc
	s_waitcnt lgkmcnt(4)
	v_add_f32_e32 v56, v73, v71
	v_cmp_gt_u32_e32 vcc, s0, v15
	v_add_u32_e32 v15, 9, v113
	s_nop 0
	v_cndmask_b32_e32 v69, v238, v56, vcc
	s_waitcnt lgkmcnt(3)
	v_add_f32_e32 v56, v58, v117
	v_cmp_gt_u32_e32 vcc, s0, v116
	v_add_u32_e32 v116, 33, v113
	v_med3_i32 v117, v116, 0, v237
	v_cndmask_b32_e32 v70, v238, v56, vcc
	s_waitcnt lgkmcnt(2)
	v_add_f32_e32 v56, v74, v118
	v_cmp_gt_u32_e32 vcc, s0, v15
	v_add_u32_e32 v15, 8, v113
	v_max_i32_e32 v118, 32, v116
	v_cndmask_b32_e32 v71, v238, v56, vcc
	s_waitcnt lgkmcnt(1)
	v_add_f32_e32 v56, v59, v120
	v_cmp_gt_u32_e32 vcc, s0, v119
	v_add_u32_e32 v59, 34, v113
	v_add_u32_e32 v119, 32, v113
	v_cndmask_b32_e32 v72, v238, v56, vcc
	v_cmp_gt_u32_e32 vcc, s0, v15
	v_add_u32_e32 v15, 35, v113
	s_waitcnt lgkmcnt(0)
	v_add_f32_e32 v56, v75, v121
	v_max_i32_e32 v57, 32, v15
	v_max_i32_e32 v75, 32, v59
	v_max_i32_e32 v121, 32, v119
	v_subrev_u32_e32 v57, 32, v57
	v_subrev_u32_e32 v75, 32, v75
	v_subrev_u32_e32 v118, 32, v118
	v_subrev_u32_e32 v121, 32, v121
	v_cndmask_b32_e32 v73, v238, v56, vcc
	v_med3_i32 v56, v15, 0, v237
	v_min_u32_e32 v57, 0x80, v57
	v_med3_i32 v74, v59, 0, v237
	v_min_u32_e32 v75, 0x80, v75
	v_min_u32_e32 v118, 0x80, v118
	v_med3_i32 v120, v119, 0, v237
	v_min_u32_e32 v121, 0x80, v121
	v_lshl_add_u32 v56, v56, 2, s67
	v_lshl_add_u32 v57, v57, 2, s67
	v_lshl_add_u32 v74, v74, 2, s67
	v_lshl_add_u32 v75, v75, 2, s67
	v_lshl_add_u32 v117, v117, 2, s67
	v_lshl_add_u32 v118, v118, 2, s67
	v_lshl_add_u32 v120, v120, 2, s67
	v_lshl_add_u32 v121, v121, 2, s67
	ds_read_b32 v56, v56
	ds_read_b32 v57, v57
	ds_read_b32 v74, v74
	ds_read_b32 v75, v75
	ds_read_b32 v117, v117
	ds_read_b32 v118, v118
	ds_read_b32 v120, v120
	ds_read_b32 v121, v121
	v_add_u32_e32 v58, 3, v113
	s_waitcnt lgkmcnt(7)
	v_add_f32_e32 v56, v60, v56
	v_cmp_gt_u32_e32 vcc, s0, v15
	s_waitcnt lgkmcnt(6)
	v_add_f32_e32 v15, v76, v57
	v_exp_f32_e32 v57, v49
	v_cndmask_b32_e32 v122, v238, v56, vcc
	v_cmp_gt_u32_e32 vcc, s0, v58
	s_waitcnt lgkmcnt(5)
	v_add_f32_e32 v56, v61, v74
	v_exp_f32_e32 v49, v10
	v_cndmask_b32_e32 v76, v238, v15, vcc
	v_add_u32_e32 v15, 2, v113
	v_cmp_gt_u32_e32 vcc, s0, v59
	v_exp_f32_e32 v59, v12
	v_exp_f32_e32 v61, v53
	v_cndmask_b32_e32 v74, v238, v56, vcc
	s_waitcnt lgkmcnt(4)
	v_add_f32_e32 v56, v77, v75
	v_cmp_gt_u32_e32 vcc, s0, v15
	v_add_u32_e32 v15, 1, v113
	v_exp_f32_e32 v53, v55
	v_cndmask_b32_e32 v75, v238, v56, vcc
	s_waitcnt lgkmcnt(3)
	v_add_f32_e32 v56, v62, v117
	v_cmp_gt_u32_e32 vcc, s0, v116
	v_exp_f32_e32 v117, v14
	s_nop 0
	v_cndmask_b32_e32 v77, v238, v56, vcc
	s_waitcnt lgkmcnt(2)
; #define LAS __attribute__((address_space(3)))
; template <int DV> __device__ __forceinline__ bf16x8 vfrag(LAS unsigned char* vt, int dv0, int kbase, int lane) {
;     const int i16 = lane & 15, q = i16 >> 2, pp_ = i16 & 3, blk = (lane >> 4) & 1;
;     LAS unsigned char* p0 = vt + ((kbase + q) * (DV + 8) + dv0 + 16 * blk + 4 * pp_) * 2;
;     const v4i16_t lo = __builtin_amdgcn_ds_read_tr16_b64_v4i16((LAS v4i16_t*)p0);
;     const v4i16_t hi = __builtin_amdgcn_ds_read_tr16_b64_v4i16((LAS v4i16_t*)(p0 + 8 * (DV + 8) * 2));
;     return __builtin_shufflevector(lo, hi, 0, 1, 2, 3, 4, 5, 6, 7);
; }
	v_add_f32_e32 v56, v78, v118
	v_cmp_gt_u32_e32 vcc, s0, v15
	s_waitcnt lgkmcnt(1)
	v_add_f32_e32 v15, v63, v120
	v_add_f32_e32 v14, v0, v117
	v_cndmask_b32_e32 v78, v238, v56, vcc
	v_cmp_gt_u32_e32 vcc, s0, v119
	v_mov_b32_e32 v56, v1
	v_exp_f32_e32 v118, v11
	v_cndmask_b32_e32 v116, v238, v15, vcc
	s_waitcnt lgkmcnt(0)
	v_add_f32_e32 v15, v79, v121
	v_cmp_gt_u32_e32 vcc, s0, v113
	v_add_f32_e32 v58, v49, v118
	v_exp_f32_e32 v63, v65
	v_cndmask_b32_e32 v79, v238, v15, vcc
	v_exp_f32_e32 v15, v48
	v_exp_f32_e32 v119, v67
	v_exp_f32_e32 v65, v69
	v_exp_f32_e32 v69, v71
	v_pk_add_f32 v[10:11], v[14:15], v[56:57]
	v_exp_f32_e32 v14, v13
	v_exp_f32_e32 v56, v51
	v_pk_add_f32 v[10:11], v[10:11], v[10:11] op_sel:[0,1] op_sel_hi:[1,0]
	v_exp_f32_e32 v51, v52
	v_mov_b32_e32 v11, v14
	v_pk_add_f32 v[10:11], v[10:11], v[58:59]
	v_exp_f32_e32 v52, v54
	v_pk_add_f32 v[10:11], v[10:11], v[10:11] op_sel:[0,1] op_sel_hi:[1,0]
	v_exp_f32_e32 v58, v64
	v_add_f32_e32 v60, v50, v56
	v_mov_b32_e32 v11, v51
	v_pk_add_f32 v[10:11], v[10:11], v[60:61]
	v_add_f32_e32 v62, v52, v58
	v_pk_add_f32 v[10:11], v[10:11], v[10:11] op_sel:[0,1] op_sel_hi:[1,0]
	v_exp_f32_e32 v60, v66
	v_mov_b32_e32 v11, v53
	v_pk_add_f32 v[10:11], v[10:11], v[62:63]
	v_exp_f32_e32 v62, v68
	v_pk_add_f32 v[10:11], v[10:11], v[10:11] op_sel:[0,1] op_sel_hi:[1,0]
	v_add_f32_e32 v64, v60, v119
	v_cvt_pk_bf16_f32 v50, v50, v51
	v_mov_b32_e32 v11, v62
	v_pk_add_f32 v[66:67], v[10:11], v[64:65]
	v_add_u32_e32 v64, 0, v200
	ds_read_b64_tr_b16 v[130:131], v64 offset:36864
	ds_read_b64_tr_b16 v[132:133], v64 offset:38016
	ds_read_b64_tr_b16 v[134:135], v64 offset:36928
	ds_read_b64_tr_b16 v[136:137], v64 offset:38080
	ds_read_b64_tr_b16 v[138:139], v64 offset:39168
	ds_read_b64_tr_b16 v[140:141], v64 offset:40320
	v_cvt_pk_bf16_f32 v51, v52, v53
	v_cvt_pk_bf16_f32 v48, v0, v15
	v_cvt_pk_bf16_f32 v49, v49, v14
	v_exp_f32_e32 v68, v70
	v_exp_f32_e32 v0, v72
	s_waitcnt lgkmcnt(6)
	ds_read_b64_tr_b16 v[142:143], v64 offset:39232
	ds_read_b64_tr_b16 v[144:145], v64 offset:40384
	s_waitcnt lgkmcnt(6)
	v_mfma_f32_32x32x16_bf16 v[32:47], v[130:133], v[48:51], v[32:47]
	v_exp_f32_e32 v15, v73
	v_exp_f32_e32 v70, v122
	v_exp_f32_e32 v71, v74
	v_exp_f32_e32 v72, v77
	v_exp_f32_e32 v73, v116
	v_add_f32_e32 v14, v68, v69
	ds_read_b64_tr_b16 v[130:131], v201 offset:36864
	ds_read_b64_tr_b16 v[132:133], v201 offset:38016
	s_waitcnt lgkmcnt(6)
	v_mfma_f32_32x32x16_bf16 v[16:31], v[134:137], v[48:51], v[16:31]
	v_cvt_pk_bf16_f32 v48, v60, v62
	v_cvt_pk_bf16_f32 v49, v68, v0
	v_cvt_pk_bf16_f32 v50, v70, v71
	v_cvt_pk_bf16_f32 v51, v72, v73
	s_nop 0
	ds_read_b64_tr_b16 v[134:135], v201 offset:36928
	ds_read_b64_tr_b16 v[136:137], v201 offset:38080
	s_waitcnt lgkmcnt(6)
	v_mfma_f32_32x32x16_bf16 v[32:47], v[138:141], v[48:51], v[32:47]
	v_add_f32_e64 v10, v66, v67
	v_add_f32_e64 v11, v67, v66
	v_mov_b32_e32 v11, v0
	v_add_u32_e32 v0, 0, v201
	v_add_f32_e64 v66, v10, v14
	v_add_f32_e64 v67, v11, v15
	v_exp_f32_e32 v14, v76
	ds_read_b64_tr_b16 v[138:139], v64 offset:43776
	ds_read_b64_tr_b16 v[140:141], v64 offset:44928
	s_waitcnt lgkmcnt(6)
	v_mfma_f32_32x32x16_bf16 v[16:31], v[142:145], v[48:51], v[16:31]
	v_cvt_pk_bf16_f32 v48, v117, v57
	v_cvt_pk_bf16_f32 v49, v118, v59
	v_cvt_pk_bf16_f32 v50, v56, v61
	v_cvt_pk_bf16_f32 v51, v58, v63
	v_exp_f32_e32 v57, v75
	v_exp_f32_e32 v0, v78
	ds_read_b64_tr_b16 v[142:143], v64 offset:43840
	ds_read_b64_tr_b16 v[144:145], v64 offset:44992
	s_waitcnt lgkmcnt(6)
	v_mfma_f32_32x32x16_bf16 v[32:47], v[130:133], v[48:51], v[32:47]
	v_exp_f32_e32 v61, v79
	v_pk_add_f32 v[58:59], v[66:67], v[66:67] op_sel:[0,1] op_sel_hi:[1,0]
	v_add_f32_e32 v56, v70, v14
	v_mov_b32_e32 v59, v71
	v_add_f32_e32 v60, v72, v0
	s_waitcnt lgkmcnt(4)
	v_mfma_f32_32x32x16_bf16 v[16:31], v[134:137], v[48:51], v[16:31]
	v_cvt_pk_bf16_f32 v48, v119, v65
	v_cvt_pk_bf16_f32 v49, v69, v15
	v_cvt_pk_bf16_f32 v50, v14, v57
	v_cvt_pk_bf16_f32 v51, v0, v61
	s_nop 0
	s_waitcnt lgkmcnt(2)
	v_mfma_f32_32x32x16_bf16 v[32:47], v[138:141], v[48:51], v[32:47]
	v_add_f32_e64 v10, v58, v56
	v_add_f32_e64 v11, v59, v57
	v_pk_add_f32 v[10:11], v[10:11], v[10:11] op_sel:[0,1] op_sel_hi:[1,0]
	s_nop 0
	v_mov_b32_e32 v11, v73
	v_pk_add_f32 v[10:11], v[10:11], v[60:61]
	s_waitcnt lgkmcnt(0)
	v_mfma_f32_32x32x16_bf16 v[16:31], v[142:145], v[48:51], v[16:31]
	v_add_f32_e32 v0, v10, v11
	v_add_f32_e32 v108, v108, v0

; template <int KIND>
; __device__ __forceinline__ void softmax_tile(f32x16& s0, f32x16& s1, float& l, int t, int k0, int h, int qlo, const LAS float* lut, const LAS float* cb, int W, int dmask, float rowshift) {
;     ...
; #pragma unroll
;         for (int i = 0; i < 16; ++i) {
;             const int j0 = k0 + (i & 3) + 8 * (i >> 2) + 4 * h, n0 = t - j0, n1 = n0 - 32;
;             const float b0 = lut[min(max(n0, 0), 128)], b1 = lut[min(max(n1, 0), 128)];
;             const bool v0 = (n0 >= 0) && (n0 <= W) && ((n0 & dmask) == 0), v1 = (n1 >= 0) && (n1 <= W) && ((n1 & dmask) == 0);
;             s0[i] = v0 ? s0[i] + b0 : NINF; s1[i] = v1 ? s1[i] + b1 : NINF;
;         }
.LBB0_542:
	v_add_u32_e32 v0, 63, v114
	v_cmp_le_i32_e32 vcc, v114, v109
	v_cmp_ge_i32_e64 s[20:21], v0, v110
	s_and_b64 vcc, vcc, s[20:21]
	s_and_saveexec_b64 s[20:21], vcc
	s_cbranch_execz .LBB0_544
	v_add_u32_e32 v0, 0, v199
	ds_read_b128 v[10:13], v0 offset:9216
	ds_read_b128 v[116:119], v0 offset:9248
	v_add_u32_e32 v14, 0x7b, v113
	v_max_i32_e32 v15, 32, v14
	v_subrev_u32_e32 v15, 32, v15
	s_waitcnt lgkmcnt(1)
	v_mfma_f32_32x32x16_bf16 v[48:63], v[10:13], v[80:83], 0
	ds_read_b128 v[10:13], v0 offset:13824
	ds_read_b128 v[120:123], v0 offset:13856
	v_min_u32_e32 v15, 0x80, v15
	v_lshl_add_u32 v15, v15, 2, s67
	v_cmp_gt_u32_e32 vcc, s0, v14
	s_waitcnt lgkmcnt(1)
	v_mfma_f32_32x32x16_bf16 v[64:79], v[10:13], v[80:83], 0
	ds_read_b128 v[10:13], v0 offset:9280
	ds_read_b128 v[124:127], v0 offset:9312
	ds_read_b128 v[128:131], v0 offset:13888
	ds_read_b128 v[132:135], v0 offset:13920
	v_med3_i32 v0, v14, 0, v237
	v_lshl_add_u32 v0, v0, 2, s67
	v_mfma_f32_32x32x16_bf16 v[48:63], v[116:119], v[84:87], v[48:63]
	v_add_u32_e32 v117, 0x7a, v113
	v_max_i32_e32 v119, 32, v117
	v_subrev_u32_e32 v119, 32, v119
	v_med3_i32 v118, v117, 0, v237
	v_min_u32_e32 v119, 0x80, v119
	v_lshl_add_u32 v118, v118, 2, s67
	v_lshl_add_u32 v119, v119, 2, s67
	s_waitcnt lgkmcnt(4)
	v_mfma_f32_32x32x16_bf16 v[64:79], v[120:123], v[84:87], v[64:79]
	v_add_u32_e32 v116, 0x5b, v113
	s_waitcnt lgkmcnt(3)
	v_mfma_f32_32x32x16_bf16 v[48:63], v[10:13], v[88:91], v[48:63]
	v_add_u32_e32 v10, 0x79, v113
	v_add_u32_e32 v13, 0x78, v113
	v_max_i32_e32 v12, 32, v10
	v_max_i32_e32 v121, 32, v13
	v_subrev_u32_e32 v12, 32, v12
	v_subrev_u32_e32 v121, 32, v121
	v_med3_i32 v11, v10, 0, v237
	s_waitcnt lgkmcnt(1)
	v_mfma_f32_32x32x16_bf16 v[64:79], v[128:131], v[88:91], v[64:79]
	v_min_u32_e32 v12, 0x80, v12
	v_med3_i32 v120, v13, 0, v237
	v_min_u32_e32 v121, 0x80, v121
	v_lshl_add_u32 v11, v11, 2, s67
	v_lshl_add_u32 v12, v12, 2, s67
	v_lshl_add_u32 v120, v120, 2, s67
	v_lshl_add_u32 v121, v121, 2, s67
	v_mfma_f32_32x32x16_bf16 v[48:63], v[124:127], v[92:95], v[48:63]
	ds_read_b32 v0, v0
	ds_read_b32 v15, v15
	ds_read_b32 v118, v118
	ds_read_b32 v119, v119
	ds_read_b32 v11, v11
	ds_read_b32 v12, v12
	ds_read_b32 v120, v120
	ds_read_b32 v121, v121
	s_waitcnt lgkmcnt(7)
	s_nop 2
	v_add_f32_e32 v0, v48, v0
	v_mfma_f32_32x32x16_bf16 v[64:79], v[132:135], v[92:95], v[64:79]
	v_cndmask_b32_e32 v0, v238, v0, vcc
	v_cmp_gt_u32_e32 vcc, s0, v116
	s_waitcnt lgkmcnt(5)
	v_add_f32_e32 v48, v49, v118
	s_waitcnt lgkmcnt(3)
	v_add_f32_e32 v11, v50, v11
	v_add_u32_e32 v116, 0x71, v113
	v_max_i32_e32 v118, 32, v116
	v_subrev_u32_e32 v118, 32, v118
	s_nop 2
	v_add_f32_e32 v14, v64, v15
	v_cndmask_b32_e32 v14, v238, v14, vcc
	v_add_u32_e32 v15, 0x5a, v113
	v_cmp_gt_u32_e32 vcc, s0, v117
	v_add_f32_e32 v49, v65, v119
	v_add_u32_e32 v65, 0x72, v113
	v_cndmask_b32_e32 v48, v238, v48, vcc
	v_cmp_gt_u32_e32 vcc, s0, v15
	v_add_u32_e32 v15, 0x59, v113
	v_add_u32_e32 v119, 0x70, v113
	v_cndmask_b32_e32 v49, v238, v49, vcc
	v_cmp_gt_u32_e32 vcc, s0, v10
	v_med3_i32 v117, v116, 0, v237
	v_min_u32_e32 v118, 0x80, v118
	v_cndmask_b32_e32 v10, v238, v11, vcc
	s_waitcnt lgkmcnt(2)
	v_add_f32_e32 v11, v66, v12
	v_cmp_gt_u32_e32 vcc, s0, v15
	v_add_u32_e32 v12, 0x58, v113
	s_waitcnt lgkmcnt(1)
	v_add_f32_e32 v15, v51, v120
	v_cndmask_b32_e32 v11, v238, v11, vcc
	v_cmp_gt_u32_e32 vcc, s0, v13
	v_med3_i32 v66, v65, 0, v237
	v_med3_i32 v120, v119, 0, v237
	v_cndmask_b32_e32 v13, v238, v15, vcc
	s_waitcnt lgkmcnt(0)
	v_add_f32_e32 v15, v67, v121
	v_cmp_gt_u32_e32 vcc, s0, v12
	v_max_i32_e32 v67, 32, v65
	v_max_i32_e32 v121, 32, v119
	v_cndmask_b32_e32 v12, v238, v15, vcc
	v_add_u32_e32 v15, 0x73, v113
	v_max_i32_e32 v51, 32, v15
	v_subrev_u32_e32 v51, 32, v51
	v_subrev_u32_e32 v67, 32, v67
	v_subrev_u32_e32 v121, 32, v121
	v_med3_i32 v50, v15, 0, v237
	v_min_u32_e32 v51, 0x80, v51
	v_min_u32_e32 v67, 0x80, v67
	v_min_u32_e32 v121, 0x80, v121
	v_lshl_add_u32 v50, v50, 2, s67
	v_lshl_add_u32 v51, v51, 2, s67
	v_lshl_add_u32 v66, v66, 2, s67
	v_lshl_add_u32 v67, v67, 2, s67
	v_lshl_add_u32 v117, v117, 2, s67
	v_lshl_add_u32 v118, v118, 2, s67
	v_lshl_add_u32 v120, v120, 2, s67
	v_lshl_add_u32 v121, v121, 2, s67
	ds_read_b32 v50, v50
	ds_read_b32 v51, v51
	ds_read_b32 v66, v66
	ds_read_b32 v67, v67
	ds_read_b32 v117, v117
	ds_read_b32 v118, v118
	ds_read_b32 v120, v120
	ds_read_b32 v121, v121
	v_add_u32_e32 v64, 0x53, v113
	s_waitcnt lgkmcnt(7)
	v_add_f32_e32 v50, v52, v50
	v_cmp_gt_u32_e32 vcc, s0, v15
	s_waitcnt lgkmcnt(6)
	v_add_f32_e32 v15, v68, v51
	s_waitcnt lgkmcnt(5)
	v_add_f32_e32 v52, v53, v66
	v_cndmask_b32_e32 v50, v238, v50, vcc
	v_cmp_gt_u32_e32 vcc, s0, v64
	s_waitcnt lgkmcnt(4)
	v_add_f32_e32 v53, v69, v67
	s_waitcnt lgkmcnt(3)
	v_add_f32_e32 v54, v54, v117
	v_cndmask_b32_e32 v51, v238, v15, vcc
	v_add_u32_e32 v15, 0x52, v113
	v_cmp_gt_u32_e32 vcc, s0, v65
	s_waitcnt lgkmcnt(2)
	v_add_f32_e32 v64, v70, v118
	s_waitcnt lgkmcnt(1)
	v_add_f32_e32 v55, v55, v120
	v_cndmask_b32_e32 v52, v238, v52, vcc
	v_cmp_gt_u32_e32 vcc, s0, v15
	v_add_u32_e32 v15, 0x51, v113
	v_add_u32_e32 v69, 0x6a, v113
	v_cndmask_b32_e32 v53, v238, v53, vcc
	v_cmp_gt_u32_e32 vcc, s0, v116
	v_add_u32_e32 v116, 0x69, v113
	s_waitcnt lgkmcnt(0)
; __device__ __forceinline__ float fexp2(float x) { return __builtin_amdgcn_exp2f(x); }
; template <int KIND>
; __device__ __forceinline__ void softmax_tile(f32x16& s0, f32x16& s1, float& l, int t, int k0, int h, int qlo, const LAS float* lut, const LAS float* cb, int W, int dmask, float rowshift) {
;     ...
; #pragma unroll
;         for (int i = 0; i < 16; ++i) {
;             const int j0 = k0 + (i & 3) + 8 * (i >> 2) + 4 * h, n0 = t - j0, n1 = n0 - 32;
;             const float b0 = lut[min(max(n0, 0), 128)], b1 = lut[min(max(n1, 0), 128)];
;             const bool v0 = (n0 >= 0) && (n0 <= W) && ((n0 & dmask) == 0), v1 = (n1 >= 0) && (n1 <= W) && ((n1 & dmask) == 0);
;             s0[i] = v0 ? s0[i] + b0 : NINF; s1[i] = v1 ? s1[i] + b1 : NINF;
;         }
;     }
;     float ps = 0.f;
; #pragma unroll
;     for (int i = 0; i < 16; ++i) { s0[i] = fexp2(s0[i]); s1[i] = fexp2(s1[i]); ps += s0[i] + s1[i]; }
;     l += ps;
	v_add_f32_e32 v65, v71, v121
	v_cndmask_b32_e32 v54, v238, v54, vcc
	v_cmp_gt_u32_e32 vcc, s0, v15
	v_add_u32_e32 v15, 0x50, v113
	v_max_i32_e32 v71, 32, v69
	v_cndmask_b32_e32 v64, v238, v64, vcc
	v_cmp_gt_u32_e32 vcc, s0, v119
	v_add_u32_e32 v119, 0x68, v113
	v_max_i32_e32 v118, 32, v116
	v_cndmask_b32_e32 v55, v238, v55, vcc
	v_cmp_gt_u32_e32 vcc, s0, v15
	v_add_u32_e32 v15, 0x6b, v113
	v_max_i32_e32 v67, 32, v15
	v_max_i32_e32 v121, 32, v119
	v_subrev_u32_e32 v67, 32, v67
	v_subrev_u32_e32 v71, 32, v71
	v_subrev_u32_e32 v118, 32, v118
	v_subrev_u32_e32 v121, 32, v121
	v_med3_i32 v66, v15, 0, v237
	v_min_u32_e32 v67, 0x80, v67
	v_med3_i32 v70, v69, 0, v237
	v_min_u32_e32 v71, 0x80, v71
	v_med3_i32 v117, v116, 0, v237
	v_min_u32_e32 v118, 0x80, v118
	v_med3_i32 v120, v119, 0, v237
	v_min_u32_e32 v121, 0x80, v121
	v_lshl_add_u32 v66, v66, 2, s67
	v_lshl_add_u32 v67, v67, 2, s67
	v_lshl_add_u32 v70, v70, 2, s67
	v_lshl_add_u32 v71, v71, 2, s67
	v_lshl_add_u32 v117, v117, 2, s67
	v_lshl_add_u32 v118, v118, 2, s67
	v_lshl_add_u32 v120, v120, 2, s67
	v_lshl_add_u32 v121, v121, 2, s67
	v_cndmask_b32_e32 v65, v238, v65, vcc
	v_add_u32_e32 v68, 0x4b, v113
	ds_read_b32 v66, v66
	ds_read_b32 v67, v67
	ds_read_b32 v70, v70
	ds_read_b32 v71, v71
	ds_read_b32 v117, v117
	ds_read_b32 v118, v118
	ds_read_b32 v120, v120
	ds_read_b32 v121, v121
	s_waitcnt lgkmcnt(7)
	v_add_f32_e32 v56, v56, v66
	v_cmp_gt_u32_e32 vcc, s0, v15
	s_waitcnt lgkmcnt(6)
	v_add_f32_e32 v15, v72, v67
	v_exp_f32_e32 v0, v0
	v_cndmask_b32_e32 v66, v238, v56, vcc
	v_cmp_gt_u32_e32 vcc, s0, v68
	s_waitcnt lgkmcnt(5)
	v_add_f32_e32 v56, v57, v70
	v_exp_f32_e32 v50, v50
	v_cndmask_b32_e32 v67, v238, v15, vcc
	v_add_u32_e32 v15, 0x4a, v113
	v_cmp_gt_u32_e32 vcc, s0, v69
	s_nop 1
	v_cndmask_b32_e32 v68, v238, v56, vcc
	s_waitcnt lgkmcnt(4)
	v_add_f32_e32 v56, v73, v71
	v_cmp_gt_u32_e32 vcc, s0, v15
	v_add_u32_e32 v15, 0x49, v113
	s_nop 0
	v_cndmask_b32_e32 v69, v238, v56, vcc
	s_waitcnt lgkmcnt(3)
	v_add_f32_e32 v56, v58, v117
	v_cmp_gt_u32_e32 vcc, s0, v116
	v_add_u32_e32 v116, 0x61, v113
	v_med3_i32 v117, v116, 0, v237
	v_cndmask_b32_e32 v70, v238, v56, vcc
	s_waitcnt lgkmcnt(2)
	v_add_f32_e32 v56, v74, v118
	v_cmp_gt_u32_e32 vcc, s0, v15
	v_add_u32_e32 v15, 0x48, v113
	v_max_i32_e32 v118, 32, v116
	v_cndmask_b32_e32 v71, v238, v56, vcc
	s_waitcnt lgkmcnt(1)
	v_add_f32_e32 v56, v59, v120
	v_cmp_gt_u32_e32 vcc, s0, v119
	v_add_u32_e32 v59, 0x62, v113
	v_add_u32_e32 v119, 0x60, v113
	v_cndmask_b32_e32 v72, v238, v56, vcc
	v_cmp_gt_u32_e32 vcc, s0, v15
	v_add_u32_e32 v15, 0x63, v113
	s_waitcnt lgkmcnt(0)
	v_add_f32_e32 v56, v75, v121
	v_max_i32_e32 v57, 32, v15
	v_max_i32_e32 v75, 32, v59
	v_max_i32_e32 v121, 32, v119
	v_subrev_u32_e32 v57, 32, v57
	v_subrev_u32_e32 v75, 32, v75
	v_subrev_u32_e32 v118, 32, v118
	v_subrev_u32_e32 v121, 32, v121
	v_cndmask_b32_e32 v73, v238, v56, vcc
	v_med3_i32 v56, v15, 0, v237
	v_min_u32_e32 v57, 0x80, v57
	v_med3_i32 v74, v59, 0, v237
	v_min_u32_e32 v75, 0x80, v75
	v_min_u32_e32 v118, 0x80, v118
	v_med3_i32 v120, v119, 0, v237
	v_min_u32_e32 v121, 0x80, v121
	v_lshl_add_u32 v56, v56, 2, s67
	v_lshl_add_u32 v57, v57, 2, s67
	v_lshl_add_u32 v74, v74, 2, s67
	v_lshl_add_u32 v75, v75, 2, s67
	v_lshl_add_u32 v117, v117, 2, s67
	v_lshl_add_u32 v118, v118, 2, s67
	v_lshl_add_u32 v120, v120, 2, s67
	v_lshl_add_u32 v121, v121, 2, s67
	ds_read_b32 v56, v56
	ds_read_b32 v57, v57
	ds_read_b32 v74, v74
	ds_read_b32 v75, v75
	ds_read_b32 v117, v117
	ds_read_b32 v118, v118
	ds_read_b32 v120, v120
	ds_read_b32 v121, v121
	v_add_u32_e32 v58, 0x43, v113
	s_waitcnt lgkmcnt(7)
	v_add_f32_e32 v56, v60, v56
	v_cmp_gt_u32_e32 vcc, s0, v15
	s_waitcnt lgkmcnt(6)
	v_add_f32_e32 v15, v76, v57
	v_exp_f32_e32 v57, v49
	v_cndmask_b32_e32 v122, v238, v56, vcc
	v_cmp_gt_u32_e32 vcc, s0, v58
	s_waitcnt lgkmcnt(5)
	v_add_f32_e32 v56, v61, v74
	v_exp_f32_e32 v49, v10
	v_cndmask_b32_e32 v76, v238, v15, vcc
	v_add_u32_e32 v15, 0x42, v113
	v_cmp_gt_u32_e32 vcc, s0, v59
	v_exp_f32_e32 v59, v12
	v_exp_f32_e32 v61, v53
	v_cndmask_b32_e32 v74, v238, v56, vcc
	s_waitcnt lgkmcnt(4)
	v_add_f32_e32 v56, v77, v75
	v_cmp_gt_u32_e32 vcc, s0, v15
	v_add_u32_e32 v15, 0x41, v113
	v_exp_f32_e32 v53, v55
	v_cndmask_b32_e32 v75, v238, v56, vcc
	s_waitcnt lgkmcnt(3)
	v_add_f32_e32 v56, v62, v117
	v_cmp_gt_u32_e32 vcc, s0, v116
	v_exp_f32_e32 v117, v14
	s_nop 0
	v_cndmask_b32_e32 v77, v238, v56, vcc
	s_waitcnt lgkmcnt(2)
; #define LAS __attribute__((address_space(3)))
; template <int DV> __device__ __forceinline__ bf16x8 vfrag(LAS unsigned char* vt, int dv0, int kbase, int lane) {
;     const int i16 = lane & 15, q = i16 >> 2, pp_ = i16 & 3, blk = (lane >> 4) & 1;
;     LAS unsigned char* p0 = vt + ((kbase + q) * (DV + 8) + dv0 + 16 * blk + 4 * pp_) * 2;
;     const v4i16_t lo = __builtin_amdgcn_ds_read_tr16_b64_v4i16((LAS v4i16_t*)p0);
;     const v4i16_t hi = __builtin_amdgcn_ds_read_tr16_b64_v4i16((LAS v4i16_t*)(p0 + 8 * (DV + 8) * 2));
;     return __builtin_shufflevector(lo, hi, 0, 1, 2, 3, 4, 5, 6, 7);
; }
	v_add_f32_e32 v56, v78, v118
	v_cmp_gt_u32_e32 vcc, s0, v15
	v_add_u32_e32 v15, 64, v113
	v_add_f32_e32 v14, v0, v117
	v_cndmask_b32_e32 v78, v238, v56, vcc
	s_waitcnt lgkmcnt(1)
	v_add_f32_e32 v56, v63, v120
	v_cmp_gt_u32_e32 vcc, s0, v119
	v_exp_f32_e32 v118, v11
	v_exp_f32_e32 v63, v65
	v_cndmask_b32_e32 v116, v238, v56, vcc
	v_cmp_gt_u32_e32 vcc, s0, v15
	v_exp_f32_e32 v15, v48
	s_waitcnt lgkmcnt(0)
	v_add_f32_e32 v56, v79, v121
	v_cndmask_b32_e32 v79, v238, v56, vcc
	v_mov_b32_e32 v56, v1
	v_pk_add_f32 v[10:11], v[14:15], v[56:57]
	v_exp_f32_e32 v14, v13
	v_exp_f32_e32 v56, v51
	v_pk_add_f32 v[10:11], v[10:11], v[10:11] op_sel:[0,1] op_sel_hi:[1,0]
	v_exp_f32_e32 v51, v52
	v_add_f32_e32 v58, v49, v118
	v_mov_b32_e32 v11, v14
	v_pk_add_f32 v[10:11], v[10:11], v[58:59]
	v_exp_f32_e32 v52, v54
	v_pk_add_f32 v[10:11], v[10:11], v[10:11] op_sel:[0,1] op_sel_hi:[1,0]
	v_exp_f32_e32 v58, v64
	v_add_f32_e32 v60, v50, v56
	v_mov_b32_e32 v11, v51
	v_pk_add_f32 v[10:11], v[10:11], v[60:61]
	v_add_f32_e32 v62, v52, v58
	v_pk_add_f32 v[10:11], v[10:11], v[10:11] op_sel:[0,1] op_sel_hi:[1,0]
	v_exp_f32_e32 v60, v66
	v_mov_b32_e32 v11, v53
	v_exp_f32_e32 v119, v67
	v_pk_add_f32 v[10:11], v[10:11], v[62:63]
	v_exp_f32_e32 v62, v68
	v_exp_f32_e32 v65, v69
	v_pk_add_f32 v[10:11], v[10:11], v[10:11] op_sel:[0,1] op_sel_hi:[1,0]
	v_add_f32_e32 v64, v60, v119
	v_mov_b32_e32 v11, v62
	v_pk_add_f32 v[66:67], v[10:11], v[64:65]
	v_add_u32_e32 v64, 0, v200
	ds_read_b64_tr_b16 v[130:131], v64 offset:54272
	ds_read_b64_tr_b16 v[132:133], v64 offset:55424
	ds_read_b64_tr_b16 v[134:135], v64 offset:54336
	ds_read_b64_tr_b16 v[136:137], v64 offset:55488
	ds_read_b64_tr_b16 v[138:139], v64 offset:56576
	ds_read_b64_tr_b16 v[140:141], v64 offset:57728
	v_cvt_pk_bf16_f32 v50, v50, v51
	v_cvt_pk_bf16_f32 v51, v52, v53
	v_cvt_pk_bf16_f32 v48, v0, v15
	v_cvt_pk_bf16_f32 v49, v49, v14
	v_exp_f32_e32 v68, v70
	v_exp_f32_e32 v69, v71
	s_waitcnt lgkmcnt(6)
	ds_read_b64_tr_b16 v[142:143], v64 offset:56640
	ds_read_b64_tr_b16 v[144:145], v64 offset:57792
	s_waitcnt lgkmcnt(6)
	v_mfma_f32_32x32x16_bf16 v[32:47], v[130:133], v[48:51], v[32:47]
	v_exp_f32_e32 v0, v72
	v_exp_f32_e32 v15, v73
	v_exp_f32_e32 v70, v122
	v_exp_f32_e32 v71, v74
	v_exp_f32_e32 v72, v77
	v_exp_f32_e32 v73, v116
	ds_read_b64_tr_b16 v[130:131], v201 offset:54272
	ds_read_b64_tr_b16 v[132:133], v201 offset:55424
	s_waitcnt lgkmcnt(6)
	v_mfma_f32_32x32x16_bf16 v[16:31], v[134:137], v[48:51], v[16:31]
	v_cvt_pk_bf16_f32 v48, v60, v62
	v_cvt_pk_bf16_f32 v49, v68, v0
	v_cvt_pk_bf16_f32 v50, v70, v71
	v_cvt_pk_bf16_f32 v51, v72, v73
	v_add_f32_e32 v14, v68, v69
	ds_read_b64_tr_b16 v[134:135], v201 offset:54336
	ds_read_b64_tr_b16 v[136:137], v201 offset:55488
	s_waitcnt lgkmcnt(6)
	v_mfma_f32_32x32x16_bf16 v[32:47], v[138:141], v[48:51], v[32:47]
	v_add_f32_e64 v10, v66, v67
	v_add_f32_e64 v11, v67, v66
	v_mov_b32_e32 v11, v0
	v_add_u32_e32 v0, 0, v201
	v_add_f32_e64 v66, v10, v14
	v_add_f32_e64 v67, v11, v15
	v_exp_f32_e32 v14, v76
	ds_read_b64_tr_b16 v[138:139], v64 offset:61184
	ds_read_b64_tr_b16 v[140:141], v64 offset:62336
	s_waitcnt lgkmcnt(6)
	v_mfma_f32_32x32x16_bf16 v[16:31], v[142:145], v[48:51], v[16:31]
	v_cvt_pk_bf16_f32 v48, v117, v57
	v_cvt_pk_bf16_f32 v49, v118, v59
	v_cvt_pk_bf16_f32 v50, v56, v61
	v_cvt_pk_bf16_f32 v51, v58, v63
	v_exp_f32_e32 v57, v75
	v_exp_f32_e32 v0, v78
	ds_read_b64_tr_b16 v[142:143], v64 offset:61248
	ds_read_b64_tr_b16 v[144:145], v64 offset:62400
	s_waitcnt lgkmcnt(6)
	v_mfma_f32_32x32x16_bf16 v[32:47], v[130:133], v[48:51], v[32:47]
	v_exp_f32_e32 v61, v79
	v_pk_add_f32 v[58:59], v[66:67], v[66:67] op_sel:[0,1] op_sel_hi:[1,0]
	v_add_f32_e32 v56, v70, v14
	v_mov_b32_e32 v59, v71
	v_add_f32_e32 v60, v72, v0
	s_waitcnt lgkmcnt(4)
	v_mfma_f32_32x32x16_bf16 v[16:31], v[134:137], v[48:51], v[16:31]
	v_cvt_pk_bf16_f32 v48, v119, v65
	v_cvt_pk_bf16_f32 v49, v69, v15
	v_cvt_pk_bf16_f32 v50, v14, v57
	v_cvt_pk_bf16_f32 v51, v0, v61
	s_nop 0
	s_waitcnt lgkmcnt(2)
	v_mfma_f32_32x32x16_bf16 v[32:47], v[138:141], v[48:51], v[32:47]
	v_add_f32_e64 v10, v58, v56
	v_add_f32_e64 v11, v59, v57
	v_pk_add_f32 v[10:11], v[10:11], v[10:11] op_sel:[0,1] op_sel_hi:[1,0]
	s_nop 0
	v_mov_b32_e32 v11, v73
	v_pk_add_f32 v[10:11], v[10:11], v[60:61]
	s_waitcnt lgkmcnt(0)
	v_mfma_f32_32x32x16_bf16 v[16:31], v[142:145], v[48:51], v[16:31]
	v_add_f32_e32 v0, v10, v11
	v_add_f32_e32 v108, v108, v0
	s_or_b64 exec, exec, s[20:21]
	s_andn2_b64 vcc, exec, s[64:65]
	s_mov_b64 s[20:21], -1
	s_cbranch_vccnz .LBB0_534
	s_branch .LBB0_545

; #define LAS __attribute__((address_space(3)))
; #define MFMA32(a, b, c) __builtin_amdgcn_mfma_f32_32x32x16_bf16((a), (b), (c), 0, 0, 0)
; template <int KIND>
; __device__ __forceinline__ void softmax_tile(f32x16& s0, f32x16& s1, float& l, int t, int k0, int h, int qlo, const LAS float* lut, const LAS float* cb, int W, int dmask, float rowshift) {
;     ...
;         const bool diag = (k0 + 63 > qlo);
; #pragma unroll
;         for (int c = 0; c < 4; ++c) {
;             const f32x4 b0 = *(const LAS f32x4*)(cb + k0 + 8 * c + 4 * h), b1 = *(const LAS f32x4*)(cb + k0 + 32 + 8 * c + 4 * h);
; #pragma unroll
;             for (int jj = 0; jj < 4; ++jj) {
;                 const int i = 4 * c + jj; const int n0 = t - (k0 + 8 * c + 4 * h + jj), n1 = n0 - 32;
;                 float x0 = s0[i] + (b0[jj] + rowshift), x1 = s1[i] + (b1[jj] + rowshift);
;                 if (diag) { x0 = (n0 >= 0) ? x0 : NINF; x1 = (n1 >= 0) ? x1 : NINF; }
;                 s0[i] = x0; s1[i] = x1;
;             }
;         }
; __device__ __forceinline__ void qk_tile(LAS unsigned char* ks, const bf16x8 (&qf)[4], int r, int h, f32x16& s0, f32x16& s1) {
;     bf16x8 kf[8];
; #pragma unroll
;     for (int kk = 0; kk < 4; ++kk) {
;         kf[2 * kk]     = *(const LAS bf16x8*)(ks + (r * KPITCH + 16 * kk + 8 * h) * 2);
;         kf[2 * kk + 1] = *(const LAS bf16x8*)(ks + ((32 + r) * KPITCH + 16 * kk + 8 * h) * 2);
;     }
; #pragma unroll
;     for (int i = 0; i < 16; ++i) { s0[i] = 0.f; s1[i] = 0.f; }
; #pragma unroll
;     for (int kk = 0; kk < 4; ++kk) { s0 = MFMA32(kf[2 * kk], qf[kk], s0); s1 = MFMA32(kf[2 * kk + 1], qf[kk], s1); }
; }
.LBB0_588:
	s_or_b64 exec, exec, s[56:57]
	s_mul_i32 s3, s44, 0x2400
	s_and_b64 s[8:9], s[58:59], s[14:15]
	s_add_i32 s62, s3, 0
	s_xor_b64 s[8:9], s[8:9], -1
	s_and_saveexec_b64 s[56:57], s[8:9]
	s_xor_b64 s[56:57], exec, s[56:57]
	s_cbranch_execz .LBB0_596
	s_xor_b64 s[8:9], s[58:59], -1
	s_and_saveexec_b64 s[58:59], s[8:9]
	s_xor_b64 s[58:59], exec, s[58:59]
	s_cbranch_execz .LBB0_593
	s_and_saveexec_b64 s[60:61], s[14:15]
	s_cbranch_execz .LBB0_592
	v_add3_u32 v0, s62, v204, v205
	ds_read_b128 v[34:37], v0 offset:9216
	ds_read_b128 v[66:69], v0 offset:9248
	s_waitcnt lgkmcnt(1)
	v_mfma_f32_32x32x16_bf16 v[50:65], v[34:37], v[98:101], 0
	ds_read_b128 v[34:37], v0 offset:13824
	ds_read_b128 v[70:73], v0 offset:13856
	s_waitcnt lgkmcnt(1)
	v_mfma_f32_32x32x16_bf16 v[34:49], v[34:37], v[98:101], 0
	v_mfma_f32_32x32x16_bf16 v[50:65], v[66:69], v[102:105], v[50:65]
	s_waitcnt lgkmcnt(0)
	v_mfma_f32_32x32x16_bf16 v[34:49], v[70:73], v[102:105], v[34:49]
	ds_read_b128 v[66:69], v0 offset:9280
	ds_read_b128 v[70:73], v0 offset:9312
	s_waitcnt lgkmcnt(1)
	v_mfma_f32_32x32x16_bf16 v[50:65], v[66:69], v[106:109], v[50:65]
	ds_read_b128 v[66:69], v0 offset:13888
	ds_read_b128 v[74:77], v0 offset:13920
	v_add_u32_e32 v0, s40, v204
	s_waitcnt lgkmcnt(1)
	v_mfma_f32_32x32x16_bf16 v[34:49], v[66:69], v[106:109], v[34:49]
	v_add_u32_e32 v66, 0xfffffe04, v0
	ds_read_b128 v[66:69], v66
	v_mfma_f32_32x32x16_bf16 v[50:65], v[70:73], v[110:113], v[50:65]
	v_add_u32_e32 v70, 0xfffffe84, v0
	ds_read_b128 v[70:73], v70
	s_waitcnt lgkmcnt(1)
	v_add_f32_e32 v66, v176, v66
	v_mfma_f32_32x32x16_bf16 v[34:49], v[74:77], v[110:113], v[34:49]
	s_nop 6
	v_add_f32_e32 v50, v50, v66
	s_waitcnt lgkmcnt(0)
	v_add_f32_e32 v66, v176, v70
	s_nop 1
	v_add_f32_e32 v34, v34, v66
	v_add_u32_e32 v66, 0x5b, v177
	v_cmp_lt_i32_e32 vcc, -1, v66
	s_nop 1
	v_cndmask_b32_e32 v70, v238, v50, vcc
	v_cmp_lt_i32_e32 vcc, 31, v66
	s_nop 1
	v_cndmask_b32_e32 v66, v238, v34, vcc
	v_cmp_gt_i32_e32 vcc, s45, v175
	s_nop 1
	v_cndmask_b32_e32 v70, v50, v70, vcc
	v_add_f32_e32 v50, v176, v71
	v_cndmask_b32_e32 v66, v34, v66, vcc
	v_add_f32_e32 v34, v176, v67
	v_add_f32_e32 v35, v35, v50
	v_add_u32_e32 v50, 0x5a, v177
	v_add_f32_e32 v34, v51, v34
	v_cmp_lt_i32_e64 s[14:15], -1, v50
	v_exp_f32_e32 v66, v66
	s_nop 0
	v_cndmask_b32_e64 v51, v238, v34, s[14:15]
	v_cmp_lt_i32_e64 s[14:15], 31, v50
	v_cndmask_b32_e32 v67, v34, v51, vcc
	v_add_f32_e32 v34, v176, v68
	v_cndmask_b32_e64 v50, v238, v35, s[14:15]
	v_cndmask_b32_e32 v71, v35, v50, vcc
	v_add_f32_e32 v35, v176, v72
	v_add_f32_e32 v35, v36, v35
	v_add_u32_e32 v36, 0x59, v177
	v_add_f32_e32 v34, v52, v34
	v_cmp_lt_i32_e64 s[14:15], -1, v36
	s_nop 1
	v_cndmask_b32_e64 v50, v238, v34, s[14:15]
	v_cndmask_b32_e32 v68, v34, v50, vcc
	v_add_f32_e32 v34, v176, v69
	v_add_f32_e32 v69, v53, v34
	v_add_f32_e32 v34, v176, v73
	v_cmp_lt_i32_e64 s[14:15], 31, v36
	v_add_f32_e32 v73, v37, v34
	v_add_u32_e32 v34, 0x58, v177
	v_cndmask_b32_e64 v36, v238, v35, s[14:15]
	v_cmp_lt_i32_e64 s[14:15], -1, v34
	v_add_u32_e32 v50, 0xfffffea4, v0
	v_cndmask_b32_e32 v72, v35, v36, vcc
	v_cndmask_b32_e64 v74, v238, v69, s[14:15]
	v_cmp_lt_i32_e64 s[14:15], 31, v34
	v_add_u32_e32 v34, 0xfffffe24, v0
	ds_read_b128 v[34:37], v34
	ds_read_b128 v[50:53], v50
	v_cndmask_b32_e64 v75, v238, v73, s[14:15]
	v_cndmask_b32_e32 v69, v69, v74, vcc
	v_cndmask_b32_e32 v73, v73, v75, vcc
	s_waitcnt lgkmcnt(1)
	v_add_f32_e32 v34, v176, v34
	s_waitcnt lgkmcnt(0)
	v_add_f32_e32 v50, v176, v50
	v_add_f32_e32 v38, v38, v50
	v_add_u32_e32 v50, 0x53, v177
	v_add_f32_e32 v34, v54, v34
	v_cmp_lt_i32_e64 s[14:15], -1, v50
	s_nop 1
	v_cndmask_b32_e64 v54, v238, v34, s[14:15]
	v_cmp_lt_i32_e64 s[14:15], 31, v50
	v_cndmask_b32_e32 v54, v34, v54, vcc
	v_add_f32_e32 v34, v176, v35
	v_cndmask_b32_e64 v50, v238, v38, s[14:15]
	v_cndmask_b32_e32 v74, v38, v50, vcc
	v_add_u32_e32 v38, 0x52, v177
	v_add_f32_e32 v34, v55, v34
	v_add_f32_e32 v35, v176, v51
	v_cmp_lt_i32_e64 s[14:15], -1, v38
	v_add_f32_e32 v35, v39, v35
	s_nop 0
	v_cndmask_b32_e64 v39, v238, v34, s[14:15]
	v_cmp_lt_i32_e64 s[14:15], 31, v38
	v_cndmask_b32_e32 v55, v34, v39, vcc
	v_add_f32_e32 v34, v176, v36
	v_add_u32_e32 v36, 0x51, v177
	v_cndmask_b32_e64 v38, v238, v35, s[14:15]
	v_add_f32_e32 v34, v56, v34
	v_cmp_lt_i32_e64 s[14:15], -1, v36
	v_cndmask_b32_e32 v75, v35, v38, vcc
	v_add_f32_e32 v35, v176, v52
	v_cndmask_b32_e64 v38, v238, v34, s[14:15]
	v_cndmask_b32_e32 v56, v34, v38, vcc
	v_add_f32_e32 v34, v176, v37
	v_add_f32_e32 v50, v57, v34
	v_add_f32_e32 v34, v176, v53
	v_add_f32_e32 v35, v40, v35
	v_cmp_lt_i32_e64 s[14:15], 31, v36
	v_add_f32_e32 v51, v41, v34
	v_add_u32_e32 v34, 0x50, v177
	v_cndmask_b32_e64 v36, v238, v35, s[14:15]
	v_cmp_lt_i32_e64 s[14:15], -1, v34
	v_add_u32_e32 v38, 0xfffffec4, v0
	v_cndmask_b32_e32 v76, v35, v36, vcc
	v_cndmask_b32_e64 v52, v238, v50, s[14:15]
	v_cmp_lt_i32_e64 s[14:15], 31, v34
	v_add_u32_e32 v34, 0xfffffe44, v0
	ds_read_b128 v[34:37], v34
	ds_read_b128 v[38:41], v38
	v_cndmask_b32_e64 v53, v238, v51, s[14:15]
	v_cndmask_b32_e32 v57, v50, v52, vcc
	v_cndmask_b32_e32 v77, v51, v53, vcc
	s_waitcnt lgkmcnt(1)
	v_add_f32_e32 v34, v176, v34
	s_waitcnt lgkmcnt(0)
; #define LAS __attribute__((address_space(3)))
; #define MFMA32(a, b, c) __builtin_amdgcn_mfma_f32_32x32x16_bf16((a), (b), (c), 0, 0, 0)
; __device__ __forceinline__ float fexp2(float x) { return __builtin_amdgcn_exp2f(x); }
; template <int KIND>
; __device__ __forceinline__ void softmax_tile(f32x16& s0, f32x16& s1, float& l, int t, int k0, int h, int qlo, const LAS float* lut, const LAS float* cb, int W, int dmask, float rowshift) {
;     ...
;     float ps = 0.f;
; #pragma unroll
;     for (int i = 0; i < 16; ++i) { s0[i] = fexp2(s0[i]); s1[i] = fexp2(s1[i]); ps += s0[i] + s1[i]; }
;     l += ps;
; }
; __device__ __forceinline__ void pv_tile(LAS unsigned char* vt, const f32x16& s0, const f32x16& s1, int h, int lane, f32x16 (&o)[2]) {
; #pragma unroll
;     for (int st = 0; st < 2; ++st) {
;         const bf16x8 pb = pack8(s0, st);
; #pragma unroll
;         for (int db = 0; db < 2; ++db) o[db] = MFMA32(vfrag<64>(vt, 32 * db, 16 * st + 4 * h, lane), pb, o[db]);
;     }
; #pragma unroll
;     for (int st = 0; st < 2; ++st) {
;         const bf16x8 pb = pack8(s1, st);
; #pragma unroll
;         for (int db = 0; db < 2; ++db) o[db] = MFMA32(vfrag<64>(vt, 32 * db, 32 + 16 * st + 4 * h, lane), pb, o[db]);
;     }
; }
	v_add_f32_e32 v38, v176, v38
	v_add_f32_e32 v38, v42, v38
	v_add_u32_e32 v42, 0x4b, v177
	v_add_f32_e32 v34, v58, v34
	v_cmp_lt_i32_e64 s[14:15], -1, v42
	s_nop 1
	v_cndmask_b32_e64 v50, v238, v34, s[14:15]
	v_cmp_lt_i32_e64 s[14:15], 31, v42
	v_cndmask_b32_e32 v58, v34, v50, vcc
	v_add_f32_e32 v34, v176, v35
	v_cndmask_b32_e64 v42, v238, v38, s[14:15]
	v_cndmask_b32_e32 v78, v38, v42, vcc
	v_add_u32_e32 v38, 0x4a, v177
	v_add_f32_e32 v34, v59, v34
	v_cmp_lt_i32_e64 s[14:15], -1, v38
	v_add_f32_e32 v35, v176, v39
	v_add_f32_e32 v35, v43, v35
	v_cndmask_b32_e64 v39, v238, v34, s[14:15]
	v_cmp_lt_i32_e64 s[14:15], 31, v38
	v_cndmask_b32_e32 v59, v34, v39, vcc
	v_add_f32_e32 v34, v176, v36
	v_add_u32_e32 v36, 0x49, v177
	v_cndmask_b32_e64 v38, v238, v35, s[14:15]
	v_add_f32_e32 v34, v60, v34
	v_cmp_lt_i32_e64 s[14:15], -1, v36
	v_cndmask_b32_e32 v79, v35, v38, vcc
	v_add_f32_e32 v35, v176, v40
	v_cndmask_b32_e64 v38, v238, v34, s[14:15]
	v_cndmask_b32_e32 v60, v34, v38, vcc
	v_add_f32_e32 v34, v176, v37
	v_add_f32_e32 v42, v61, v34
	v_add_f32_e32 v34, v176, v41
	v_add_f32_e32 v35, v44, v35
	v_cmp_lt_i32_e64 s[14:15], 31, v36
	v_add_f32_e32 v43, v45, v34
	v_add_u32_e32 v34, 0x48, v177
	v_cndmask_b32_e64 v36, v238, v35, s[14:15]
	v_cmp_lt_i32_e64 s[14:15], -1, v34
	v_cndmask_b32_e32 v80, v35, v36, vcc
	s_nop 0
	v_cndmask_b32_e64 v44, v238, v42, s[14:15]
	v_cmp_lt_i32_e64 s[14:15], 31, v34
	v_add_u32_e32 v34, 0xfffffe64, v0
	v_add_u32_e32 v0, 0xfffffee4, v0
	ds_read_b128 v[34:37], v34
	ds_read_b128 v[38:41], v0
	v_cndmask_b32_e64 v45, v238, v43, s[14:15]
	v_cndmask_b32_e32 v61, v42, v44, vcc
	v_cndmask_b32_e32 v81, v43, v45, vcc
	s_waitcnt lgkmcnt(1)
	v_add_f32_e32 v0, v176, v34
	s_waitcnt lgkmcnt(0)
	v_add_f32_e32 v34, v176, v38
	v_add_u32_e32 v38, 0x43, v177
	v_add_f32_e32 v0, v62, v0
	v_cmp_lt_i32_e64 s[14:15], -1, v38
	v_add_f32_e32 v34, v46, v34
	v_exp_f32_e32 v44, v57
	v_cndmask_b32_e64 v42, v238, v0, s[14:15]
	v_cmp_lt_i32_e64 s[14:15], 31, v38
	v_cndmask_b32_e32 v62, v0, v42, vcc
	v_add_f32_e32 v0, v176, v35
	v_cndmask_b32_e64 v38, v238, v34, s[14:15]
	v_add_u32_e32 v35, 0x42, v177
	v_cndmask_b32_e32 v82, v34, v38, vcc
	v_add_f32_e32 v0, v63, v0
	v_add_f32_e32 v34, v176, v39
	v_cmp_lt_i32_e64 s[14:15], -1, v35
	v_add_f32_e32 v34, v47, v34
	v_exp_f32_e32 v42, v69
	v_cndmask_b32_e64 v38, v238, v0, s[14:15]
	v_cmp_lt_i32_e64 s[14:15], 31, v35
	v_cndmask_b32_e32 v63, v0, v38, vcc
	v_add_f32_e32 v0, v176, v36
	v_cndmask_b32_e64 v35, v238, v34, s[14:15]
	v_cndmask_b32_e32 v83, v34, v35, vcc
	v_add_f32_e32 v34, v64, v0
	v_add_f32_e32 v0, v176, v40
	v_exp_f32_e32 v64, v70
	v_add_f32_e32 v36, v48, v0
	v_add_u32_e32 v35, 0x41, v177
	v_exp_f32_e32 v38, v67
	v_exp_f32_e32 v0, v71
	v_cmp_lt_i32_e64 s[14:15], -1, v35
	v_exp_f32_e32 v71, v78
	v_add_u32_e32 v70, 64, v177
	v_cndmask_b32_e64 v39, v238, v34, s[14:15]
	v_cndmask_b32_e32 v67, v34, v39, vcc
	v_add_f32_e32 v39, v64, v66
	v_cmp_lt_i32_e64 s[14:15], 31, v35
	v_pk_add_f32 v[34:35], v[38:39], v[0:1]
	v_exp_f32_e32 v39, v68
	v_pk_add_f32 v[46:47], v[34:35], v[34:35] op_sel_hi:[0,1]
	v_exp_f32_e32 v68, v72
	v_exp_f32_e32 v46, v73
	v_cndmask_b32_e64 v40, v238, v36, s[14:15]
	v_cndmask_b32_e32 v69, v36, v40, vcc
	v_add_f32_e32 v43, v39, v68
	v_pk_add_f32 v[34:35], v[42:43], v[46:47]
	v_exp_f32_e32 v43, v54
	v_pk_add_f32 v[50:51], v[34:35], v[34:35] op_sel_hi:[0,1]
	v_exp_f32_e32 v47, v74
	v_exp_f32_e32 v40, v55
	v_exp_f32_e32 v50, v75
	v_add_f32_e32 v36, v176, v37
	v_add_f32_e32 v37, v176, v41
	v_add_f32_e32 v41, v43, v47
	v_pk_add_f32 v[34:35], v[40:41], v[50:51]
	v_exp_f32_e32 v41, v56
	v_pk_add_f32 v[52:53], v[34:35], v[34:35] op_sel_hi:[0,1]
	v_exp_f32_e32 v51, v76
	v_exp_f32_e32 v52, v77
	v_add_f32_e32 v36, v65, v36
	v_add_f32_e32 v65, v49, v37
	v_add_f32_e32 v45, v41, v51
	v_pk_add_f32 v[34:35], v[44:45], v[52:53]
	v_exp_f32_e32 v53, v58
	v_pk_add_f32 v[48:49], v[34:35], v[34:35] op_sel_hi:[0,1]
	v_exp_f32_e32 v54, v59
	v_exp_f32_e32 v48, v79
	v_cmp_lt_i32_e64 s[14:15], -1, v70
	v_add_f32_e32 v55, v53, v71
	v_cvt_pk_bf16_f32 v39, v39, v42
	v_cndmask_b32_e64 v34, v238, v36, s[14:15]
	v_cndmask_b32_e32 v59, v36, v34, vcc
	v_pk_add_f32 v[34:35], v[54:55], v[48:49]
	v_add_u32_e32 v49, s62, v200
	v_pk_add_f32 v[56:57], v[34:35], v[34:35] op_sel_hi:[0,1]
	ds_read_b64_tr_b16 v[74:75], v49 offset:46080
	ds_read_b64_tr_b16 v[76:77], v49 offset:47232
	ds_read_b64_tr_b16 v[84:85], v49 offset:46144
	ds_read_b64_tr_b16 v[86:87], v49 offset:47296
	ds_read_b64_tr_b16 v[88:89], v49 offset:48384
	ds_read_b64_tr_b16 v[90:91], v49 offset:49536
	v_cvt_pk_bf16_f32 v40, v43, v40
	v_cvt_pk_bf16_f32 v41, v41, v44
	v_cvt_pk_bf16_f32 v38, v64, v38
	v_exp_f32_e32 v55, v60
	v_exp_f32_e32 v58, v61
	s_waitcnt lgkmcnt(6)
; #define LAS __attribute__((address_space(3)))
; #define MFMA32(a, b, c) __builtin_amdgcn_mfma_f32_32x32x16_bf16((a), (b), (c), 0, 0, 0)
; __device__ __forceinline__ void pv_tile(LAS unsigned char* vt, const f32x16& s0, const f32x16& s1, int h, int lane, f32x16 (&o)[2]) {
; #pragma unroll
;     for (int st = 0; st < 2; ++st) {
;         const bf16x8 pb = pack8(s0, st);
; #pragma unroll
;         for (int db = 0; db < 2; ++db) o[db] = MFMA32(vfrag<64>(vt, 32 * db, 16 * st + 4 * h, lane), pb, o[db]);
;     }
; #pragma unroll
;     for (int st = 0; st < 2; ++st) {
;         const bf16x8 pb = pack8(s1, st);
; #pragma unroll
;         for (int db = 0; db < 2; ++db) o[db] = MFMA32(vfrag<64>(vt, 32 * db, 32 + 16 * st + 4 * h, lane), pb, o[db]);
;     }
; }
	ds_read_b64_tr_b16 v[92:93], v49 offset:48448
	ds_read_b64_tr_b16 v[94:95], v49 offset:49600
	s_waitcnt lgkmcnt(6)
	v_mfma_f32_32x32x16_bf16 v[18:33], v[74:77], v[38:41], v[18:33]
	v_exp_f32_e32 v61, v62
	v_exp_f32_e32 v60, v63
	v_exp_f32_e32 v63, v67
	v_exp_f32_e32 v62, v59
	v_exp_f32_e32 v72, v80
	v_exp_f32_e32 v56, v81
	ds_read_b64_tr_b16 v[74:75], v49 offset:50688
	ds_read_b64_tr_b16 v[76:77], v49 offset:51840
	s_waitcnt lgkmcnt(6)
	v_mfma_f32_32x32x16_bf16 v[2:17], v[84:87], v[38:41], v[2:17]
	v_cvt_pk_bf16_f32 v38, v53, v54
	v_cvt_pk_bf16_f32 v39, v55, v58
	v_cvt_pk_bf16_f32 v40, v61, v60
	v_cvt_pk_bf16_f32 v41, v63, v62
	v_add_f32_e32 v59, v55, v72
	v_cmp_lt_i32_e64 s[14:15], 31, v70
	ds_read_b64_tr_b16 v[84:85], v49 offset:50752
	ds_read_b64_tr_b16 v[86:87], v49 offset:51904
	s_waitcnt lgkmcnt(6)
	v_mfma_f32_32x32x16_bf16 v[18:33], v[88:91], v[38:41], v[18:33]
	v_add_f32_e64 v34, v58, v56
	v_add_f32_e64 v35, v59, v57
	v_exp_f32_e32 v57, v82
	v_pk_add_f32 v[54:55], v[34:35], v[34:35] op_sel_hi:[0,1]
	v_exp_f32_e32 v54, v83
	v_add_f32_e32 v61, v61, v57
	v_cndmask_b32_e64 v53, v238, v65, s[14:15]
	ds_read_b64_tr_b16 v[88:89], v49 offset:52992
	ds_read_b64_tr_b16 v[90:91], v49 offset:54144
	s_waitcnt lgkmcnt(6)
	v_mfma_f32_32x32x16_bf16 v[2:17], v[92:95], v[38:41], v[2:17]
	v_cvt_pk_bf16_f32 v38, v66, v0
	v_cvt_pk_bf16_f32 v39, v68, v46
	v_cvt_pk_bf16_f32 v40, v47, v50
	v_cvt_pk_bf16_f32 v41, v51, v52
	v_cndmask_b32_e32 v0, v65, v53, vcc
	v_exp_f32_e32 v50, v69
	ds_read_b64_tr_b16 v[92:93], v49 offset:53056
	ds_read_b64_tr_b16 v[94:95], v49 offset:54208
	s_waitcnt lgkmcnt(6)
	v_mfma_f32_32x32x16_bf16 v[18:33], v[74:77], v[38:41], v[18:33]
	v_add_f32_e64 v34, v60, v54
	v_add_f32_e64 v35, v61, v55
	v_add_f32_e32 v63, v63, v50
	v_add_f32_e64 v46, v34, v34
	v_add_f32_e64 v47, v34, v35
	v_exp_f32_e32 v46, v0
	s_waitcnt lgkmcnt(4)
	v_mfma_f32_32x32x16_bf16 v[2:17], v[84:87], v[38:41], v[2:17]
	v_cvt_pk_bf16_f32 v38, v71, v48
	v_cvt_pk_bf16_f32 v39, v72, v56
	v_cvt_pk_bf16_f32 v40, v57, v54
	v_cvt_pk_bf16_f32 v41, v50, v46
	s_nop 0
	s_waitcnt lgkmcnt(2)
	v_mfma_f32_32x32x16_bf16 v[18:33], v[88:91], v[38:41], v[18:33]
	v_add_f32_e64 v34, v62, v46
	v_add_f32_e64 v35, v63, v47
	v_add_f32_e32 v0, v34, v35
	v_add_f32_e32 v172, v172, v0
	s_waitcnt lgkmcnt(0)
	v_mfma_f32_32x32x16_bf16 v[2:17], v[92:95], v[38:41], v[2:17]

; #define LAS __attribute__((address_space(3)))
; #define MFMA32(a, b, c) __builtin_amdgcn_mfma_f32_32x32x16_bf16((a), (b), (c), 0, 0, 0)
; template <int KIND>
; __device__ __forceinline__ void softmax_tile(f32x16& s0, f32x16& s1, float& l, int t, int k0, int h, int qlo, const LAS float* lut, const LAS float* cb, int W, int dmask, float rowshift) {
;     ...
;         const bool diag = (k0 + 63 > qlo);
; #pragma unroll
;         for (int c = 0; c < 4; ++c) {
;             const f32x4 b0 = *(const LAS f32x4*)(cb + k0 + 8 * c + 4 * h), b1 = *(const LAS f32x4*)(cb + k0 + 32 + 8 * c + 4 * h);
; #pragma unroll
;             for (int jj = 0; jj < 4; ++jj) {
;                 const int i = 4 * c + jj; const int n0 = t - (k0 + 8 * c + 4 * h + jj), n1 = n0 - 32;
;                 float x0 = s0[i] + (b0[jj] + rowshift), x1 = s1[i] + (b1[jj] + rowshift);
;                 if (diag) { x0 = (n0 >= 0) ? x0 : NINF; x1 = (n1 >= 0) ? x1 : NINF; }
;                 s0[i] = x0; s1[i] = x1;
;             }
;         }
; __device__ __forceinline__ void qk_tile(LAS unsigned char* ks, const bf16x8 (&qf)[4], int r, int h, f32x16& s0, f32x16& s1) {
;     bf16x8 kf[8];
; #pragma unroll
;     for (int kk = 0; kk < 4; ++kk) {
;         kf[2 * kk]     = *(const LAS bf16x8*)(ks + (r * KPITCH + 16 * kk + 8 * h) * 2);
;         kf[2 * kk + 1] = *(const LAS bf16x8*)(ks + ((32 + r) * KPITCH + 16 * kk + 8 * h) * 2);
;     }
; #pragma unroll
;     for (int i = 0; i < 16; ++i) { s0[i] = 0.f; s1[i] = 0.f; }
; #pragma unroll
;     for (int kk = 0; kk < 4; ++kk) { s0 = MFMA32(kf[2 * kk], qf[kk], s0); s1 = MFMA32(kf[2 * kk + 1], qf[kk], s1); }
; }
.LBB0_593:
	s_andn2_saveexec_b64 s[58:59], s[58:59]
	s_cbranch_execz .LBB0_595
	v_add3_u32 v0, s62, v204, v205
	ds_read_b128 v[34:37], v0
	ds_read_b128 v[66:69], v0 offset:32
	s_waitcnt lgkmcnt(1)
	v_mfma_f32_32x32x16_bf16 v[50:65], v[34:37], v[98:101], 0
	ds_read_b128 v[34:37], v0 offset:4608
	ds_read_b128 v[70:73], v0 offset:4640
	s_waitcnt lgkmcnt(1)
	v_mfma_f32_32x32x16_bf16 v[34:49], v[34:37], v[98:101], 0
	v_mfma_f32_32x32x16_bf16 v[50:65], v[66:69], v[102:105], v[50:65]
	s_waitcnt lgkmcnt(0)
	v_mfma_f32_32x32x16_bf16 v[34:49], v[70:73], v[102:105], v[34:49]
	ds_read_b128 v[66:69], v0 offset:64
	ds_read_b128 v[70:73], v0 offset:96
	s_waitcnt lgkmcnt(1)
	v_mfma_f32_32x32x16_bf16 v[50:65], v[66:69], v[106:109], v[50:65]
	ds_read_b128 v[66:69], v0 offset:4672
	ds_read_b128 v[74:77], v0 offset:4704
	v_add_u32_e32 v0, s40, v204
	s_waitcnt lgkmcnt(1)
	v_mfma_f32_32x32x16_bf16 v[34:49], v[66:69], v[106:109], v[34:49]
	v_add_u32_e32 v66, 0xffffff04, v0
	ds_read_b128 v[66:69], v66
	v_mfma_f32_32x32x16_bf16 v[50:65], v[70:73], v[110:113], v[50:65]
	v_add_u32_e32 v70, 0xffffff84, v0
	ds_read_b128 v[70:73], v70
	s_waitcnt lgkmcnt(1)
	v_add_f32_e32 v66, v176, v66
	v_mfma_f32_32x32x16_bf16 v[34:49], v[74:77], v[110:113], v[34:49]
	s_nop 6
	v_add_f32_e32 v50, v50, v66
	s_waitcnt lgkmcnt(0)
	v_add_f32_e32 v66, v176, v70
	s_nop 1
	v_add_f32_e32 v34, v34, v66
	v_add_u32_e32 v66, 27, v177
	v_cmp_lt_i32_e32 vcc, -1, v66
	s_nop 1
	v_cndmask_b32_e32 v70, v238, v50, vcc
	v_cmp_lt_i32_e32 vcc, 31, v66
	s_nop 1
	v_cndmask_b32_e32 v66, v238, v34, vcc
	v_cmp_gt_i32_e32 vcc, s41, v171
	s_nop 1
	v_cndmask_b32_e32 v70, v50, v70, vcc
	v_add_f32_e32 v50, v176, v71
	v_cndmask_b32_e32 v66, v34, v66, vcc
	v_add_f32_e32 v34, v176, v67
	v_add_f32_e32 v35, v35, v50
	v_add_u32_e32 v50, 26, v177
	v_add_f32_e32 v34, v51, v34
	v_cmp_lt_i32_e64 s[14:15], -1, v50
	v_exp_f32_e32 v66, v66
	s_nop 0
	v_cndmask_b32_e64 v51, v238, v34, s[14:15]
	v_cmp_lt_i32_e64 s[14:15], 31, v50
	v_cndmask_b32_e32 v67, v34, v51, vcc
	v_add_f32_e32 v34, v176, v68
	v_cndmask_b32_e64 v50, v238, v35, s[14:15]
	v_cndmask_b32_e32 v71, v35, v50, vcc
	v_add_f32_e32 v35, v176, v72
	v_add_f32_e32 v35, v36, v35
	v_add_u32_e32 v36, 25, v177
	v_add_f32_e32 v34, v52, v34
	v_cmp_lt_i32_e64 s[14:15], -1, v36
	s_nop 1
	v_cndmask_b32_e64 v50, v238, v34, s[14:15]
	v_cndmask_b32_e32 v68, v34, v50, vcc
	v_add_f32_e32 v34, v176, v69
	v_add_f32_e32 v69, v53, v34
	v_add_f32_e32 v34, v176, v73
	v_cmp_lt_i32_e64 s[14:15], 31, v36
	v_add_f32_e32 v73, v37, v34
	v_add_u32_e32 v34, 24, v177
	v_cndmask_b32_e64 v36, v238, v35, s[14:15]
	v_cmp_lt_i32_e64 s[14:15], -1, v34
	v_add_u32_e32 v50, 0xffffffa4, v0
	v_cndmask_b32_e32 v72, v35, v36, vcc
	v_cndmask_b32_e64 v74, v238, v69, s[14:15]
	v_cmp_lt_i32_e64 s[14:15], 31, v34
	v_add_u32_e32 v34, 0xffffff24, v0
	ds_read_b128 v[34:37], v34
	ds_read_b128 v[50:53], v50
	v_cndmask_b32_e64 v75, v238, v73, s[14:15]
	v_cndmask_b32_e32 v69, v69, v74, vcc
	v_cndmask_b32_e32 v73, v73, v75, vcc
	s_waitcnt lgkmcnt(1)
	v_add_f32_e32 v34, v176, v34
	s_waitcnt lgkmcnt(0)
	v_add_f32_e32 v50, v176, v50
	v_add_f32_e32 v38, v38, v50
	v_add_u32_e32 v50, 19, v177
	v_add_f32_e32 v34, v54, v34
	v_cmp_lt_i32_e64 s[14:15], -1, v50
	s_nop 1
	v_cndmask_b32_e64 v54, v238, v34, s[14:15]
	v_cmp_lt_i32_e64 s[14:15], 31, v50
	v_cndmask_b32_e32 v54, v34, v54, vcc
	v_add_f32_e32 v34, v176, v35
	v_cndmask_b32_e64 v50, v238, v38, s[14:15]
	v_cndmask_b32_e32 v74, v38, v50, vcc
	v_add_u32_e32 v38, 18, v177
	v_add_f32_e32 v34, v55, v34
	v_add_f32_e32 v35, v176, v51
	v_cmp_lt_i32_e64 s[14:15], -1, v38
	v_add_f32_e32 v35, v39, v35
	s_nop 0
	v_cndmask_b32_e64 v39, v238, v34, s[14:15]
	v_cmp_lt_i32_e64 s[14:15], 31, v38
	v_cndmask_b32_e32 v55, v34, v39, vcc
	v_add_f32_e32 v34, v176, v36
	v_add_u32_e32 v36, 17, v177
	v_cndmask_b32_e64 v38, v238, v35, s[14:15]
	v_add_f32_e32 v34, v56, v34
	v_cmp_lt_i32_e64 s[14:15], -1, v36
	v_cndmask_b32_e32 v75, v35, v38, vcc
	v_add_f32_e32 v35, v176, v52
	v_cndmask_b32_e64 v38, v238, v34, s[14:15]
	v_cndmask_b32_e32 v56, v34, v38, vcc
	v_add_f32_e32 v34, v176, v37
	v_add_f32_e32 v50, v57, v34
	v_add_f32_e32 v34, v176, v53
	v_add_f32_e32 v35, v40, v35
	v_cmp_lt_i32_e64 s[14:15], 31, v36
	v_add_f32_e32 v51, v41, v34
	v_add_u32_e32 v34, 16, v177
	v_cndmask_b32_e64 v36, v238, v35, s[14:15]
	v_cmp_lt_i32_e64 s[14:15], -1, v34
	v_subrev_u32_e32 v38, 60, v0
	v_cndmask_b32_e32 v76, v35, v36, vcc
	v_cndmask_b32_e64 v52, v238, v50, s[14:15]
	v_cmp_lt_i32_e64 s[14:15], 31, v34
	v_add_u32_e32 v34, 0xffffff44, v0
	ds_read_b128 v[34:37], v34
	ds_read_b128 v[38:41], v38
	v_cndmask_b32_e64 v53, v238, v51, s[14:15]
	v_cndmask_b32_e32 v57, v50, v52, vcc
	v_cndmask_b32_e32 v77, v51, v53, vcc
	s_waitcnt lgkmcnt(1)
	v_add_f32_e32 v34, v176, v34
	s_waitcnt lgkmcnt(0)
	v_add_f32_e32 v38, v176, v38
	v_add_f32_e32 v38, v42, v38
	v_add_u32_e32 v42, 11, v177
	v_add_f32_e32 v34, v58, v34
	v_cmp_lt_i32_e64 s[14:15], -1, v42
	s_nop 1
	v_cndmask_b32_e64 v50, v238, v34, s[14:15]
	v_cmp_lt_i32_e64 s[14:15], 31, v42
	v_cndmask_b32_e32 v58, v34, v50, vcc
	v_add_f32_e32 v34, v176, v35
	v_cndmask_b32_e64 v42, v238, v38, s[14:15]
	v_cndmask_b32_e32 v78, v38, v42, vcc
	v_add_u32_e32 v38, 10, v177
	v_add_f32_e32 v34, v59, v34
	v_cmp_lt_i32_e64 s[14:15], -1, v38
	v_add_f32_e32 v35, v176, v39
	v_add_f32_e32 v35, v43, v35
	v_cndmask_b32_e64 v39, v238, v34, s[14:15]
	v_cmp_lt_i32_e64 s[14:15], 31, v38
	v_cndmask_b32_e32 v59, v34, v39, vcc
	v_add_f32_e32 v34, v176, v36
	v_add_u32_e32 v36, 9, v177
	v_cndmask_b32_e64 v38, v238, v35, s[14:15]
	v_add_f32_e32 v34, v60, v34
	v_cmp_lt_i32_e64 s[14:15], -1, v36
	v_cndmask_b32_e32 v79, v35, v38, vcc
	v_add_f32_e32 v35, v176, v40
	v_cndmask_b32_e64 v38, v238, v34, s[14:15]
	v_cndmask_b32_e32 v60, v34, v38, vcc
	v_add_f32_e32 v34, v176, v37
	v_add_f32_e32 v42, v61, v34
	v_add_f32_e32 v34, v176, v41
	v_add_f32_e32 v35, v44, v35
	v_cmp_lt_i32_e64 s[14:15], 31, v36
	v_add_f32_e32 v43, v45, v34
	v_add_u32_e32 v34, 8, v177
	v_cndmask_b32_e64 v36, v238, v35, s[14:15]
	v_cmp_lt_i32_e64 s[14:15], -1, v34
	v_cndmask_b32_e32 v80, v35, v36, vcc
	s_nop 0
	v_cndmask_b32_e64 v44, v238, v42, s[14:15]
	v_cmp_lt_i32_e64 s[14:15], 31, v34
	v_add_u32_e32 v34, 0xffffff64, v0
	v_subrev_u32_e32 v0, 28, v0
	ds_read_b128 v[34:37], v34
	ds_read_b128 v[38:41], v0
	v_cndmask_b32_e64 v45, v238, v43, s[14:15]
	v_cndmask_b32_e32 v61, v42, v44, vcc
	v_cndmask_b32_e32 v81, v43, v45, vcc
	s_waitcnt lgkmcnt(1)
; #define LAS __attribute__((address_space(3)))
; #define MFMA32(a, b, c) __builtin_amdgcn_mfma_f32_32x32x16_bf16((a), (b), (c), 0, 0, 0)
; __device__ __forceinline__ float fexp2(float x) { return __builtin_amdgcn_exp2f(x); }
; template <int KIND>
; __device__ __forceinline__ void softmax_tile(f32x16& s0, f32x16& s1, float& l, int t, int k0, int h, int qlo, const LAS float* lut, const LAS float* cb, int W, int dmask, float rowshift) {
;     ...
;     float ps = 0.f;
; #pragma unroll
;     for (int i = 0; i < 16; ++i) { s0[i] = fexp2(s0[i]); s1[i] = fexp2(s1[i]); ps += s0[i] + s1[i]; }
;     l += ps;
; }
; __device__ __forceinline__ void pv_tile(LAS unsigned char* vt, const f32x16& s0, const f32x16& s1, int h, int lane, f32x16 (&o)[2]) {
; #pragma unroll
;     for (int st = 0; st < 2; ++st) {
;         const bf16x8 pb = pack8(s0, st);
; #pragma unroll
;         for (int db = 0; db < 2; ++db) o[db] = MFMA32(vfrag<64>(vt, 32 * db, 16 * st + 4 * h, lane), pb, o[db]);
;     }
; #pragma unroll
;     for (int st = 0; st < 2; ++st) {
;         const bf16x8 pb = pack8(s1, st);
; #pragma unroll
;         for (int db = 0; db < 2; ++db) o[db] = MFMA32(vfrag<64>(vt, 32 * db, 32 + 16 * st + 4 * h, lane), pb, o[db]);
;     }
; }
	v_add_f32_e32 v0, v176, v34
	s_waitcnt lgkmcnt(0)
	v_add_f32_e32 v34, v176, v38
	v_add_u32_e32 v38, 3, v177
	v_add_f32_e32 v0, v62, v0
	v_cmp_lt_i32_e64 s[14:15], -1, v38
	v_add_f32_e32 v34, v46, v34
	s_nop 0
	v_cndmask_b32_e64 v42, v238, v0, s[14:15]
	v_cmp_lt_i32_e64 s[14:15], 31, v38
	v_cndmask_b32_e32 v62, v0, v42, vcc
	v_add_f32_e32 v0, v176, v35
	v_add_u32_e32 v35, 2, v177
	v_cndmask_b32_e64 v38, v238, v34, s[14:15]
	v_add_f32_e32 v0, v63, v0
	v_cmp_lt_i32_e64 s[14:15], -1, v35
	v_cndmask_b32_e32 v82, v34, v38, vcc
	v_add_f32_e32 v34, v176, v39
	v_cndmask_b32_e64 v38, v238, v0, s[14:15]
	v_cndmask_b32_e32 v63, v0, v38, vcc
	v_add_f32_e32 v0, v176, v36
	v_add_f32_e32 v36, v64, v0
	v_add_f32_e32 v0, v176, v40
	v_exp_f32_e32 v64, v70
	v_add_f32_e32 v34, v47, v34
	v_cmp_lt_i32_e64 s[14:15], 31, v35
	v_add_f32_e32 v40, v48, v0
	v_exp_f32_e32 v38, v67
	v_exp_f32_e32 v0, v71
	v_cndmask_b32_e64 v35, v238, v34, s[14:15]
	v_cndmask_b32_e32 v83, v34, v35, vcc
	v_add_u32_e32 v34, 1, v177
	v_cmp_lt_i32_e64 s[14:15], -1, v34
	v_add_f32_e32 v39, v64, v66
	v_exp_f32_e32 v67, v72
	v_cndmask_b32_e64 v43, v238, v36, s[14:15]
	v_cmp_lt_i32_e64 s[14:15], 31, v34
	v_pk_add_f32 v[34:35], v[38:39], v[0:1]
	v_exp_f32_e32 v39, v68
	v_pk_add_f32 v[46:47], v[34:35], v[34:35] op_sel_hi:[0,1]
	v_exp_f32_e32 v42, v69
	v_exp_f32_e32 v46, v73
	v_cndmask_b32_e32 v68, v36, v43, vcc
	v_add_f32_e32 v43, v39, v67
	v_cndmask_b32_e64 v44, v238, v40, s[14:15]
	v_pk_add_f32 v[34:35], v[42:43], v[46:47]
	v_cndmask_b32_e32 v69, v40, v44, vcc
	v_pk_add_f32 v[50:51], v[34:35], v[34:35] op_sel_hi:[0,1]
	v_exp_f32_e32 v40, v54
	v_exp_f32_e32 v47, v74
	v_exp_f32_e32 v44, v55
	v_exp_f32_e32 v50, v75
	v_add_f32_e32 v34, v176, v37
	v_add_f32_e32 v45, v40, v47
	v_add_f32_e32 v36, v65, v34
	v_pk_add_f32 v[34:35], v[44:45], v[50:51]
	v_exp_f32_e32 v43, v56
	v_pk_add_f32 v[52:53], v[34:35], v[34:35] op_sel_hi:[0,1]
	v_exp_f32_e32 v51, v76
	v_exp_f32_e32 v48, v57
	v_exp_f32_e32 v52, v77
	v_add_f32_e32 v34, v176, v41
	v_add_f32_e32 v65, v49, v34
	v_add_f32_e32 v49, v43, v51
	v_pk_add_f32 v[34:35], v[48:49], v[52:53]
	v_exp_f32_e32 v49, v58
	v_pk_add_f32 v[54:55], v[34:35], v[34:35] op_sel_hi:[0,1]
	v_exp_f32_e32 v53, v78
	v_exp_f32_e32 v56, v59
	v_exp_f32_e32 v54, v79
	v_cmp_lt_i32_e64 s[14:15], -1, v177
	v_add_f32_e32 v57, v49, v53
	v_cvt_pk_bf16_f32 v39, v39, v42
	v_cndmask_b32_e64 v34, v238, v36, s[14:15]
	v_cndmask_b32_e32 v70, v36, v34, vcc
	v_pk_add_f32 v[34:35], v[56:57], v[54:55]
	v_add_u32_e32 v55, s62, v200
	v_pk_add_f32 v[58:59], v[34:35], v[34:35] op_sel_hi:[0,1]
	ds_read_b64_tr_b16 v[72:73], v55 offset:36864
	ds_read_b64_tr_b16 v[74:75], v55 offset:38016
	ds_read_b64_tr_b16 v[76:77], v55 offset:36928
	ds_read_b64_tr_b16 v[78:79], v55 offset:38080
	ds_read_b64_tr_b16 v[84:85], v55 offset:39168
	ds_read_b64_tr_b16 v[86:87], v55 offset:40320
	v_cvt_pk_bf16_f32 v40, v40, v44
	v_cvt_pk_bf16_f32 v41, v43, v48
	v_cvt_pk_bf16_f32 v38, v64, v38
	v_exp_f32_e32 v57, v60
	v_exp_f32_e32 v48, v61
	s_waitcnt lgkmcnt(6)
	ds_read_b64_tr_b16 v[88:89], v55 offset:39232
	ds_read_b64_tr_b16 v[90:91], v55 offset:40384
	s_waitcnt lgkmcnt(6)
	v_mfma_f32_32x32x16_bf16 v[18:33], v[72:75], v[38:41], v[18:33]
	v_exp_f32_e32 v61, v62
	v_exp_f32_e32 v60, v63
	v_exp_f32_e32 v63, v68
	v_exp_f32_e32 v62, v70
	v_exp_f32_e32 v71, v80
	v_exp_f32_e32 v58, v81
	ds_read_b64_tr_b16 v[72:73], v55 offset:41472
	ds_read_b64_tr_b16 v[74:75], v55 offset:42624
	s_waitcnt lgkmcnt(6)
	v_mfma_f32_32x32x16_bf16 v[2:17], v[76:79], v[38:41], v[2:17]
	v_cvt_pk_bf16_f32 v38, v49, v56
	v_cvt_pk_bf16_f32 v39, v57, v48
	v_cvt_pk_bf16_f32 v40, v61, v60
	v_cvt_pk_bf16_f32 v41, v63, v62
	v_add_f32_e32 v49, v57, v71
	v_exp_f32_e32 v57, v82
	ds_read_b64_tr_b16 v[76:77], v55 offset:41536
	ds_read_b64_tr_b16 v[78:79], v55 offset:42688
	s_waitcnt lgkmcnt(6)
	v_mfma_f32_32x32x16_bf16 v[18:33], v[84:87], v[38:41], v[18:33]
	v_add_f32_e64 v34, v48, v58
	v_add_f32_e64 v35, v49, v59
	v_cmp_lt_i32_e64 s[14:15], 31, v177
	v_add_f32_e64 v48, v34, v34
	v_add_f32_e64 v49, v34, v35
	v_exp_f32_e32 v48, v83
	v_add_f32_e32 v61, v61, v57
	v_cndmask_b32_e64 v56, v238, v65, s[14:15]
	ds_read_b64_tr_b16 v[84:85], v55 offset:43776
	ds_read_b64_tr_b16 v[86:87], v55 offset:44928
	s_waitcnt lgkmcnt(6)
	v_mfma_f32_32x32x16_bf16 v[2:17], v[88:91], v[38:41], v[2:17]
	v_cvt_pk_bf16_f32 v38, v66, v0
	v_cvt_pk_bf16_f32 v39, v67, v46
	v_cvt_pk_bf16_f32 v40, v47, v50
	v_cvt_pk_bf16_f32 v41, v51, v52
	v_cndmask_b32_e32 v0, v65, v56, vcc
	ds_read_b64_tr_b16 v[88:89], v55 offset:43840
	ds_read_b64_tr_b16 v[90:91], v55 offset:44992
	s_waitcnt lgkmcnt(6)
	v_mfma_f32_32x32x16_bf16 v[18:33], v[72:75], v[38:41], v[18:33]
	v_add_f32_e64 v34, v60, v48
	v_add_f32_e64 v35, v61, v49
	v_exp_f32_e32 v49, v69
	v_pk_add_f32 v[46:47], v[34:35], v[34:35] op_sel_hi:[0,1]
	v_exp_f32_e32 v46, v0
	v_add_f32_e32 v63, v63, v49
	s_waitcnt lgkmcnt(4)
	v_mfma_f32_32x32x16_bf16 v[2:17], v[76:79], v[38:41], v[2:17]
	v_cvt_pk_bf16_f32 v38, v53, v54
	v_cvt_pk_bf16_f32 v39, v71, v58
	v_cvt_pk_bf16_f32 v40, v57, v48
	v_cvt_pk_bf16_f32 v41, v49, v46
	s_nop 0
	s_waitcnt lgkmcnt(2)
	v_mfma_f32_32x32x16_bf16 v[18:33], v[84:87], v[38:41], v[18:33]
	v_add_f32_e64 v34, v62, v46
	v_add_f32_e64 v35, v63, v47
	v_add_f32_e32 v0, v34, v35
	v_add_f32_e32 v172, v172, v0
	s_waitcnt lgkmcnt(0)
	v_mfma_f32_32x32x16_bf16 v[2:17], v[88:91], v[38:41], v[2:17]

; #define LAS __attribute__((address_space(3)))
; #define MFMA32(a, b, c) __builtin_amdgcn_mfma_f32_32x32x16_bf16((a), (b), (c), 0, 0, 0)
; __device__ __forceinline__ void qk_tile(LAS unsigned char* ks, const bf16x8 (&qf)[4], int r, int h, f32x16& s0, f32x16& s1) {
;     bf16x8 kf[8];
; #pragma unroll
;     for (int kk = 0; kk < 4; ++kk) {
;         kf[2 * kk]     = *(const LAS bf16x8*)(ks + (r * KPITCH + 16 * kk + 8 * h) * 2);
;         kf[2 * kk + 1] = *(const LAS bf16x8*)(ks + ((32 + r) * KPITCH + 16 * kk + 8 * h) * 2);
;     }
; #pragma unroll
;     for (int i = 0; i < 16; ++i) { s0[i] = 0.f; s1[i] = 0.f; }
; #pragma unroll
;     for (int kk = 0; kk < 4; ++kk) { s0 = MFMA32(kf[2 * kk], qf[kk], s0); s1 = MFMA32(kf[2 * kk + 1], qf[kk], s1); }
; }
; template <int KIND  > ...
;     ...
;         if (actA && actB) {
;             f32x16 a0, a1, b0, b1;
;             qk_tile(ksA, qf, r, h, a0, a1);
;             qk_tile(ksB, qf, r, h, b0, b1);
;             score_tile<KIND>(a0, a1, l, Rr, t, k0a, h, qlo, lut, cb, W, dmask, rowshift);
.LBB0_596:
	s_andn2_saveexec_b64 s[56:57], s[56:57]
	s_cbranch_execz .LBB0_598
	v_add_u32_e32 v0, s62, v206
	ds_read_b128 v[34:37], v0 offset:4608
	ds_read_b128 v[38:41], v0
	ds_read_b128 v[42:45], v0 offset:32
	ds_read_b128 v[46:49], v0 offset:4640
	ds_read_b128 v[50:53], v0 offset:64
	ds_read_b128 v[54:57], v0 offset:4672
	ds_read_b128 v[58:61], v0 offset:96
	ds_read_b128 v[62:65], v0 offset:4704
	s_waitcnt lgkmcnt(6)
	v_mfma_f32_32x32x16_bf16 v[66:81], v[38:41], v[98:101], 0
	v_add_u32_e32 v133, s40, v204
	v_cmp_gt_i32_e32 vcc, s41, v171
	v_mfma_f32_32x32x16_bf16 v[82:97], v[34:37], v[98:101], 0
	ds_read_b128 v[34:37], v0 offset:9216
	ds_read_b128 v[38:41], v0 offset:13824
	ds_read_b128 v[134:137], v0 offset:9248
	ds_read_b128 v[138:141], v0 offset:13856
	ds_read_b128 v[142:145], v0 offset:9280
	ds_read_b128 v[146:149], v0 offset:13888
	ds_read_b128 v[150:153], v0 offset:9312
	ds_read_b128 v[158:161], v0 offset:13920
	v_add_u32_e32 v0, 0xffffff04, v133
	s_waitcnt lgkmcnt(13)
	v_mfma_f32_32x32x16_bf16 v[66:81], v[42:45], v[102:105], v[66:81]
	s_waitcnt lgkmcnt(12)
	v_mfma_f32_32x32x16_bf16 v[82:97], v[46:49], v[102:105], v[82:97]
	s_waitcnt lgkmcnt(11)
	v_mfma_f32_32x32x16_bf16 v[66:81], v[50:53], v[106:109], v[66:81]
	s_waitcnt lgkmcnt(10)
	v_mfma_f32_32x32x16_bf16 v[82:97], v[54:57], v[106:109], v[82:97]
	s_waitcnt lgkmcnt(9)
	v_mfma_f32_32x32x16_bf16 v[66:81], v[58:61], v[110:113], v[66:81]
	s_waitcnt lgkmcnt(8)
	v_mfma_f32_32x32x16_bf16 v[82:97], v[62:65], v[110:113], v[82:97]
	s_waitcnt lgkmcnt(7)
	v_mfma_f32_32x32x16_bf16 v[50:65], v[34:37], v[98:101], 0
	s_waitcnt lgkmcnt(6)
	v_mfma_f32_32x32x16_bf16 v[34:49], v[38:41], v[98:101], 0
	s_waitcnt lgkmcnt(4)
	v_mfma_f32_32x32x16_bf16 v[34:49], v[138:141], v[102:105], v[34:49]
	v_add_u32_e32 v138, 0xffffff84, v133
	v_mfma_f32_32x32x16_bf16 v[50:65], v[134:137], v[102:105], v[50:65]
	ds_read_b128 v[134:137], v0
	ds_read_b128 v[138:141], v138
	s_waitcnt lgkmcnt(1)
	v_add_f32_e32 v0, v176, v134
	v_add_f32_e32 v0, v66, v0
	s_waitcnt lgkmcnt(0)
	v_add_f32_e32 v66, v176, v138
	v_add_f32_e32 v66, v82, v66
	v_add_u32_e32 v82, 27, v177
	v_cmp_lt_i32_e64 s[14:15], -1, v82
	v_mfma_f32_32x32x16_bf16 v[50:65], v[142:145], v[106:109], v[50:65]
	s_nop 0
	v_cndmask_b32_e64 v134, v238, v0, s[14:15]
	v_cmp_lt_i32_e64 s[14:15], 31, v82
	v_cndmask_b32_e32 v0, v0, v134, vcc
	s_nop 0
	v_cndmask_b32_e64 v82, v238, v66, s[14:15]
	v_cndmask_b32_e32 v134, v66, v82, vcc
	v_add_f32_e32 v66, v176, v135
	v_add_u32_e32 v82, 26, v177
	v_add_f32_e32 v66, v67, v66
	v_add_f32_e32 v67, v176, v139
	v_cmp_lt_i32_e64 s[14:15], -1, v82
	v_add_f32_e32 v67, v83, v67
	v_mfma_f32_32x32x16_bf16 v[34:49], v[146:149], v[106:109], v[34:49]
	v_cndmask_b32_e64 v83, v238, v66, s[14:15]
	v_cmp_lt_i32_e64 s[14:15], 31, v82
	v_cndmask_b32_e32 v135, v66, v83, vcc
	v_add_f32_e32 v66, v176, v136
	v_cndmask_b32_e64 v82, v238, v67, s[14:15]
	v_add_f32_e32 v66, v68, v66
	v_add_u32_e32 v68, 25, v177
	v_cndmask_b32_e32 v138, v67, v82, vcc
	v_add_f32_e32 v67, v176, v140
	v_cmp_lt_i32_e64 s[14:15], -1, v68
	v_add_f32_e32 v67, v84, v67
	v_mfma_f32_32x32x16_bf16 v[50:65], v[150:153], v[110:113], v[50:65]
	v_cndmask_b32_e64 v82, v238, v66, s[14:15]
	v_cmp_lt_i32_e64 s[14:15], 31, v68
	v_cndmask_b32_e32 v136, v66, v82, vcc
	v_add_f32_e32 v66, v176, v137
	v_cndmask_b32_e64 v68, v238, v67, s[14:15]
	v_cndmask_b32_e32 v139, v67, v68, vcc
	v_add_u32_e32 v68, 24, v177
	v_add_f32_e32 v66, v69, v66
	v_add_f32_e32 v67, v176, v141
	v_cmp_lt_i32_e64 s[14:15], -1, v68
	v_add_f32_e32 v67, v85, v67
	v_add_u32_e32 v82, 0xffffffa4, v133
	v_cndmask_b32_e64 v69, v238, v66, s[14:15]
	v_cmp_lt_i32_e64 s[14:15], 31, v68
	v_cndmask_b32_e32 v137, v66, v69, vcc
	v_add_u32_e32 v66, 0xffffff24, v133
	v_cndmask_b32_e64 v68, v238, v67, s[14:15]
	v_cndmask_b32_e32 v140, v67, v68, vcc
	ds_read_b128 v[66:69], v66
	ds_read_b128 v[82:85], v82
	v_exp_f32_e32 v150, v0
	v_add_u32_e32 v0, s62, v200
	v_mfma_f32_32x32x16_bf16 v[34:49], v[158:161], v[110:113], v[34:49]
	s_waitcnt lgkmcnt(1)
	v_add_f32_e32 v66, v176, v66
	v_add_f32_e32 v66, v70, v66
	s_waitcnt lgkmcnt(0)
	v_add_f32_e32 v70, v176, v82
	v_add_u32_e32 v82, 19, v177
	v_cmp_lt_i32_e64 s[14:15], -1, v82
	v_add_f32_e32 v70, v86, v70
	v_exp_f32_e32 v152, v135
	v_cndmask_b32_e64 v86, v238, v66, s[14:15]
	v_cmp_lt_i32_e64 s[14:15], 31, v82
	v_cndmask_b32_e32 v141, v66, v86, vcc
	v_add_f32_e32 v66, v176, v67
	v_cndmask_b32_e64 v82, v238, v70, s[14:15]
	v_cndmask_b32_e32 v142, v70, v82, vcc
	v_add_u32_e32 v70, 18, v177
	v_add_f32_e32 v66, v71, v66
	v_add_f32_e32 v67, v176, v83
	v_cmp_lt_i32_e64 s[14:15], -1, v70
	v_add_f32_e32 v67, v87, v67
	v_exp_f32_e32 v154, v136
	v_cndmask_b32_e64 v71, v238, v66, s[14:15]
	v_cmp_lt_i32_e64 s[14:15], 31, v70
	v_cndmask_b32_e32 v83, v66, v71, vcc
	v_add_f32_e32 v66, v176, v68
	v_cndmask_b32_e64 v70, v238, v67, s[14:15]
	v_add_u32_e32 v68, 17, v177
	v_cndmask_b32_e32 v87, v67, v70, vcc
	v_add_f32_e32 v66, v72, v66
	v_add_f32_e32 v67, v176, v84
	v_cmp_lt_i32_e64 s[14:15], -1, v68
	v_add_f32_e32 v67, v88, v67
	v_exp_f32_e32 v158, v137
	v_cndmask_b32_e64 v70, v238, v66, s[14:15]
	v_cmp_lt_i32_e64 s[14:15], 31, v68
	v_cndmask_b32_e32 v143, v66, v70, vcc
	v_add_f32_e32 v66, v176, v69
	v_cndmask_b32_e64 v68, v238, v67, s[14:15]
	v_cndmask_b32_e32 v144, v67, v68, vcc
	v_add_u32_e32 v68, 16, v177
	v_add_f32_e32 v66, v73, v66
	v_add_f32_e32 v67, v176, v85
	v_cmp_lt_i32_e64 s[14:15], -1, v68
	v_add_f32_e32 v67, v89, v67
	v_subrev_u32_e32 v70, 60, v133
	v_cndmask_b32_e64 v69, v238, v66, s[14:15]
	v_cmp_lt_i32_e64 s[14:15], 31, v68
	v_cndmask_b32_e32 v85, v66, v69, vcc
	v_add_u32_e32 v66, 0xffffff44, v133
	v_cndmask_b32_e64 v68, v238, v67, s[14:15]
	v_cndmask_b32_e32 v89, v67, v68, vcc
	ds_read_b128 v[66:69], v66
	ds_read_b128 v[70:73], v70
	v_exp_f32_e32 v160, v141
	v_exp_f32_e32 v162, v83
	v_exp_f32_e32 v164, v143
	s_waitcnt lgkmcnt(1)
; #define LAS __attribute__((address_space(3)))
; #define MFMA32(a, b, c) __builtin_amdgcn_mfma_f32_32x32x16_bf16((a), (b), (c), 0, 0, 0)
; __device__ __forceinline__ float fexp2(float x) { return __builtin_amdgcn_exp2f(x); }
; template <int KIND>
; __device__ __forceinline__ void softmax_tile(f32x16& s0, f32x16& s1, float& l, int t, int k0, int h, int qlo, const LAS float* lut, const LAS float* cb, int W, int dmask, float rowshift) {
;     ...
;         const bool diag = (k0 + 63 > qlo);
; #pragma unroll
;         for (int c = 0; c < 4; ++c) {
;             const f32x4 b0 = *(const LAS f32x4*)(cb + k0 + 8 * c + 4 * h), b1 = *(const LAS f32x4*)(cb + k0 + 32 + 8 * c + 4 * h);
; #pragma unroll
;             for (int jj = 0; jj < 4; ++jj) {
;                 const int i = 4 * c + jj; const int n0 = t - (k0 + 8 * c + 4 * h + jj), n1 = n0 - 32;
;                 float x0 = s0[i] + (b0[jj] + rowshift), x1 = s1[i] + (b1[jj] + rowshift);
;                 if (diag) { x0 = (n0 >= 0) ? x0 : NINF; x1 = (n1 >= 0) ? x1 : NINF; }
;                 s0[i] = x0; s1[i] = x1;
;             }
;         }
;     } else {
; #pragma unroll
;         for (int i = 0; i < 16; ++i) {
;             const int j0 = k0 + (i & 3) + 8 * (i >> 2) + 4 * h, n0 = t - j0, n1 = n0 - 32;
;             const float b0 = lut[min(max(n0, 0), 128)], b1 = lut[min(max(n1, 0), 128)];
;             const bool v0 = (n0 >= 0) && (n0 <= W) && ((n0 & dmask) == 0), v1 = (n1 >= 0) && (n1 <= W) && ((n1 & dmask) == 0);
;             s0[i] = v0 ? s0[i] + b0 : NINF; s1[i] = v1 ? s1[i] + b1 : NINF;
;         }
;     }
;     float ps = 0.f;
; #pragma unroll
;     for (int i = 0; i < 16; ++i) { s0[i] = fexp2(s0[i]); s1[i] = fexp2(s1[i]); ps += s0[i] + s1[i]; }
;     l += ps;
; }
; __device__ __forceinline__ void pv_tile(LAS unsigned char* vt, const f32x16& s0, const f32x16& s1, int h, int lane, f32x16 (&o)[2]) {
; #pragma unroll
;     for (int st = 0; st < 2; ++st) {
;         const bf16x8 pb = pack8(s0, st);
; #pragma unroll
;         for (int db = 0; db < 2; ++db) o[db] = MFMA32(vfrag<64>(vt, 32 * db, 16 * st + 4 * h, lane), pb, o[db]);
;     }
; #pragma unroll
;     for (int st = 0; st < 2; ++st) {
;         const bf16x8 pb = pack8(s1, st);
; #pragma unroll
;         for (int db = 0; db < 2; ++db) o[db] = MFMA32(vfrag<64>(vt, 32 * db, 32 + 16 * st + 4 * h, lane), pb, o[db]);
;     }
; }
	v_add_f32_e32 v66, v176, v66
	v_add_f32_e32 v66, v74, v66
	v_add_u32_e32 v74, 11, v177
	s_waitcnt lgkmcnt(0)
	v_add_f32_e32 v70, v176, v70
	v_cmp_lt_i32_e64 s[14:15], -1, v74
	v_add_f32_e32 v70, v90, v70
	v_exp_f32_e32 v166, v85
	v_cndmask_b32_e64 v82, v238, v66, s[14:15]
	v_cmp_lt_i32_e64 s[14:15], 31, v74
	v_cndmask_b32_e32 v145, v66, v82, vcc
	v_add_f32_e32 v66, v176, v67
	v_cndmask_b32_e64 v74, v238, v70, s[14:15]
	v_cndmask_b32_e32 v74, v70, v74, vcc
	v_add_u32_e32 v70, 10, v177
	v_add_f32_e32 v66, v75, v66
	v_add_f32_e32 v67, v176, v71
	v_cmp_lt_i32_e64 s[14:15], -1, v70
	v_add_f32_e32 v67, v91, v67
	v_cvt_pk_bf16_f32 v178, v150, v152
	v_cndmask_b32_e64 v71, v238, v66, s[14:15]
	v_cmp_lt_i32_e64 s[14:15], 31, v70
	v_cndmask_b32_e32 v75, v66, v71, vcc
	v_add_f32_e32 v66, v176, v68
	v_cndmask_b32_e64 v70, v238, v67, s[14:15]
	v_add_u32_e32 v68, 9, v177
	v_cndmask_b32_e32 v91, v67, v70, vcc
	v_add_f32_e32 v66, v76, v66
	v_add_f32_e32 v67, v176, v72
	v_cmp_lt_i32_e64 s[14:15], -1, v68
	v_add_f32_e32 v67, v92, v67
	v_cvt_pk_bf16_f32 v179, v154, v158
	v_cndmask_b32_e64 v70, v238, v66, s[14:15]
	v_cmp_lt_i32_e64 s[14:15], 31, v68
	v_cndmask_b32_e32 v76, v66, v70, vcc
	v_add_f32_e32 v66, v176, v69
	v_cndmask_b32_e64 v68, v238, v67, s[14:15]
	v_cndmask_b32_e32 v146, v67, v68, vcc
	v_add_u32_e32 v68, 8, v177
	v_add_f32_e32 v66, v77, v66
	v_add_f32_e32 v67, v176, v73
	v_cmp_lt_i32_e64 s[14:15], -1, v68
	v_add_f32_e32 v67, v93, v67
	v_subrev_u32_e32 v70, 28, v133
	v_cndmask_b32_e64 v69, v238, v66, s[14:15]
	v_cmp_lt_i32_e64 s[14:15], 31, v68
	v_cndmask_b32_e32 v77, v66, v69, vcc
	v_add_u32_e32 v66, 0xffffff64, v133
	v_cndmask_b32_e64 v68, v238, v67, s[14:15]
	v_cndmask_b32_e32 v93, v67, v68, vcc
	ds_read_b128 v[66:69], v66
	ds_read_b128 v[70:73], v70
	ds_read_b64_tr_b16 v[240:241], v0 offset:36864
	ds_read_b64_tr_b16 v[242:243], v0 offset:38016
	ds_read_b64_tr_b16 v[244:245], v0 offset:36928
	ds_read_b64_tr_b16 v[246:247], v0 offset:38080
	v_cvt_pk_bf16_f32 v180, v160, v162
	v_cvt_pk_bf16_f32 v181, v164, v166
	s_waitcnt lgkmcnt(5)
	v_add_f32_e32 v66, v176, v66
	v_add_f32_e32 v66, v78, v66
	v_add_u32_e32 v78, 3, v177
	s_waitcnt lgkmcnt(4)
	v_add_f32_e32 v70, v176, v70
	v_cmp_lt_i32_e64 s[14:15], -1, v78
	v_add_f32_e32 v70, v94, v70
	s_waitcnt lgkmcnt(2)
	ds_read_b64_tr_b16 v[248:249], v0 offset:39168
	ds_read_b64_tr_b16 v[250:251], v0 offset:40320
	s_waitcnt lgkmcnt(4)
	v_mfma_f32_32x32x16_bf16 v[18:33], v[240:243], v[178:181], v[18:33]
	v_cndmask_b32_e64 v82, v238, v66, s[14:15]
	v_cmp_lt_i32_e64 s[14:15], 31, v78
	v_cndmask_b32_e32 v147, v66, v82, vcc
	v_add_f32_e32 v66, v176, v67
	v_cndmask_b32_e64 v78, v238, v70, s[14:15]
	v_cndmask_b32_e32 v78, v70, v78, vcc
	v_add_u32_e32 v70, 2, v177
	v_add_f32_e32 v66, v79, v66
	v_add_f32_e32 v67, v176, v71
	v_cmp_lt_i32_e64 s[14:15], -1, v70
	v_add_f32_e32 v67, v95, v67
	s_nop 0
	v_cndmask_b32_e64 v71, v238, v66, s[14:15]
	v_cmp_lt_i32_e64 s[14:15], 31, v70
	v_cndmask_b32_e32 v71, v66, v71, vcc
	v_add_f32_e32 v66, v176, v68
	v_cndmask_b32_e64 v70, v238, v67, s[14:15]
	v_cndmask_b32_e32 v67, v67, v70, vcc
	v_add_u32_e32 v70, 1, v177
	v_add_f32_e32 v66, v80, v66
	v_add_f32_e32 v68, v176, v72
	v_cmp_lt_i32_e64 s[14:15], -1, v70
	v_add_f32_e32 v68, v96, v68
	v_exp_f32_e32 v82, v134
	v_cndmask_b32_e64 v72, v238, v66, s[14:15]
	v_cmp_lt_i32_e64 s[14:15], 31, v70
	v_cndmask_b32_e32 v79, v66, v72, vcc
	v_add_f32_e32 v66, v176, v69
	v_cndmask_b32_e64 v70, v238, v68, s[14:15]
	v_cndmask_b32_e32 v80, v68, v70, vcc
	v_add_f32_e32 v66, v81, v66
	v_add_f32_e32 v68, v176, v73
	v_cmp_lt_i32_e64 s[14:15], -1, v177
	v_add_f32_e32 v68, v97, v68
	v_exp_f32_e32 v84, v138
	v_cndmask_b32_e64 v69, v238, v66, s[14:15]
	v_cmp_lt_i32_e64 s[14:15], 31, v177
	v_cndmask_b32_e32 v69, v66, v69, vcc
	v_exp_f32_e32 v88, v140
	v_cndmask_b32_e64 v70, v238, v68, s[14:15]
	v_cndmask_b32_e32 v73, v68, v70, vcc
	v_exp_f32_e32 v90, v142
	v_exp_f32_e32 v94, v144
	v_exp_f32_e32 v134, v145
	v_exp_f32_e32 v136, v75
	v_exp_f32_e32 v138, v76
	v_exp_f32_e32 v70, v146
	v_exp_f32_e32 v140, v77
	v_exp_f32_e32 v142, v147
	v_exp_f32_e32 v144, v71
	v_exp_f32_e32 v146, v79
	v_exp_f32_e32 v148, v69
	ds_read_b64_tr_b16 v[240:241], v0 offset:39232
	ds_read_b64_tr_b16 v[242:243], v0 offset:40384
	s_waitcnt lgkmcnt(4)
	v_mfma_f32_32x32x16_bf16 v[2:17], v[244:247], v[178:181], v[2:17]
	v_cvt_pk_bf16_f32 v178, v134, v136
	v_cvt_pk_bf16_f32 v179, v138, v140
	v_cvt_pk_bf16_f32 v180, v142, v144
	v_cvt_pk_bf16_f32 v181, v146, v148
	v_exp_f32_e32 v86, v139
	v_exp_f32_e32 v92, v87
	ds_read_b64_tr_b16 v[244:245], v0 offset:41472
	ds_read_b64_tr_b16 v[246:247], v0 offset:42624
	s_waitcnt lgkmcnt(4)
	v_mfma_f32_32x32x16_bf16 v[18:33], v[248:251], v[178:181], v[18:33]
	v_exp_f32_e32 v96, v89
	v_exp_f32_e32 v66, v74
	v_exp_f32_e32 v68, v91
	v_exp_f32_e32 v72, v93
	v_exp_f32_e32 v74, v78
	v_exp_f32_e32 v76, v67
	ds_read_b64_tr_b16 v[248:249], v0 offset:41536
	ds_read_b64_tr_b16 v[250:251], v0 offset:42688
	s_waitcnt lgkmcnt(4)
	v_mfma_f32_32x32x16_bf16 v[2:17], v[240:243], v[178:181], v[2:17]
	v_cvt_pk_bf16_f32 v178, v82, v84
	v_cvt_pk_bf16_f32 v179, v86, v88
	v_cvt_pk_bf16_f32 v180, v90, v92
	v_cvt_pk_bf16_f32 v181, v94, v96
	v_exp_f32_e32 v78, v80
	v_exp_f32_e32 v80, v73
	ds_read_b64_tr_b16 v[240:241], v0 offset:43776
	ds_read_b64_tr_b16 v[242:243], v0 offset:44928
	s_waitcnt lgkmcnt(4)
	v_mfma_f32_32x32x16_bf16 v[18:33], v[244:247], v[178:181], v[18:33]
	v_add_u32_e32 v67, 0xfffffe04, v133
	v_add_u32_e32 v69, 0xfffffe84, v133
	v_cmp_gt_i32_e32 vcc, s45, v175
	ds_read_b64_tr_b16 v[244:245], v0 offset:43840
	ds_read_b64_tr_b16 v[246:247], v0 offset:44992
	s_waitcnt lgkmcnt(4)
; #define LAS __attribute__((address_space(3)))
; #define MFMA32(a, b, c) __builtin_amdgcn_mfma_f32_32x32x16_bf16((a), (b), (c), 0, 0, 0)
; template <int KIND>
; __device__ __forceinline__ void softmax_tile(f32x16& s0, f32x16& s1, float& l, int t, int k0, int h, int qlo, const LAS float* lut, const LAS float* cb, int W, int dmask, float rowshift) {
;     ...
;         const bool diag = (k0 + 63 > qlo);
; #pragma unroll
;         for (int c = 0; c < 4; ++c) {
;             const f32x4 b0 = *(const LAS f32x4*)(cb + k0 + 8 * c + 4 * h), b1 = *(const LAS f32x4*)(cb + k0 + 32 + 8 * c + 4 * h);
; #pragma unroll
;             for (int jj = 0; jj < 4; ++jj) {
;                 const int i = 4 * c + jj; const int n0 = t - (k0 + 8 * c + 4 * h + jj), n1 = n0 - 32;
;                 float x0 = s0[i] + (b0[jj] + rowshift), x1 = s1[i] + (b1[jj] + rowshift);
;                 if (diag) { x0 = (n0 >= 0) ? x0 : NINF; x1 = (n1 >= 0) ? x1 : NINF; }
;                 s0[i] = x0; s1[i] = x1;
;             }
;         }
; __device__ __forceinline__ void pv_tile(LAS unsigned char* vt, const f32x16& s0, const f32x16& s1, int h, int lane, f32x16 (&o)[2]) {
; #pragma unroll
;     for (int st = 0; st < 2; ++st) {
;         const bf16x8 pb = pack8(s0, st);
; #pragma unroll
;         for (int db = 0; db < 2; ++db) o[db] = MFMA32(vfrag<64>(vt, 32 * db, 16 * st + 4 * h, lane), pb, o[db]);
;     }
; #pragma unroll
;     for (int st = 0; st < 2; ++st) {
;         const bf16x8 pb = pack8(s1, st);
; #pragma unroll
;         for (int db = 0; db < 2; ++db) o[db] = MFMA32(vfrag<64>(vt, 32 * db, 32 + 16 * st + 4 * h, lane), pb, o[db]);
;     }
; }
	v_mfma_f32_32x32x16_bf16 v[2:17], v[248:251], v[178:181], v[2:17]
	v_cvt_pk_bf16_f32 v178, v66, v68
	v_cvt_pk_bf16_f32 v179, v70, v72
	v_cvt_pk_bf16_f32 v180, v74, v76
	v_cvt_pk_bf16_f32 v181, v78, v80
	s_nop 0
	s_waitcnt lgkmcnt(2)
	v_mfma_f32_32x32x16_bf16 v[18:33], v[240:243], v[178:181], v[18:33]
	s_waitcnt lgkmcnt(0)
	v_mfma_f32_32x32x16_bf16 v[2:17], v[244:247], v[178:181], v[2:17]
	ds_read_b128 v[178:181], v67
	ds_read_b128 v[182:185], v69
	s_waitcnt lgkmcnt(1)
	v_add_f32_e32 v67, v176, v178
	v_add_f32_e32 v50, v50, v67
	s_waitcnt lgkmcnt(0)
	v_add_f32_e32 v67, v176, v182
	v_add_f32_e32 v34, v34, v67
	v_add_u32_e32 v67, 0x5b, v177
	v_cmp_lt_i32_e64 s[14:15], -1, v67
	s_nop 1
	v_cndmask_b32_e64 v69, v238, v50, s[14:15]
	v_cmp_lt_i32_e64 s[14:15], 31, v67
	v_cndmask_b32_e32 v69, v50, v69, vcc
	v_add_f32_e32 v50, v176, v183
	v_cndmask_b32_e64 v67, v238, v34, s[14:15]
	v_cndmask_b32_e32 v67, v34, v67, vcc
	v_add_f32_e32 v34, v176, v179
	v_add_f32_e32 v35, v35, v50
	v_add_u32_e32 v50, 0x5a, v177
	v_add_f32_e32 v34, v51, v34
	v_cmp_lt_i32_e64 s[14:15], -1, v50
	v_exp_f32_e32 v151, v69
	v_exp_f32_e32 v83, v67
	v_cndmask_b32_e64 v51, v238, v34, s[14:15]
	v_cmp_lt_i32_e64 s[14:15], 31, v50
	v_cndmask_b32_e32 v71, v34, v51, vcc
	v_add_f32_e32 v34, v176, v180
	v_cndmask_b32_e64 v50, v238, v35, s[14:15]
	v_cndmask_b32_e32 v73, v35, v50, vcc
	v_add_f32_e32 v35, v176, v184
	v_add_f32_e32 v35, v36, v35
	v_add_u32_e32 v36, 0x59, v177
	v_add_f32_e32 v34, v52, v34
	v_cmp_lt_i32_e64 s[14:15], -1, v36
	v_exp_f32_e32 v153, v71
	v_exp_f32_e32 v85, v73
	v_cndmask_b32_e64 v50, v238, v34, s[14:15]
	v_cmp_lt_i32_e64 s[14:15], 31, v36
	v_cndmask_b32_e32 v75, v34, v50, vcc
	v_add_f32_e32 v34, v176, v181
	v_cndmask_b32_e64 v36, v238, v35, s[14:15]
	v_cndmask_b32_e32 v77, v35, v36, vcc
	v_add_u32_e32 v36, 0x58, v177
	v_add_f32_e32 v34, v53, v34
	v_add_f32_e32 v35, v176, v185
	v_cmp_lt_i32_e64 s[14:15], -1, v36
	v_add_f32_e32 v35, v37, v35
	v_add_u32_e32 v50, 0xfffffea4, v133
	v_cndmask_b32_e64 v37, v238, v34, s[14:15]
	v_cmp_lt_i32_e64 s[14:15], 31, v36
	v_cndmask_b32_e32 v79, v34, v37, vcc
	v_add_u32_e32 v34, 0xfffffe24, v133
	v_cndmask_b32_e64 v36, v238, v35, s[14:15]
	v_cndmask_b32_e32 v81, v35, v36, vcc
	ds_read_b128 v[34:37], v34
	ds_read_b128 v[50:53], v50
	v_exp_f32_e32 v155, v75
	v_exp_f32_e32 v87, v77
	v_exp_f32_e32 v159, v79
	s_waitcnt lgkmcnt(1)
	v_add_f32_e32 v34, v176, v34
	s_waitcnt lgkmcnt(0)
	v_add_f32_e32 v50, v176, v50
	v_add_f32_e32 v38, v38, v50
	v_add_u32_e32 v50, 0x53, v177
	v_add_f32_e32 v34, v54, v34
	v_cmp_lt_i32_e64 s[14:15], -1, v50
	v_exp_f32_e32 v89, v81
	s_nop 0
	v_cndmask_b32_e64 v54, v238, v34, s[14:15]
	v_cmp_lt_i32_e64 s[14:15], 31, v50
	v_cndmask_b32_e32 v54, v34, v54, vcc
	v_add_f32_e32 v34, v176, v35
	v_cndmask_b32_e64 v50, v238, v38, s[14:15]
	v_cndmask_b32_e32 v50, v38, v50, vcc
	v_add_u32_e32 v38, 0x52, v177
	v_add_f32_e32 v34, v55, v34
	v_add_f32_e32 v35, v176, v51
	v_cmp_lt_i32_e64 s[14:15], -1, v38
	v_add_f32_e32 v35, v39, v35
	v_exp_f32_e32 v161, v54
	v_cndmask_b32_e64 v39, v238, v34, s[14:15]
	v_cmp_lt_i32_e64 s[14:15], 31, v38
	v_cndmask_b32_e32 v51, v34, v39, vcc
	v_add_f32_e32 v34, v176, v36
	v_cndmask_b32_e64 v38, v238, v35, s[14:15]
	v_add_u32_e32 v36, 0x51, v177
	v_cndmask_b32_e32 v55, v35, v38, vcc
	v_add_f32_e32 v34, v56, v34
	v_add_f32_e32 v35, v176, v52
	v_cmp_lt_i32_e64 s[14:15], -1, v36
	v_add_f32_e32 v35, v40, v35
	v_exp_f32_e32 v91, v50
	v_cndmask_b32_e64 v38, v238, v34, s[14:15]
	v_cmp_lt_i32_e64 s[14:15], 31, v36
	v_cndmask_b32_e32 v52, v34, v38, vcc
	v_add_f32_e32 v34, v176, v37
	v_cndmask_b32_e64 v36, v238, v35, s[14:15]
	v_cndmask_b32_e32 v56, v35, v36, vcc
	v_add_u32_e32 v36, 0x50, v177
	v_add_f32_e32 v34, v57, v34
	v_add_f32_e32 v35, v176, v53
	v_cmp_lt_i32_e64 s[14:15], -1, v36
	v_add_f32_e32 v35, v41, v35
	v_add_u32_e32 v38, 0xfffffec4, v133
	v_cndmask_b32_e64 v37, v238, v34, s[14:15]
	v_cmp_lt_i32_e64 s[14:15], 31, v36
	v_cndmask_b32_e32 v53, v34, v37, vcc
	v_add_u32_e32 v34, 0xfffffe44, v133
	v_cndmask_b32_e64 v36, v238, v35, s[14:15]
	v_cndmask_b32_e32 v57, v35, v36, vcc
	ds_read_b128 v[34:37], v34
	ds_read_b128 v[38:41], v38
	v_exp_f32_e32 v163, v51
	v_exp_f32_e32 v93, v55
	v_exp_f32_e32 v165, v52
	s_waitcnt lgkmcnt(1)
	v_add_f32_e32 v34, v176, v34
	s_waitcnt lgkmcnt(0)
	v_add_f32_e32 v38, v176, v38
	v_add_f32_e32 v38, v42, v38
	v_add_u32_e32 v42, 0x4b, v177
	v_add_f32_e32 v34, v58, v34
	v_cmp_lt_i32_e64 s[14:15], -1, v42
	v_exp_f32_e32 v95, v56
	v_exp_f32_e32 v167, v53
	v_cndmask_b32_e64 v58, v238, v34, s[14:15]
	v_cmp_lt_i32_e64 s[14:15], 31, v42
	v_cndmask_b32_e32 v58, v34, v58, vcc
	v_add_f32_e32 v34, v176, v35
	v_cndmask_b32_e64 v42, v238, v38, s[14:15]
	v_cndmask_b32_e32 v42, v38, v42, vcc
	v_add_u32_e32 v38, 0x4a, v177
	v_add_f32_e32 v34, v59, v34
	v_add_f32_e32 v35, v176, v39
	v_cmp_lt_i32_e64 s[14:15], -1, v38
	v_add_f32_e32 v35, v43, v35
	v_exp_f32_e32 v97, v57
	v_cndmask_b32_e64 v39, v238, v34, s[14:15]
	v_cmp_lt_i32_e64 s[14:15], 31, v38
	v_cndmask_b32_e32 v43, v34, v39, vcc
	v_add_f32_e32 v34, v176, v36
	v_cndmask_b32_e64 v38, v238, v35, s[14:15]
	v_add_u32_e32 v36, 0x49, v177
	v_cndmask_b32_e32 v59, v35, v38, vcc
	v_add_f32_e32 v34, v60, v34
	v_add_f32_e32 v35, v176, v40
	v_cmp_lt_i32_e64 s[14:15], -1, v36
	v_add_f32_e32 v35, v44, v35
	v_exp_f32_e32 v135, v58
	v_cndmask_b32_e64 v38, v238, v34, s[14:15]
	v_cmp_lt_i32_e64 s[14:15], 31, v36
	v_cndmask_b32_e32 v44, v34, v38, vcc
	v_add_f32_e32 v34, v176, v37
	v_cndmask_b32_e64 v36, v238, v35, s[14:15]
	v_cndmask_b32_e32 v60, v35, v36, vcc
	v_add_u32_e32 v36, 0x48, v177
	v_add_f32_e32 v34, v61, v34
	v_add_f32_e32 v35, v176, v41
	v_cmp_lt_i32_e64 s[14:15], -1, v36
	v_add_f32_e32 v35, v45, v35
	v_add_u32_e32 v38, 0xfffffee4, v133
	v_cndmask_b32_e64 v37, v238, v34, s[14:15]
	v_cmp_lt_i32_e64 s[14:15], 31, v36
	v_cndmask_b32_e32 v45, v34, v37, vcc
	v_add_u32_e32 v34, 0xfffffe64, v133
	v_cndmask_b32_e64 v36, v238, v35, s[14:15]
	v_cndmask_b32_e32 v61, v35, v36, vcc
	ds_read_b128 v[34:37], v34
	ds_read_b128 v[38:41], v38
	v_exp_f32_e32 v67, v42
	v_exp_f32_e32 v137, v43
	v_exp_f32_e32 v69, v59
	s_waitcnt lgkmcnt(1)
; #define LAS __attribute__((address_space(3)))
; #define MFMA32(a, b, c) __builtin_amdgcn_mfma_f32_32x32x16_bf16((a), (b), (c), 0, 0, 0)
; __device__ __forceinline__ float fexp2(float x) { return __builtin_amdgcn_exp2f(x); }
; template <int KIND>
; __device__ __forceinline__ void softmax_tile(f32x16& s0, f32x16& s1, float& l, int t, int k0, int h, int qlo, const LAS float* lut, const LAS float* cb, int W, int dmask, float rowshift) {
;     ...
;     float ps = 0.f;
; #pragma unroll
;     for (int i = 0; i < 16; ++i) { s0[i] = fexp2(s0[i]); s1[i] = fexp2(s1[i]); ps += s0[i] + s1[i]; }
;     l += ps;
; }
; __device__ __forceinline__ void pv_tile(LAS unsigned char* vt, const f32x16& s0, const f32x16& s1, int h, int lane, f32x16 (&o)[2]) {
; #pragma unroll
;     for (int st = 0; st < 2; ++st) {
;         const bf16x8 pb = pack8(s0, st);
; #pragma unroll
;         for (int db = 0; db < 2; ++db) o[db] = MFMA32(vfrag<64>(vt, 32 * db, 16 * st + 4 * h, lane), pb, o[db]);
;     }
; #pragma unroll
;     for (int st = 0; st < 2; ++st) {
;         const bf16x8 pb = pack8(s1, st);
; #pragma unroll
;         for (int db = 0; db < 2; ++db) o[db] = MFMA32(vfrag<64>(vt, 32 * db, 32 + 16 * st + 4 * h, lane), pb, o[db]);
;     }
; }
	v_add_f32_e32 v34, v176, v34
	s_waitcnt lgkmcnt(0)
	v_add_f32_e32 v38, v176, v38
	v_add_f32_e32 v38, v46, v38
	v_add_u32_e32 v46, 0x43, v177
	v_add_f32_e32 v34, v62, v34
	v_cmp_lt_i32_e64 s[14:15], -1, v46
	v_exp_f32_e32 v139, v44
	v_exp_f32_e32 v71, v60
	v_cndmask_b32_e64 v62, v238, v34, s[14:15]
	v_cmp_lt_i32_e64 s[14:15], 31, v46
	v_cndmask_b32_e32 v62, v34, v62, vcc
	v_add_f32_e32 v34, v176, v35
	v_add_f32_e32 v35, v176, v39
	v_add_u32_e32 v39, 0x42, v177
	v_cndmask_b32_e64 v46, v238, v38, s[14:15]
	v_add_f32_e32 v34, v63, v34
	v_cmp_lt_i32_e64 s[14:15], -1, v39
	v_cndmask_b32_e32 v38, v38, v46, vcc
	v_add_f32_e32 v35, v47, v35
	v_cndmask_b32_e64 v46, v238, v34, s[14:15]
	v_cmp_lt_i32_e64 s[14:15], 31, v39
	v_cndmask_b32_e32 v46, v34, v46, vcc
	v_add_f32_e32 v34, v176, v36
	v_cndmask_b32_e64 v39, v238, v35, s[14:15]
	v_add_u32_e32 v36, 0x41, v177
	v_cndmask_b32_e32 v39, v35, v39, vcc
	v_add_f32_e32 v34, v64, v34
	v_add_f32_e32 v35, v176, v40
	v_cmp_lt_i32_e64 s[14:15], -1, v36
	v_add_f32_e32 v35, v48, v35
	v_exp_f32_e32 v141, v45
	v_cndmask_b32_e64 v40, v238, v34, s[14:15]
	v_cmp_lt_i32_e64 s[14:15], 31, v36
	v_cndmask_b32_e32 v40, v34, v40, vcc
	v_add_f32_e32 v34, v176, v37
	v_cndmask_b32_e64 v36, v238, v35, s[14:15]
	v_cndmask_b32_e32 v47, v35, v36, vcc
	v_add_u32_e32 v36, 64, v177
	v_add_f32_e32 v34, v65, v34
	v_add_f32_e32 v35, v176, v41
	v_cmp_lt_i32_e64 s[14:15], -1, v36
	v_add_f32_e32 v35, v49, v35
	v_exp_f32_e32 v73, v61
	v_cndmask_b32_e64 v37, v238, v34, s[14:15]
	v_cmp_lt_i32_e64 s[14:15], 31, v36
	v_cndmask_b32_e32 v41, v34, v37, vcc
	v_exp_f32_e32 v143, v62
	v_cndmask_b32_e64 v36, v238, v35, s[14:15]
	v_cndmask_b32_e32 v48, v35, v36, vcc
	v_pk_add_f32 v[34:35], v[150:151], v[82:83]
	v_pk_add_f32 v[36:37], v[152:153], v[84:85]
	v_pk_add_f32 v[34:35], v[34:35], 0 op_sel_hi:[1,0]
	v_exp_f32_e32 v75, v38
	v_pk_add_f32 v[34:35], v[36:37], v[34:35]
	v_pk_add_f32 v[36:37], v[154:155], v[86:87]
	v_exp_f32_e32 v145, v46
	v_pk_add_f32 v[34:35], v[36:37], v[34:35]
	v_pk_add_f32 v[36:37], v[158:159], v[88:89]
	v_exp_f32_e32 v77, v39
	v_pk_add_f32 v[34:35], v[36:37], v[34:35]
	v_pk_add_f32 v[36:37], v[160:161], v[90:91]
	v_exp_f32_e32 v147, v40
	v_pk_add_f32 v[34:35], v[36:37], v[34:35]
	v_pk_add_f32 v[36:37], v[162:163], v[92:93]
	v_exp_f32_e32 v79, v47
	v_pk_add_f32 v[34:35], v[36:37], v[34:35]
	v_pk_add_f32 v[36:37], v[164:165], v[94:95]
	v_exp_f32_e32 v149, v41
	v_pk_add_f32 v[34:35], v[36:37], v[34:35]
	v_pk_add_f32 v[36:37], v[166:167], v[96:97]
	v_exp_f32_e32 v81, v48
	v_pk_add_f32 v[34:35], v[36:37], v[34:35]
	v_pk_add_f32 v[36:37], v[134:135], v[66:67]
	ds_read_b64_tr_b16 v[42:43], v0 offset:46080
	ds_read_b64_tr_b16 v[44:45], v0 offset:47232
	ds_read_b64_tr_b16 v[46:47], v0 offset:46144
	ds_read_b64_tr_b16 v[48:49], v0 offset:47296
	ds_read_b64_tr_b16 v[50:51], v0 offset:48384
	ds_read_b64_tr_b16 v[52:53], v0 offset:49536
	v_pk_add_f32 v[34:35], v[36:37], v[34:35]
	v_pk_add_f32 v[36:37], v[136:137], v[68:69]
	s_nop 0
	v_pk_add_f32 v[34:35], v[36:37], v[34:35]
	v_pk_add_f32 v[36:37], v[138:139], v[70:71]
	s_nop 0
	v_pk_add_f32 v[34:35], v[36:37], v[34:35]
	v_pk_add_f32 v[36:37], v[140:141], v[72:73]
	s_nop 0
	v_pk_add_f32 v[34:35], v[36:37], v[34:35]
	v_pk_add_f32 v[36:37], v[142:143], v[74:75]
	s_nop 0
	v_pk_add_f32 v[34:35], v[36:37], v[34:35]
	v_pk_add_f32 v[36:37], v[144:145], v[76:77]
	s_nop 0
	v_pk_add_f32 v[34:35], v[36:37], v[34:35]
	v_pk_add_f32 v[36:37], v[146:147], v[78:79]
	s_nop 0
	v_pk_add_f32 v[34:35], v[36:37], v[34:35]
	v_pk_add_f32 v[36:37], v[148:149], v[80:81]
	s_nop 0
	v_pk_add_f32 v[34:35], v[36:37], v[34:35]
	v_cvt_pk_bf16_f32 v36, v161, v163
	v_add_f32_e32 v34, v172, v34
	v_add_f32_e32 v172, v34, v35
	v_cvt_pk_bf16_f32 v34, v151, v153
	v_cvt_pk_bf16_f32 v35, v155, v159
	v_cvt_pk_bf16_f32 v37, v165, v167
	s_waitcnt lgkmcnt(4)
	s_nop 0
	ds_read_b64_tr_b16 v[54:55], v0 offset:48448
	ds_read_b64_tr_b16 v[56:57], v0 offset:49600
	s_waitcnt lgkmcnt(6)
	v_mfma_f32_32x32x16_bf16 v[18:33], v[42:45], v[34:37], v[18:33]
	ds_read_b64_tr_b16 v[42:43], v0 offset:50688
	ds_read_b64_tr_b16 v[44:45], v0 offset:51840
	s_waitcnt lgkmcnt(6)
	v_mfma_f32_32x32x16_bf16 v[2:17], v[46:49], v[34:37], v[2:17]
	v_cvt_pk_bf16_f32 v34, v135, v137
	v_cvt_pk_bf16_f32 v35, v139, v141
	v_cvt_pk_bf16_f32 v36, v143, v145
	v_cvt_pk_bf16_f32 v37, v147, v149
	s_nop 0
	ds_read_b64_tr_b16 v[46:47], v0 offset:50752
	ds_read_b64_tr_b16 v[48:49], v0 offset:51904
	s_waitcnt lgkmcnt(6)
	v_mfma_f32_32x32x16_bf16 v[18:33], v[50:53], v[34:37], v[18:33]
	ds_read_b64_tr_b16 v[50:51], v0 offset:52992
	ds_read_b64_tr_b16 v[52:53], v0 offset:54144
	s_waitcnt lgkmcnt(6)
	v_mfma_f32_32x32x16_bf16 v[2:17], v[54:57], v[34:37], v[2:17]
	v_cvt_pk_bf16_f32 v34, v83, v85
	v_cvt_pk_bf16_f32 v35, v87, v89
	v_cvt_pk_bf16_f32 v36, v91, v93
	v_cvt_pk_bf16_f32 v37, v95, v97
	s_nop 0
	ds_read_b64_tr_b16 v[54:55], v0 offset:53056
	ds_read_b64_tr_b16 v[56:57], v0 offset:54208
	s_waitcnt lgkmcnt(6)
	v_mfma_f32_32x32x16_bf16 v[18:33], v[42:45], v[34:37], v[18:33]
	s_waitcnt lgkmcnt(4)
	v_mfma_f32_32x32x16_bf16 v[2:17], v[46:49], v[34:37], v[2:17]
	v_cvt_pk_bf16_f32 v34, v67, v69
	v_cvt_pk_bf16_f32 v35, v71, v73
	v_cvt_pk_bf16_f32 v36, v75, v77
	v_cvt_pk_bf16_f32 v37, v79, v81
	s_nop 0
	s_waitcnt lgkmcnt(2)
	v_mfma_f32_32x32x16_bf16 v[18:33], v[50:53], v[34:37], v[18:33]
	s_waitcnt lgkmcnt(0)
	v_mfma_f32_32x32x16_bf16 v[2:17], v[54:57], v[34:37], v[2:17]

; #define LAS __attribute__((address_space(3)))
; #define MFMA32(a, b, c) __builtin_amdgcn_mfma_f32_32x32x16_bf16((a), (b), (c), 0, 0, 0)
; __device__ __forceinline__ float fexp2(float x) { return __builtin_amdgcn_exp2f(x); }
; __device__ __forceinline__ float flog2(float x) { return __builtin_amdgcn_logf(x); }
; __device__ __forceinline__ void stick_block(f32x16& s, float& Rr, int t, int kbase, int h, bool diag) {
;     float u[16], gs[4], pg[4];
; #pragma unroll
;     for (int i = 0; i < 16; ++i) {
;         const float z = s[i];
;         const float sp = fmaxf(z, 0.f) + flog2(1.0f + fexp2(-fabsf(z)));
;         const int j = kbase + (i & 3) + 8 * (i >> 2) + 4 * h;
;         const bool valid = !diag || (j < t);
;         u[i] = valid ? -sp : 0.f;
;         s[i] = valid ? (z - sp) : -__builtin_inff();
;     }
; __device__ __forceinline__ void qk_tile(LAS unsigned char* ks, const bf16x8 (&qf)[4], int r, int h, f32x16& s0, f32x16& s1) {
;     bf16x8 kf[8];
; #pragma unroll
;     for (int kk = 0; kk < 4; ++kk) {
;         kf[2 * kk]     = *(const LAS bf16x8*)(ks + (r * KPITCH + 16 * kk + 8 * h) * 2);
;         kf[2 * kk + 1] = *(const LAS bf16x8*)(ks + ((32 + r) * KPITCH + 16 * kk + 8 * h) * 2);
;     }
; #pragma unroll
;     for (int i = 0; i < 16; ++i) { s0[i] = 0.f; s1[i] = 0.f; }
; #pragma unroll
;     for (int kk = 0; kk < 4; ++kk) { s0 = MFMA32(kf[2 * kk], qf[kk], s0); s1 = MFMA32(kf[2 * kk + 1], qf[kk], s1); }
; }
.LBB0_617:
	s_sub_i32 s44, s36, 63
	s_add_i32 s3, s36, 0xffffff81
	s_cmp_lg_u32 s30, 0
	s_cselect_b64 s[8:9], -1, 0
	v_cmp_le_i32_e64 s[14:15], s3, v139
	v_cmp_le_i32_e32 vcc, s44, v139
	s_and_b64 s[8:9], s[8:9], s[14:15]
	s_xor_b64 s[58:59], s[18:19], -1
	s_and_b64 s[18:19], vcc, s[58:59]
	s_and_b64 s[14:15], s[8:9], s[58:59]
	s_mul_i32 s3, s37, 0x2400
	s_and_b64 s[8:9], s[18:19], s[14:15]
	s_add_i32 s45, s3, 0
	s_xor_b64 s[8:9], s[8:9], -1
	s_and_saveexec_b64 s[60:61], s[8:9]
	s_xor_b64 s[60:61], exec, s[60:61]
	s_cbranch_execz .LBB0_627
	s_xor_b64 s[8:9], s[18:19], -1
	s_and_saveexec_b64 s[18:19], s[8:9]
	s_xor_b64 s[18:19], exec, s[18:19]
	s_cbranch_execz .LBB0_622
	s_and_saveexec_b64 s[62:63], s[14:15]
	s_cbranch_execz .LBB0_621
	v_add3_u32 v38, s45, v204, v205
	ds_read_b128 v[50:53], v38 offset:13824
	ds_read_b128 v[34:37], v38 offset:9216
	ds_read_b128 v[66:69], v38 offset:9248
	ds_read_b128 v[70:73], v38 offset:13856
	ds_read_b128 v[74:77], v38 offset:9280
	ds_read_b128 v[78:81], v38 offset:13888
	ds_read_b128 v[82:85], v38 offset:9312
	ds_read_b128 v[86:89], v38 offset:13920
	s_waitcnt lgkmcnt(7)
	v_mfma_f32_32x32x16_bf16 v[50:65], v[50:53], v[98:101], 0
	v_cmp_gt_i32_e32 vcc, s44, v137
	s_waitcnt lgkmcnt(4)
	v_mfma_f32_32x32x16_bf16 v[50:65], v[70:73], v[102:105], v[50:65]
	s_waitcnt lgkmcnt(2)
	v_mfma_f32_32x32x16_bf16 v[50:65], v[78:81], v[106:109], v[50:65]
	v_mfma_f32_32x32x16_bf16 v[34:49], v[34:37], v[98:101], 0
	s_waitcnt lgkmcnt(0)
	v_mfma_f32_32x32x16_bf16 v[50:65], v[86:89], v[110:113], v[50:65]
	v_mfma_f32_32x32x16_bf16 v[34:49], v[66:69], v[102:105], v[34:49]
	s_nop 10
	v_exp_f32_e64 v69, -|v50|
	v_add_u32_e32 v67, s36, v198
	v_add_u32_e32 v66, 0xffffffa1, v67
	v_max_f32_e32 v68, v50, v50
	v_add_f32_e32 v69, 1.0, v69
	v_log_f32_e32 v69, v69
	v_max_f32_e32 v68, 0, v68
	v_cmp_ge_i32_e64 s[14:15], v66, v138
	s_and_b64 s[14:15], vcc, s[14:15]
	v_add_f32_e32 v68, v68, v69
	v_mfma_f32_32x32x16_bf16 v[34:49], v[74:77], v[106:109], v[34:49]
	v_cndmask_b32_e64 v74, -v68, 0, s[14:15]
	v_sub_f32_e32 v50, v50, v68
	v_exp_f32_e64 v68, -|v51|
	v_cndmask_b32_e64 v66, v50, v238, s[14:15]
	v_max_f32_e32 v50, v51, v51
	v_max_f32_e32 v50, 0, v50
	v_add_f32_e32 v68, 1.0, v68
	v_log_f32_e32 v68, v68
	v_mfma_f32_32x32x16_bf16 v[34:49], v[82:85], v[110:113], v[34:49]
	v_add_u32_e32 v81, 0xffffff81, v67
	v_add_f32_e32 v50, v50, v68
	v_add_u32_e32 v68, 0xffffffa2, v67
	v_cmp_ge_i32_e64 s[14:15], v68, v138
	s_and_b64 s[14:15], vcc, s[14:15]
	s_nop 0
	v_cndmask_b32_e64 v68, -v50, 0, s[14:15]
	v_sub_f32_e32 v50, v51, v50
	v_exp_f32_e64 v51, -|v52|
	v_cndmask_b32_e64 v69, v50, v238, s[14:15]
	v_max_f32_e32 v50, v52, v52
	v_max_f32_e32 v50, 0, v50
	v_add_f32_e32 v51, 1.0, v51
	v_log_f32_e32 v51, v51
	s_nop 0
	v_add_f32_e32 v50, v50, v51
	v_add_u32_e32 v51, 0xffffffa3, v67
	v_cmp_ge_i32_e64 s[14:15], v51, v138
	v_exp_f32_e64 v51, -|v53|
	s_and_b64 s[14:15], vcc, s[14:15]
	v_cndmask_b32_e64 v70, -v50, 0, s[14:15]
	v_sub_f32_e32 v50, v52, v50
	v_add_f32_e32 v51, 1.0, v51
	v_log_f32_e32 v51, v51
	v_cndmask_b32_e64 v71, v50, v238, s[14:15]
	v_max_f32_e32 v50, v53, v53
	v_max_f32_e32 v50, 0, v50
	v_add_f32_e32 v50, v50, v51
	v_add_u32_e32 v51, 0xffffffa4, v67
	v_cmp_ge_i32_e64 s[14:15], v51, v138
	v_exp_f32_e64 v51, -|v54|
	v_exp_f32_e64 v52, -|v55|
	s_and_b64 s[14:15], vcc, s[14:15]
	v_cndmask_b32_e64 v72, -v50, 0, s[14:15]
	v_add_f32_e32 v51, 1.0, v51
	v_log_f32_e32 v51, v51
	v_sub_f32_e32 v50, v53, v50
	v_cndmask_b32_e64 v73, v50, v238, s[14:15]
	v_max_f32_e32 v50, v54, v54
	v_add_f32_e32 v52, 1.0, v52
	v_max_f32_e32 v50, 0, v50
	v_log_f32_e32 v52, v52
	v_add_f32_e32 v50, v50, v51
	v_add_u32_e32 v51, 0xffffffa9, v67
	v_exp_f32_e64 v53, -|v56|
	v_cmp_ge_i32_e64 s[14:15], v51, v138
	v_max_f32_e32 v51, v55, v55
	s_and_b64 s[14:15], vcc, s[14:15]
	v_max_f32_e32 v51, 0, v51
	v_cndmask_b32_e64 v75, -v50, 0, s[14:15]
	v_sub_f32_e32 v50, v54, v50
	v_add_f32_e32 v51, v51, v52
	v_add_u32_e32 v52, 0xffffffaa, v67
	v_cndmask_b32_e64 v50, v50, v238, s[14:15]
	v_cmp_ge_i32_e64 s[14:15], v52, v138
	v_add_f32_e32 v53, 1.0, v53
	s_and_b64 s[14:15], vcc, s[14:15]
	v_log_f32_e32 v53, v53
	v_cndmask_b32_e64 v52, -v51, 0, s[14:15]
	v_sub_f32_e32 v51, v55, v51
	v_cndmask_b32_e64 v79, v51, v238, s[14:15]
	v_max_f32_e32 v51, v56, v56
	v_max_f32_e32 v51, 0, v51
	v_add_f32_e32 v51, v51, v53
	v_add_u32_e32 v53, 0xffffffab, v67
	v_cmp_ge_i32_e64 s[14:15], v53, v138
	v_exp_f32_e64 v53, -|v57|
	s_and_b64 s[14:15], vcc, s[14:15]
	v_cndmask_b32_e64 v80, -v51, 0, s[14:15]
	v_sub_f32_e32 v51, v56, v51
	v_add_f32_e32 v53, 1.0, v53
	v_log_f32_e32 v53, v53
	v_cndmask_b32_e64 v78, v51, v238, s[14:15]
	v_max_f32_e32 v51, v57, v57
	v_max_f32_e32 v51, 0, v51
	v_add_f32_e32 v51, v51, v53
	v_add_u32_e32 v53, 0xffffffac, v67
	v_cmp_ge_i32_e64 s[14:15], v53, v138
	v_exp_f32_e64 v53, -|v58|
	s_and_b64 s[14:15], vcc, s[14:15]
	v_cndmask_b32_e64 v83, -v51, 0, s[14:15]
	v_sub_f32_e32 v51, v57, v51
	v_add_f32_e32 v53, 1.0, v53
	v_log_f32_e32 v53, v53
	v_cndmask_b32_e64 v84, v51, v238, s[14:15]
	v_max_f32_e32 v51, v58, v58
	v_max_f32_e32 v51, 0, v51
	v_add_f32_e32 v51, v51, v53
	v_add_u32_e32 v53, 0xffffffb1, v67
	v_cmp_ge_i32_e64 s[14:15], v53, v138
	v_exp_f32_e64 v53, -|v59|
	s_and_b64 s[14:15], vcc, s[14:15]
	v_cndmask_b32_e64 v54, -v51, 0, s[14:15]
	v_sub_f32_e32 v51, v58, v51
	v_add_f32_e32 v53, 1.0, v53
	v_log_f32_e32 v53, v53
	v_cndmask_b32_e64 v58, v51, v238, s[14:15]
	v_max_f32_e32 v51, v59, v59
	v_max_f32_e32 v51, 0, v51
	v_add_f32_e32 v51, v51, v53
	v_add_u32_e32 v53, 0xffffffb2, v67
	v_cmp_ge_i32_e64 s[14:15], v53, v138
	v_exp_f32_e64 v53, -|v60|
	s_and_b64 s[14:15], vcc, s[14:15]
; __device__ __forceinline__ float fexp2(float x) { return __builtin_amdgcn_exp2f(x); }
; __device__ __forceinline__ float flog2(float x) { return __builtin_amdgcn_logf(x); }
; __device__ __forceinline__ void stick_block(f32x16& s, float& Rr, int t, int kbase, int h, bool diag) {
;     float u[16], gs[4], pg[4];
; #pragma unroll
;     for (int i = 0; i < 16; ++i) {
;         const float z = s[i];
;         const float sp = fmaxf(z, 0.f) + flog2(1.0f + fexp2(-fabsf(z)));
;         const int j = kbase + (i & 3) + 8 * (i >> 2) + 4 * h;
;         const bool valid = !diag || (j < t);
;         u[i] = valid ? -sp : 0.f;
;         s[i] = valid ? (z - sp) : -__builtin_inff();
;     }
; #pragma unroll
;     for (int c = 0; c < 4; ++c) { gs[c] = (u[4 * c] + u[4 * c + 1]) + (u[4 * c + 2] + u[4 * c + 3]); pg[c] = __shfl_xor(gs[c], 32); }
;     float run = Rr;
; #pragma unroll
;     for (int c = 3; c >= 0; --c) {
;         float tl = run + ((h == 0) ? pg[c] : 0.f);
; #pragma unroll
;     ...
;         run += gs[c] + pg[c];
;     }
;     Rr = run;
; }
	v_cndmask_b32_e64 v56, -v51, 0, s[14:15]
	v_sub_f32_e32 v51, v59, v51
	v_add_f32_e32 v53, 1.0, v53
	v_log_f32_e32 v53, v53
	v_cndmask_b32_e64 v59, v51, v238, s[14:15]
	v_max_f32_e32 v51, v60, v60
	v_max_f32_e32 v51, 0, v51
	v_add_f32_e32 v51, v51, v53
	v_add_u32_e32 v53, 0xffffffb3, v67
	v_cmp_ge_i32_e64 s[14:15], v53, v138
	v_exp_f32_e64 v53, -|v61|
	s_and_b64 s[14:15], vcc, s[14:15]
	v_cndmask_b32_e64 v76, -v51, 0, s[14:15]
	v_sub_f32_e32 v51, v60, v51
	v_add_f32_e32 v53, 1.0, v53
	v_log_f32_e32 v53, v53
	v_cndmask_b32_e64 v77, v51, v238, s[14:15]
	v_max_f32_e32 v51, v61, v61
	v_max_f32_e32 v51, 0, v51
	v_add_f32_e32 v51, v51, v53
	v_add_u32_e32 v53, 0xffffffb4, v67
	v_cmp_ge_i32_e64 s[14:15], v53, v138
	v_exp_f32_e64 v53, -|v62|
	s_and_b64 s[14:15], vcc, s[14:15]
	v_cndmask_b32_e64 v85, -v51, 0, s[14:15]
	v_sub_f32_e32 v51, v61, v51
	v_add_f32_e32 v53, 1.0, v53
	v_log_f32_e32 v53, v53
	v_cndmask_b32_e64 v86, v51, v238, s[14:15]
	v_max_f32_e32 v51, v62, v62
	v_max_f32_e32 v51, 0, v51
	v_add_f32_e32 v51, v51, v53
	v_add_u32_e32 v53, 0xffffffb9, v67
	v_cmp_ge_i32_e64 s[14:15], v53, v138
	v_exp_f32_e64 v53, -|v63|
	s_and_b64 s[14:15], vcc, s[14:15]
	v_cndmask_b32_e64 v55, -v51, 0, s[14:15]
	v_sub_f32_e32 v51, v62, v51
	v_add_f32_e32 v53, 1.0, v53
	v_log_f32_e32 v53, v53
	v_cndmask_b32_e64 v87, v51, v238, s[14:15]
	v_max_f32_e32 v51, v63, v63
	v_max_f32_e32 v51, 0, v51
	v_add_f32_e32 v51, v51, v53
	v_add_u32_e32 v53, 0xffffffba, v67
	v_cmp_ge_i32_e64 s[14:15], v53, v138
	v_exp_f32_e64 v53, -|v64|
	s_and_b64 s[14:15], vcc, s[14:15]
	v_cndmask_b32_e64 v88, -v51, 0, s[14:15]
	v_sub_f32_e32 v51, v63, v51
	v_add_f32_e32 v53, 1.0, v53
	v_log_f32_e32 v53, v53
	v_cndmask_b32_e64 v89, v51, v238, s[14:15]
	v_max_f32_e32 v51, v64, v64
	v_max_f32_e32 v51, 0, v51
	v_add_f32_e32 v51, v51, v53
	v_add_u32_e32 v53, 0xffffffbb, v67
	v_cmp_ge_i32_e64 s[14:15], v53, v138
	v_exp_f32_e64 v53, -|v65|
	s_and_b64 s[14:15], vcc, s[14:15]
	v_cndmask_b32_e64 v90, -v51, 0, s[14:15]
	v_sub_f32_e32 v51, v64, v51
	v_add_f32_e32 v53, 1.0, v53
	v_log_f32_e32 v53, v53
	v_cndmask_b32_e64 v63, v51, v238, s[14:15]
	v_max_f32_e32 v51, v65, v65
	v_max_f32_e32 v51, 0, v51
	v_add_f32_e32 v51, v51, v53
	v_add_u32_e32 v53, 0xffffffbc, v67
	v_cmp_ge_i32_e64 s[14:15], v53, v138
	s_and_b64 s[14:15], vcc, s[14:15]
	v_and_b32_e32 v53, 64, v236
	v_cndmask_b32_e64 v64, -v51, 0, s[14:15]
	v_sub_f32_e32 v51, v65, v51
	v_cndmask_b32_e64 v62, v51, v238, s[14:15]
	v_xor_b32_e32 v51, 32, v236
	v_add_u32_e32 v53, 64, v53
	v_cmp_lt_i32_e64 s[14:15], v51, v53
	v_add_f32_e32 v57, v75, v52
	v_add_f32_e32 v60, v80, v83
	v_cndmask_b32_e64 v51, v236, v51, s[14:15]
	v_add_f32_e32 v91, v57, v60
	v_add_f32_e32 v55, v55, v88
	v_add_f32_e32 v57, v90, v64
	v_lshlrev_b32_e32 v82, 2, v51
	v_pk_add_f32 v[54:55], v[54:55], v[56:57]
	ds_bpermute_b32 v61, v82, v55
	v_add_f32_e32 v60, v76, v85
	ds_bpermute_b32 v92, v82, v91
	v_add_f32_e32 v51, v74, v68
	v_cmp_ge_i32_e64 s[14:15], v81, v138
	s_waitcnt lgkmcnt(1)
	v_pk_add_f32 v[54:55], v[54:55], v[60:61]
	v_cndmask_b32_e64 v57, 0, v61, s[12:13]
	ds_bpermute_b32 v132, v82, v54
	v_add_f32_e32 v57, v133, v57
	v_add_f32_e32 v60, v62, v57
	v_add_f32_e32 v57, v64, v57
	v_exp_f32_e32 v62, v60
	v_add_f32_e32 v60, v63, v57
	v_add_f32_e32 v57, v90, v57
	v_exp_f32_e32 v63, v60
	v_add_f32_e32 v60, v89, v57
	v_add_f32_e32 v57, v88, v57
	v_add_f32_e32 v57, v87, v57
	v_exp_f32_e32 v65, v57
	s_waitcnt lgkmcnt(0)
	v_cndmask_b32_e64 v57, 0, v132, s[12:13]
	v_pk_add_f32 v[54:55], v[54:55], v[132:133]
	v_exp_f32_e32 v64, v60
	v_add_f32_e32 v57, v57, v55
	v_add_f32_e32 v60, v86, v57
	v_add_f32_e32 v57, v85, v57
	v_exp_f32_e32 v74, v60
	v_add_f32_e32 v60, v77, v57
	v_add_f32_e32 v57, v76, v57
	v_add_f32_e32 v59, v59, v57
	v_add_f32_e32 v56, v56, v57
	v_exp_f32_e32 v76, v59
	v_add_f32_e32 v56, v58, v56
	v_pk_add_f32 v[58:59], v[54:55], v[54:55] op_sel:[0,1] op_sel_hi:[1,0]
	v_cndmask_b32_e64 v54, 0, v92, s[12:13]
	v_add_f32_e32 v54, v54, v58
	v_add_f32_e32 v55, v84, v54
	v_add_f32_e32 v54, v83, v54
	v_exp_f32_e32 v59, v55
	v_add_f32_e32 v55, v78, v54
	v_add_f32_e32 v54, v80, v54
	v_add_f32_e32 v52, v52, v54
	v_add_f32_e32 v50, v50, v52
	v_exp_f32_e64 v52, -|v34|
	v_exp_f32_e32 v80, v50
	v_max_f32_e32 v50, v34, v34
	v_max_f32_e32 v50, 0, v50
	v_add_f32_e32 v52, 1.0, v52
	v_log_f32_e32 v52, v52
	s_and_b64 s[14:15], vcc, s[14:15]
	v_exp_f32_e32 v77, v56
	v_exp_f32_e32 v75, v60
	v_add_f32_e32 v50, v50, v52
	v_cndmask_b32_e64 v56, -v50, 0, s[14:15]
	v_sub_f32_e32 v34, v34, v50
	v_exp_f32_e64 v50, -|v35|
	v_cndmask_b32_e64 v81, v34, v238, s[14:15]
	v_max_f32_e32 v34, v35, v35
	v_max_f32_e32 v34, 0, v34
	v_add_f32_e32 v50, 1.0, v50
	v_log_f32_e32 v50, v50
	v_exp_f32_e32 v78, v55
	v_add_f32_e32 v55, v79, v54
	v_exp_f32_e32 v79, v55
	v_add_f32_e32 v50, v34, v50
	v_add_u32_e32 v34, 0xffffff82, v67
	v_cmp_ge_i32_e64 s[14:15], v34, v138
	s_and_b64 s[14:15], vcc, s[14:15]
	v_sub_f32_e32 v35, v35, v50
	v_cndmask_b32_e64 v34, -v50, 0, s[14:15]
	v_exp_f32_e64 v50, -|v36|
	v_cndmask_b32_e64 v83, v35, v238, s[14:15]
	v_max_f32_e32 v35, v36, v36
	v_max_f32_e32 v35, 0, v35
	v_add_f32_e32 v50, 1.0, v50
	v_log_f32_e32 v50, v50
	v_add_f32_e32 v55, v91, v92
	v_add_f32_e32 v53, v70, v72
	v_add_f32_e32 v53, v51, v53
	v_add_f32_e32 v35, v35, v50
	v_add_u32_e32 v50, 0xffffff83, v67
	v_cmp_ge_i32_e64 s[14:15], v50, v138
	s_and_b64 s[14:15], vcc, s[14:15]
	v_exp_f32_e64 v50, -|v39|
	v_cndmask_b32_e64 v60, -v35, 0, s[14:15]
	v_sub_f32_e32 v35, v36, v35
	v_exp_f32_e64 v36, -|v37|
	v_cndmask_b32_e64 v84, v35, v238, s[14:15]
	v_max_f32_e32 v35, v37, v37
	v_max_f32_e32 v35, 0, v35
	v_add_f32_e32 v36, 1.0, v36
	v_log_f32_e32 v36, v36
	v_add_f32_e32 v50, 1.0, v50
	v_log_f32_e32 v50, v50
	ds_bpermute_b32 v51, v82, v53
	v_add_f32_e32 v35, v35, v36
	v_add_u32_e32 v36, 0xffffff84, v67
	v_cmp_ge_i32_e64 s[14:15], v36, v138
	s_and_b64 s[14:15], vcc, s[14:15]
	s_waitcnt lgkmcnt(0)
; __device__ __forceinline__ float fexp2(float x) { return __builtin_amdgcn_exp2f(x); }
; __device__ __forceinline__ float flog2(float x) { return __builtin_amdgcn_logf(x); }
; __device__ __forceinline__ void stick_block(f32x16& s, float& Rr, int t, int kbase, int h, bool diag) {
;     float u[16], gs[4], pg[4];
; #pragma unroll
;     for (int i = 0; i < 16; ++i) {
;         const float z = s[i];
;         const float sp = fmaxf(z, 0.f) + flog2(1.0f + fexp2(-fabsf(z)));
;         const int j = kbase + (i & 3) + 8 * (i >> 2) + 4 * h;
;         const bool valid = !diag || (j < t);
;         u[i] = valid ? -sp : 0.f;
;         s[i] = valid ? (z - sp) : -__builtin_inff();
;     }
; #pragma unroll
;     for (int c = 0; c < 4; ++c) { gs[c] = (u[4 * c] + u[4 * c + 1]) + (u[4 * c + 2] + u[4 * c + 3]); pg[c] = __shfl_xor(gs[c], 32); }
;     float run = Rr;
; #pragma unroll
;     for (int c = 3; c >= 0; --c) {
;         float tl = run + ((h == 0) ? pg[c] : 0.f);
; #pragma unroll
;     ...
;         run += gs[c] + pg[c];
;     }
;     Rr = run;
; }
	v_cndmask_b32_e64 v61, 0, v51, s[12:13]
	v_cndmask_b32_e64 v36, -v35, 0, s[14:15]
	v_sub_f32_e32 v35, v37, v35
	v_exp_f32_e64 v37, -|v38|
	v_cndmask_b32_e64 v85, v35, v238, s[14:15]
	v_max_f32_e32 v35, v38, v38
	v_max_f32_e32 v35, 0, v35
	v_add_f32_e32 v37, 1.0, v37
	v_log_f32_e32 v37, v37
	s_nop 0
	v_add_f32_e32 v37, v35, v37
	v_add_u32_e32 v35, 0xffffff89, v67
	v_cmp_ge_i32_e64 s[14:15], v35, v138
	s_and_b64 s[14:15], vcc, s[14:15]
	s_nop 0
	v_cndmask_b32_e64 v35, -v37, 0, s[14:15]
	v_sub_f32_e32 v37, v38, v37
	v_cndmask_b32_e64 v38, v37, v238, s[14:15]
	v_max_f32_e32 v37, v39, v39
	v_max_f32_e32 v37, 0, v37
	v_add_f32_e32 v37, v37, v50
	v_add_u32_e32 v50, 0xffffff8a, v67
	v_cmp_ge_i32_e64 s[14:15], v50, v138
	v_exp_f32_e64 v50, -|v40|
	s_and_b64 s[14:15], vcc, s[14:15]
	v_cndmask_b32_e64 v86, -v37, 0, s[14:15]
	v_sub_f32_e32 v37, v39, v37
	v_add_f32_e32 v50, 1.0, v50
	v_log_f32_e32 v50, v50
	v_cndmask_b32_e64 v39, v37, v238, s[14:15]
	v_max_f32_e32 v37, v40, v40
	v_max_f32_e32 v37, 0, v37
	v_add_f32_e32 v37, v37, v50
	v_add_u32_e32 v50, 0xffffff8b, v67
	v_cmp_ge_i32_e64 s[14:15], v50, v138
	v_exp_f32_e64 v50, -|v41|
	s_and_b64 s[14:15], vcc, s[14:15]
	v_cndmask_b32_e64 v87, -v37, 0, s[14:15]
	v_sub_f32_e32 v37, v40, v37
	v_add_f32_e32 v50, 1.0, v50
	v_log_f32_e32 v50, v50
	v_cndmask_b32_e64 v40, v37, v238, s[14:15]
	v_max_f32_e32 v37, v41, v41
	v_max_f32_e32 v37, 0, v37
	v_add_f32_e32 v37, v37, v50
	v_add_u32_e32 v50, 0xffffff8c, v67
	v_cmp_ge_i32_e64 s[14:15], v50, v138
	v_exp_f32_e64 v50, -|v42|
	s_and_b64 s[14:15], vcc, s[14:15]
	v_cndmask_b32_e64 v88, -v37, 0, s[14:15]
	v_sub_f32_e32 v37, v41, v37
	v_add_f32_e32 v50, 1.0, v50
	v_log_f32_e32 v50, v50
	v_cndmask_b32_e64 v41, v37, v238, s[14:15]
	v_max_f32_e32 v37, v42, v42
	v_max_f32_e32 v37, 0, v37
	v_add_f32_e32 v37, v37, v50
	v_add_u32_e32 v50, 0xffffff91, v67
	v_cmp_ge_i32_e64 s[14:15], v50, v138
	v_exp_f32_e64 v50, -|v43|
	s_and_b64 s[14:15], vcc, s[14:15]
	v_cndmask_b32_e64 v89, -v37, 0, s[14:15]
	v_sub_f32_e32 v37, v42, v37
	v_add_f32_e32 v50, 1.0, v50
	v_log_f32_e32 v50, v50
	v_cndmask_b32_e64 v42, v37, v238, s[14:15]
	v_max_f32_e32 v37, v43, v43
	v_max_f32_e32 v37, 0, v37
	v_add_f32_e32 v37, v37, v50
	v_add_u32_e32 v50, 0xffffff92, v67
	v_cmp_ge_i32_e64 s[14:15], v50, v138
	v_exp_f32_e64 v50, -|v44|
	s_and_b64 s[14:15], vcc, s[14:15]
	v_cndmask_b32_e64 v90, -v37, 0, s[14:15]
	v_sub_f32_e32 v37, v43, v37
	v_add_f32_e32 v50, 1.0, v50
	v_log_f32_e32 v50, v50
	v_cndmask_b32_e64 v43, v37, v238, s[14:15]
	v_max_f32_e32 v37, v44, v44
	v_max_f32_e32 v37, 0, v37
	v_add_f32_e32 v37, v37, v50
	v_add_u32_e32 v50, 0xffffff93, v67
	v_cmp_ge_i32_e64 s[14:15], v50, v138
	s_and_b64 s[14:15], vcc, s[14:15]
	v_add_f32_e32 v35, v35, v86
	v_cndmask_b32_e64 v91, -v37, 0, s[14:15]
	v_sub_f32_e32 v37, v44, v37
	v_exp_f32_e64 v44, -|v45|
	v_cndmask_b32_e64 v92, v37, v238, s[14:15]
	v_max_f32_e32 v37, v45, v45
	v_max_f32_e32 v37, 0, v37
	v_add_f32_e32 v44, 1.0, v44
	v_log_f32_e32 v44, v44
	s_nop 0
	v_add_f32_e32 v37, v37, v44
	v_add_u32_e32 v44, 0xffffff94, v67
	v_cmp_ge_i32_e64 s[14:15], v44, v138
	v_exp_f32_e64 v44, -|v46|
	s_and_b64 s[14:15], vcc, s[14:15]
	v_cndmask_b32_e64 v93, -v37, 0, s[14:15]
	v_sub_f32_e32 v37, v45, v37
	v_exp_f32_e64 v45, -|v47|
	v_add_f32_e32 v44, 1.0, v44
	v_log_f32_e32 v44, v44
	v_cndmask_b32_e64 v94, v37, v238, s[14:15]
	v_max_f32_e32 v37, v46, v46
	v_add_f32_e32 v45, 1.0, v45
	v_max_f32_e32 v37, 0, v37
	v_log_f32_e32 v45, v45
	v_add_f32_e32 v37, v37, v44
	v_add_u32_e32 v44, 0xffffff99, v67
	v_cmp_ge_i32_e64 s[14:15], v44, v138
	v_max_f32_e32 v44, v47, v47
	s_and_b64 s[14:15], vcc, s[14:15]
	v_max_f32_e32 v44, 0, v44
	v_cndmask_b32_e64 v52, -v37, 0, s[14:15]
	v_sub_f32_e32 v37, v46, v37
	v_add_f32_e32 v44, v44, v45
	v_add_u32_e32 v45, 0xffffff9a, v67
	v_cndmask_b32_e64 v37, v37, v238, s[14:15]
	v_cmp_ge_i32_e64 s[14:15], v45, v138
	v_exp_f32_e64 v45, -|v48|
	s_and_b64 s[14:15], vcc, s[14:15]
	v_cndmask_b32_e64 v50, -v44, 0, s[14:15]
	v_sub_f32_e32 v44, v47, v44
	v_add_f32_e32 v45, 1.0, v45
	v_log_f32_e32 v45, v45
	v_cndmask_b32_e64 v95, v44, v238, s[14:15]
	v_max_f32_e32 v44, v48, v48
	v_max_f32_e32 v44, 0, v44
	v_add_f32_e32 v44, v44, v45
	v_add_u32_e32 v45, 0xffffff9b, v67
	v_cmp_ge_i32_e64 s[14:15], v45, v138
	v_exp_f32_e64 v45, -|v49|
	s_and_b64 s[14:15], vcc, s[14:15]
	v_cndmask_b32_e64 v54, -v44, 0, s[14:15]
	v_sub_f32_e32 v44, v48, v44
	v_add_f32_e32 v45, 1.0, v45
	v_log_f32_e32 v45, v45
	v_cndmask_b32_e64 v96, v44, v238, s[14:15]
	v_max_f32_e32 v44, v49, v49
	v_max_f32_e32 v44, 0, v44
	v_add_f32_e32 v45, v44, v45
	v_add_u32_e32 v44, 0xffffff9c, v67
	v_cmp_ge_i32_e64 s[14:15], v44, v138
	s_and_b64 vcc, vcc, s[14:15]
	v_cndmask_b32_e64 v44, -v45, 0, vcc
	v_sub_f32_e32 v45, v49, v45
	v_cndmask_b32_e32 v67, v45, v238, vcc
	v_add_f32_e32 v45, v87, v88
	v_add_f32_e32 v57, v35, v45
	v_add_f32_e32 v45, v89, v90
	v_add_f32_e32 v46, v91, v93
	v_add_f32_e32 v89, v45, v46
	v_mov_b32_e32 v45, v58
	v_pk_add_f32 v[46:47], v[54:55], v[44:45]
	ds_bpermute_b32 v97, v82, v89
	v_add_f32_e32 v45, v61, v47
	v_add_f32_e32 v48, v73, v45
	v_add_f32_e32 v45, v72, v45
	v_exp_f32_e32 v55, v48
	v_add_f32_e32 v48, v71, v45
	v_add_f32_e32 v45, v70, v45
	v_exp_f32_e32 v58, v48
	v_add_f32_e32 v48, v69, v45
	v_exp_f32_e32 v69, v48
	v_add_f32_e32 v45, v68, v45
	v_pk_add_f32 v[48:49], v[52:53], v[50:51]
	v_add_f32_e32 v45, v66, v45
	v_pk_add_f32 v[46:47], v[48:49], v[46:47]
	v_exp_f32_e32 v66, v45
	ds_bpermute_b32 v45, v82, v46
	ds_bpermute_b32 v35, v82, v57
	s_waitcnt lgkmcnt(2)
; #define LAS __attribute__((address_space(3)))
; #define MFMA32(a, b, c) __builtin_amdgcn_mfma_f32_32x32x16_bf16((a), (b), (c), 0, 0, 0)
; __device__ __forceinline__ void stick_block(f32x16& s, float& Rr, int t, int kbase, int h, bool diag) {
;     ...
; #pragma unroll
;     for (int c = 0; c < 4; ++c) { gs[c] = (u[4 * c] + u[4 * c + 1]) + (u[4 * c + 2] + u[4 * c + 3]); pg[c] = __shfl_xor(gs[c], 32); }
;     float run = Rr;
; #pragma unroll
;     for (int c = 3; c >= 0; --c) {
;         float tl = run + ((h == 0) ? pg[c] : 0.f);
; #pragma unroll
;     ...
;         run += gs[c] + pg[c];
;     }
;     Rr = run;
; }
; __device__ __forceinline__ void pv_tile(LAS unsigned char* vt, const f32x16& s0, const f32x16& s1, int h, int lane, f32x16 (&o)[2]) {
; #pragma unroll
;     for (int st = 0; st < 2; ++st) {
;         const bf16x8 pb = pack8(s0, st);
; #pragma unroll
;         for (int db = 0; db < 2; ++db) o[db] = MFMA32(vfrag<64>(vt, 32 * db, 16 * st + 4 * h, lane), pb, o[db]);
;     }
; #pragma unroll
;     for (int st = 0; st < 2; ++st) {
;         const bf16x8 pb = pack8(s1, st);
; #pragma unroll
;         for (int db = 0; db < 2; ++db) o[db] = MFMA32(vfrag<64>(vt, 32 * db, 32 + 16 * st + 4 * h, lane), pb, o[db]);
;     }
; }
	v_add_f32_e32 v61, v89, v97
	s_waitcnt lgkmcnt(1)
	v_cndmask_b32_e64 v48, 0, v45, s[12:13]
	v_add_f32_e32 v48, v48, v47
	v_add_f32_e32 v44, v44, v48
	v_add_f32_e32 v49, v67, v48
	v_add_f32_e32 v48, v96, v44
	v_add_f32_e32 v44, v54, v44
	v_add_f32_e32 v51, v95, v44
	v_add_f32_e32 v44, v50, v44
	v_add_f32_e32 v37, v37, v44
	v_exp_f32_e32 v50, v37
	v_add_f32_e32 v37, v46, v45
	v_add_f32_e32 v37, v37, v47
	v_cndmask_b32_e64 v44, 0, v97, s[12:13]
	v_add_f32_e32 v44, v44, v37
	v_add_f32_e32 v45, v94, v44
	v_add_f32_e32 v44, v93, v44
	v_exp_f32_e32 v46, v45
	v_add_f32_e32 v45, v92, v44
	v_add_f32_e32 v44, v91, v44
	v_add_f32_e32 v43, v43, v44
	v_exp_f32_e32 v52, v43
	v_add_f32_e32 v43, v90, v44
	v_add_f32_e32 v42, v42, v43
	v_exp_f32_e32 v47, v45
	v_exp_f32_e32 v53, v42
	v_pk_add_f32 v[42:43], v[60:61], v[36:37]
	s_waitcnt lgkmcnt(0)
	v_pk_add_f32 v[44:45], v[56:57], v[34:35]
	v_cndmask_b32_e64 v54, 0, v35, s[12:13]
	v_pk_add_f32 v[44:45], v[44:45], v[42:43]
	ds_bpermute_b32 v35, v82, v44
	v_add_f32_e32 v37, v54, v43
	v_add_f32_e32 v41, v41, v37
	v_add_f32_e32 v37, v88, v37
	v_add_f32_e32 v40, v40, v37
	v_add_f32_e32 v37, v87, v37
	v_add_f32_e32 v39, v39, v37
	v_add_f32_e32 v37, v86, v37
	v_add_f32_e32 v37, v38, v37
	s_waitcnt lgkmcnt(0)
	v_cndmask_b32_e64 v38, 0, v35, s[12:13]
	v_add_f32_e32 v38, v38, v45
	v_add_f32_e32 v36, v36, v38
	v_add_f32_e32 v42, v85, v38
	v_add_f32_e32 v38, v84, v36
	v_exp_f32_e32 v42, v42
	v_exp_f32_e32 v38, v38
	v_exp_f32_e32 v41, v41
	v_exp_f32_e32 v40, v40
	v_exp_f32_e32 v39, v39
	v_exp_f32_e32 v37, v37
	v_add_f32_e32 v36, v60, v36
	v_add_f32_e32 v34, v34, v36
	v_add_f32_e32 v35, v44, v35
	v_add_f32_e32 v43, v83, v36
	v_add_f32_e32 v34, v81, v34
	v_add_f32_e32 v133, v35, v45
	v_cvt_pk_bf16_f32 v35, v38, v42
	v_add_u32_e32 v42, s45, v200
	v_exp_f32_e32 v43, v43
	v_exp_f32_e32 v34, v34
	v_cvt_pk_bf16_f32 v36, v37, v39
	v_cvt_pk_bf16_f32 v37, v40, v41
	ds_read_b64_tr_b16 v[70:71], v42 offset:46080
	ds_read_b64_tr_b16 v[72:73], v42 offset:47232
	ds_read_b64_tr_b16 v[82:83], v42 offset:46144
	ds_read_b64_tr_b16 v[84:85], v42 offset:47296
	ds_read_b64_tr_b16 v[86:87], v42 offset:48384
	ds_read_b64_tr_b16 v[88:89], v42 offset:49536
	v_cvt_pk_bf16_f32 v34, v34, v43
	v_exp_f32_e32 v49, v49
	v_exp_f32_e32 v48, v48
	s_waitcnt lgkmcnt(4)
	ds_read_b64_tr_b16 v[90:91], v42 offset:48448
	ds_read_b64_tr_b16 v[92:93], v42 offset:49600
	s_waitcnt lgkmcnt(6)
	v_mfma_f32_32x32x16_bf16 v[18:33], v[70:73], v[34:37], v[18:33]
	v_exp_f32_e32 v51, v51
	ds_read_b64_tr_b16 v[70:71], v42 offset:50688
	ds_read_b64_tr_b16 v[72:73], v42 offset:51840
	s_waitcnt lgkmcnt(6)
	v_mfma_f32_32x32x16_bf16 v[2:17], v[82:85], v[34:37], v[2:17]
	v_cvt_pk_bf16_f32 v34, v53, v52
	v_cvt_pk_bf16_f32 v35, v47, v46
	v_cvt_pk_bf16_f32 v36, v50, v51
	v_cvt_pk_bf16_f32 v37, v48, v49
	s_nop 0
	ds_read_b64_tr_b16 v[82:83], v42 offset:50752
	ds_read_b64_tr_b16 v[84:85], v42 offset:51904
	s_waitcnt lgkmcnt(6)
	v_mfma_f32_32x32x16_bf16 v[18:33], v[86:89], v[34:37], v[18:33]
	ds_read_b64_tr_b16 v[86:87], v42 offset:52992
	ds_read_b64_tr_b16 v[88:89], v42 offset:54144
	s_waitcnt lgkmcnt(6)
	v_mfma_f32_32x32x16_bf16 v[2:17], v[90:93], v[34:37], v[2:17]
	v_cvt_pk_bf16_f32 v34, v66, v69
	v_cvt_pk_bf16_f32 v35, v58, v55
	v_cvt_pk_bf16_f32 v36, v80, v79
	v_cvt_pk_bf16_f32 v37, v78, v59
	s_nop 0
	ds_read_b64_tr_b16 v[90:91], v42 offset:53056
	ds_read_b64_tr_b16 v[92:93], v42 offset:54208
	s_waitcnt lgkmcnt(6)
	v_mfma_f32_32x32x16_bf16 v[18:33], v[70:73], v[34:37], v[18:33]
	s_waitcnt lgkmcnt(4)
	v_mfma_f32_32x32x16_bf16 v[2:17], v[82:85], v[34:37], v[2:17]
	v_cvt_pk_bf16_f32 v34, v77, v76
	v_cvt_pk_bf16_f32 v35, v75, v74
	v_cvt_pk_bf16_f32 v36, v65, v64
	v_cvt_pk_bf16_f32 v37, v63, v62
	s_nop 0
	s_waitcnt lgkmcnt(2)
	v_mfma_f32_32x32x16_bf16 v[18:33], v[86:89], v[34:37], v[18:33]
	s_waitcnt lgkmcnt(0)
	v_mfma_f32_32x32x16_bf16 v[2:17], v[90:93], v[34:37], v[2:17]

; #define LAS __attribute__((address_space(3)))
; #define MFMA32(a, b, c) __builtin_amdgcn_mfma_f32_32x32x16_bf16((a), (b), (c), 0, 0, 0)
; __device__ __forceinline__ float fexp2(float x) { return __builtin_amdgcn_exp2f(x); }
; __device__ __forceinline__ float flog2(float x) { return __builtin_amdgcn_logf(x); }
; __device__ __forceinline__ void stick_block(f32x16& s, float& Rr, int t, int kbase, int h, bool diag) {
;     float u[16], gs[4], pg[4];
; #pragma unroll
;     for (int i = 0; i < 16; ++i) {
;         const float z = s[i];
;         const float sp = fmaxf(z, 0.f) + flog2(1.0f + fexp2(-fabsf(z)));
;         const int j = kbase + (i & 3) + 8 * (i >> 2) + 4 * h;
;         const bool valid = !diag || (j < t);
;         u[i] = valid ? -sp : 0.f;
;         s[i] = valid ? (z - sp) : -__builtin_inff();
;     }
; __device__ __forceinline__ void qk_tile(LAS unsigned char* ks, const bf16x8 (&qf)[4], int r, int h, f32x16& s0, f32x16& s1) {
;     bf16x8 kf[8];
; #pragma unroll
;     for (int kk = 0; kk < 4; ++kk) {
;         kf[2 * kk]     = *(const LAS bf16x8*)(ks + (r * KPITCH + 16 * kk + 8 * h) * 2);
;         kf[2 * kk + 1] = *(const LAS bf16x8*)(ks + ((32 + r) * KPITCH + 16 * kk + 8 * h) * 2);
;     }
; #pragma unroll
;     for (int i = 0; i < 16; ++i) { s0[i] = 0.f; s1[i] = 0.f; }
; #pragma unroll
;     for (int kk = 0; kk < 4; ++kk) { s0 = MFMA32(kf[2 * kk], qf[kk], s0); s1 = MFMA32(kf[2 * kk + 1], qf[kk], s1); }
; }
.LBB0_622:
	s_andn2_saveexec_b64 s[18:19], s[18:19]
	s_cbranch_execz .LBB0_624
	v_add3_u32 v38, s45, v204, v205
	ds_read_b128 v[50:53], v38 offset:4608
	ds_read_b128 v[34:37], v38
	ds_read_b128 v[66:69], v38 offset:32
	ds_read_b128 v[70:73], v38 offset:4640
	ds_read_b128 v[74:77], v38 offset:64
	ds_read_b128 v[78:81], v38 offset:4672
	ds_read_b128 v[82:85], v38 offset:96
	ds_read_b128 v[86:89], v38 offset:4704
	s_waitcnt lgkmcnt(7)
	v_mfma_f32_32x32x16_bf16 v[50:65], v[50:53], v[98:101], 0
	v_cmp_ge_i32_e32 vcc, s36, v137
	s_waitcnt lgkmcnt(4)
	v_mfma_f32_32x32x16_bf16 v[50:65], v[70:73], v[102:105], v[50:65]
	s_waitcnt lgkmcnt(2)
	v_mfma_f32_32x32x16_bf16 v[50:65], v[78:81], v[106:109], v[50:65]
	v_mfma_f32_32x32x16_bf16 v[34:49], v[34:37], v[98:101], 0
	s_waitcnt lgkmcnt(0)
	v_mfma_f32_32x32x16_bf16 v[50:65], v[86:89], v[110:113], v[50:65]
	v_mfma_f32_32x32x16_bf16 v[34:49], v[66:69], v[102:105], v[34:49]
	s_nop 10
	v_exp_f32_e64 v69, -|v50|
	v_add_u32_e32 v67, s36, v198
	v_subrev_u32_e32 v66, 31, v67
	v_max_f32_e32 v68, v50, v50
	v_add_f32_e32 v69, 1.0, v69
	v_log_f32_e32 v69, v69
	v_max_f32_e32 v68, 0, v68
	v_cmp_ge_i32_e64 s[14:15], v66, v138
	s_and_b64 s[14:15], vcc, s[14:15]
	v_add_f32_e32 v68, v68, v69
	v_mfma_f32_32x32x16_bf16 v[34:49], v[74:77], v[106:109], v[34:49]
	v_cndmask_b32_e64 v74, -v68, 0, s[14:15]
	v_sub_f32_e32 v50, v50, v68
	v_exp_f32_e64 v68, -|v51|
	v_cndmask_b32_e64 v66, v50, v238, s[14:15]
	v_max_f32_e32 v50, v51, v51
	v_max_f32_e32 v50, 0, v50
	v_add_f32_e32 v68, 1.0, v68
	v_log_f32_e32 v68, v68
	v_mfma_f32_32x32x16_bf16 v[34:49], v[82:85], v[110:113], v[34:49]
	v_subrev_u32_e32 v81, 63, v67
	v_add_f32_e32 v50, v50, v68
	v_subrev_u32_e32 v68, 30, v67
	v_cmp_ge_i32_e64 s[14:15], v68, v138
	s_and_b64 s[14:15], vcc, s[14:15]
	s_nop 0
	v_cndmask_b32_e64 v68, -v50, 0, s[14:15]
	v_sub_f32_e32 v50, v51, v50
	v_exp_f32_e64 v51, -|v52|
	v_cndmask_b32_e64 v69, v50, v238, s[14:15]
	v_max_f32_e32 v50, v52, v52
	v_max_f32_e32 v50, 0, v50
	v_add_f32_e32 v51, 1.0, v51
	v_log_f32_e32 v51, v51
	s_nop 0
	v_add_f32_e32 v50, v50, v51
	v_subrev_u32_e32 v51, 29, v67
	v_cmp_ge_i32_e64 s[14:15], v51, v138
	v_exp_f32_e64 v51, -|v53|
	s_and_b64 s[14:15], vcc, s[14:15]
	v_cndmask_b32_e64 v70, -v50, 0, s[14:15]
	v_sub_f32_e32 v50, v52, v50
	v_add_f32_e32 v51, 1.0, v51
	v_log_f32_e32 v51, v51
	v_cndmask_b32_e64 v71, v50, v238, s[14:15]
	v_max_f32_e32 v50, v53, v53
	v_max_f32_e32 v50, 0, v50
	v_add_f32_e32 v50, v50, v51
	v_subrev_u32_e32 v51, 28, v67
	v_cmp_ge_i32_e64 s[14:15], v51, v138
	v_exp_f32_e64 v51, -|v54|
	v_exp_f32_e64 v52, -|v55|
	s_and_b64 s[14:15], vcc, s[14:15]
	v_cndmask_b32_e64 v72, -v50, 0, s[14:15]
	v_add_f32_e32 v51, 1.0, v51
	v_log_f32_e32 v51, v51
	v_sub_f32_e32 v50, v53, v50
	v_cndmask_b32_e64 v73, v50, v238, s[14:15]
	v_max_f32_e32 v50, v54, v54
	v_add_f32_e32 v52, 1.0, v52
	v_max_f32_e32 v50, 0, v50
	v_log_f32_e32 v52, v52
	v_add_f32_e32 v50, v50, v51
	v_subrev_u32_e32 v51, 23, v67
	v_exp_f32_e64 v53, -|v56|
	v_cmp_ge_i32_e64 s[14:15], v51, v138
	v_max_f32_e32 v51, v55, v55
	s_and_b64 s[14:15], vcc, s[14:15]
	v_max_f32_e32 v51, 0, v51
	v_cndmask_b32_e64 v75, -v50, 0, s[14:15]
	v_sub_f32_e32 v50, v54, v50
	v_add_f32_e32 v51, v51, v52
	v_subrev_u32_e32 v52, 22, v67
	v_cndmask_b32_e64 v50, v50, v238, s[14:15]
	v_cmp_ge_i32_e64 s[14:15], v52, v138
	v_add_f32_e32 v53, 1.0, v53
	s_and_b64 s[14:15], vcc, s[14:15]
	v_log_f32_e32 v53, v53
	v_cndmask_b32_e64 v52, -v51, 0, s[14:15]
	v_sub_f32_e32 v51, v55, v51
	v_cndmask_b32_e64 v79, v51, v238, s[14:15]
	v_max_f32_e32 v51, v56, v56
	v_max_f32_e32 v51, 0, v51
	v_add_f32_e32 v51, v51, v53
	v_subrev_u32_e32 v53, 21, v67
	v_cmp_ge_i32_e64 s[14:15], v53, v138
	v_exp_f32_e64 v53, -|v57|
	s_and_b64 s[14:15], vcc, s[14:15]
	v_cndmask_b32_e64 v80, -v51, 0, s[14:15]
	v_sub_f32_e32 v51, v56, v51
	v_add_f32_e32 v53, 1.0, v53
	v_log_f32_e32 v53, v53
	v_cndmask_b32_e64 v78, v51, v238, s[14:15]
	v_max_f32_e32 v51, v57, v57
	v_max_f32_e32 v51, 0, v51
	v_add_f32_e32 v51, v51, v53
	v_subrev_u32_e32 v53, 20, v67
	v_cmp_ge_i32_e64 s[14:15], v53, v138
	v_exp_f32_e64 v53, -|v58|
	s_and_b64 s[14:15], vcc, s[14:15]
	v_cndmask_b32_e64 v83, -v51, 0, s[14:15]
	v_sub_f32_e32 v51, v57, v51
	v_add_f32_e32 v53, 1.0, v53
	v_log_f32_e32 v53, v53
	v_cndmask_b32_e64 v84, v51, v238, s[14:15]
	v_max_f32_e32 v51, v58, v58
	v_max_f32_e32 v51, 0, v51
	v_add_f32_e32 v51, v51, v53
	v_add_u32_e32 v53, -15, v67
	v_cmp_ge_i32_e64 s[14:15], v53, v138
	v_exp_f32_e64 v53, -|v59|
	s_and_b64 s[14:15], vcc, s[14:15]
	v_cndmask_b32_e64 v54, -v51, 0, s[14:15]
	v_sub_f32_e32 v51, v58, v51
	v_add_f32_e32 v53, 1.0, v53
	v_log_f32_e32 v53, v53
	v_cndmask_b32_e64 v58, v51, v238, s[14:15]
	v_max_f32_e32 v51, v59, v59
	v_max_f32_e32 v51, 0, v51
	v_add_f32_e32 v51, v51, v53
	v_add_u32_e32 v53, -14, v67
	v_cmp_ge_i32_e64 s[14:15], v53, v138
	v_exp_f32_e64 v53, -|v60|
	s_and_b64 s[14:15], vcc, s[14:15]
	v_cndmask_b32_e64 v56, -v51, 0, s[14:15]
	v_sub_f32_e32 v51, v59, v51
	v_add_f32_e32 v53, 1.0, v53
	v_log_f32_e32 v53, v53
	v_cndmask_b32_e64 v59, v51, v238, s[14:15]
	v_max_f32_e32 v51, v60, v60
	v_max_f32_e32 v51, 0, v51
	v_add_f32_e32 v51, v51, v53
	v_add_u32_e32 v53, -13, v67
	v_cmp_ge_i32_e64 s[14:15], v53, v138
	v_exp_f32_e64 v53, -|v61|
	s_and_b64 s[14:15], vcc, s[14:15]
	v_cndmask_b32_e64 v76, -v51, 0, s[14:15]
	v_sub_f32_e32 v51, v60, v51
	v_add_f32_e32 v53, 1.0, v53
	v_log_f32_e32 v53, v53
	v_cndmask_b32_e64 v77, v51, v238, s[14:15]
	v_max_f32_e32 v51, v61, v61
	v_max_f32_e32 v51, 0, v51
	v_add_f32_e32 v51, v51, v53
	v_add_u32_e32 v53, -12, v67
	v_cmp_ge_i32_e64 s[14:15], v53, v138
	v_exp_f32_e64 v53, -|v62|
	s_and_b64 s[14:15], vcc, s[14:15]
; __device__ __forceinline__ float fexp2(float x) { return __builtin_amdgcn_exp2f(x); }
; __device__ __forceinline__ float flog2(float x) { return __builtin_amdgcn_logf(x); }
; __device__ __forceinline__ void stick_block(f32x16& s, float& Rr, int t, int kbase, int h, bool diag) {
;     float u[16], gs[4], pg[4];
; #pragma unroll
;     for (int i = 0; i < 16; ++i) {
;         const float z = s[i];
;         const float sp = fmaxf(z, 0.f) + flog2(1.0f + fexp2(-fabsf(z)));
;         const int j = kbase + (i & 3) + 8 * (i >> 2) + 4 * h;
;         const bool valid = !diag || (j < t);
;         u[i] = valid ? -sp : 0.f;
;         s[i] = valid ? (z - sp) : -__builtin_inff();
;     }
; #pragma unroll
;     for (int c = 0; c < 4; ++c) { gs[c] = (u[4 * c] + u[4 * c + 1]) + (u[4 * c + 2] + u[4 * c + 3]); pg[c] = __shfl_xor(gs[c], 32); }
;     float run = Rr;
; #pragma unroll
;     for (int c = 3; c >= 0; --c) {
;         float tl = run + ((h == 0) ? pg[c] : 0.f);
; #pragma unroll
;     ...
;         run += gs[c] + pg[c];
;     }
;     Rr = run;
; }
	v_cndmask_b32_e64 v85, -v51, 0, s[14:15]
	v_sub_f32_e32 v51, v61, v51
	v_add_f32_e32 v53, 1.0, v53
	v_log_f32_e32 v53, v53
	v_cndmask_b32_e64 v86, v51, v238, s[14:15]
	v_max_f32_e32 v51, v62, v62
	v_max_f32_e32 v51, 0, v51
	v_add_f32_e32 v51, v51, v53
	v_add_u32_e32 v53, -7, v67
	v_cmp_ge_i32_e64 s[14:15], v53, v138
	v_exp_f32_e64 v53, -|v63|
	s_and_b64 s[14:15], vcc, s[14:15]
	v_cndmask_b32_e64 v55, -v51, 0, s[14:15]
	v_sub_f32_e32 v51, v62, v51
	v_add_f32_e32 v53, 1.0, v53
	v_log_f32_e32 v53, v53
	v_cndmask_b32_e64 v87, v51, v238, s[14:15]
	v_max_f32_e32 v51, v63, v63
	v_max_f32_e32 v51, 0, v51
	v_add_f32_e32 v51, v51, v53
	v_add_u32_e32 v53, -6, v67
	v_cmp_ge_i32_e64 s[14:15], v53, v138
	v_exp_f32_e64 v53, -|v64|
	s_and_b64 s[14:15], vcc, s[14:15]
	v_cndmask_b32_e64 v88, -v51, 0, s[14:15]
	v_sub_f32_e32 v51, v63, v51
	v_add_f32_e32 v53, 1.0, v53
	v_log_f32_e32 v53, v53
	v_cndmask_b32_e64 v89, v51, v238, s[14:15]
	v_max_f32_e32 v51, v64, v64
	v_max_f32_e32 v51, 0, v51
	v_add_f32_e32 v51, v51, v53
	v_add_u32_e32 v53, -5, v67
	v_cmp_ge_i32_e64 s[14:15], v53, v138
	v_exp_f32_e64 v53, -|v65|
	s_and_b64 s[14:15], vcc, s[14:15]
	v_cndmask_b32_e64 v90, -v51, 0, s[14:15]
	v_sub_f32_e32 v51, v64, v51
	v_add_f32_e32 v53, 1.0, v53
	v_log_f32_e32 v53, v53
	v_cndmask_b32_e64 v63, v51, v238, s[14:15]
	v_max_f32_e32 v51, v65, v65
	v_max_f32_e32 v51, 0, v51
	v_add_f32_e32 v51, v51, v53
	v_add_u32_e32 v53, -4, v67
	v_cmp_ge_i32_e64 s[14:15], v53, v138
	s_and_b64 s[14:15], vcc, s[14:15]
	v_and_b32_e32 v53, 64, v236
	v_cndmask_b32_e64 v64, -v51, 0, s[14:15]
	v_sub_f32_e32 v51, v65, v51
	v_cndmask_b32_e64 v62, v51, v238, s[14:15]
	v_xor_b32_e32 v51, 32, v236
	v_add_u32_e32 v53, 64, v53
	v_cmp_lt_i32_e64 s[14:15], v51, v53
	v_add_f32_e32 v57, v75, v52
	v_add_f32_e32 v60, v80, v83
	v_cndmask_b32_e64 v51, v236, v51, s[14:15]
	v_add_f32_e32 v91, v57, v60
	v_add_f32_e32 v55, v55, v88
	v_add_f32_e32 v57, v90, v64
	v_lshlrev_b32_e32 v82, 2, v51
	v_pk_add_f32 v[54:55], v[54:55], v[56:57]
	ds_bpermute_b32 v61, v82, v55
	v_add_f32_e32 v60, v76, v85
	ds_bpermute_b32 v92, v82, v91
	v_add_f32_e32 v51, v74, v68
	v_cmp_ge_i32_e64 s[14:15], v81, v138
	s_waitcnt lgkmcnt(1)
	v_pk_add_f32 v[54:55], v[54:55], v[60:61]
	v_cndmask_b32_e64 v57, 0, v61, s[12:13]
	ds_bpermute_b32 v132, v82, v54
	v_add_f32_e32 v57, v133, v57
	v_add_f32_e32 v60, v62, v57
	v_add_f32_e32 v57, v64, v57
	v_exp_f32_e32 v62, v60
	v_add_f32_e32 v60, v63, v57
	v_add_f32_e32 v57, v90, v57
	v_exp_f32_e32 v63, v60
	v_add_f32_e32 v60, v89, v57
	v_add_f32_e32 v57, v88, v57
	v_add_f32_e32 v57, v87, v57
	v_exp_f32_e32 v65, v57
	s_waitcnt lgkmcnt(0)
	v_cndmask_b32_e64 v57, 0, v132, s[12:13]
	v_pk_add_f32 v[54:55], v[54:55], v[132:133]
	v_exp_f32_e32 v64, v60
	v_add_f32_e32 v57, v57, v55
	v_add_f32_e32 v60, v86, v57
	v_add_f32_e32 v57, v85, v57
	v_exp_f32_e32 v74, v60
	v_add_f32_e32 v60, v77, v57
	v_add_f32_e32 v57, v76, v57
	v_add_f32_e32 v59, v59, v57
	v_add_f32_e32 v56, v56, v57
	v_exp_f32_e32 v76, v59
	v_add_f32_e32 v56, v58, v56
	v_pk_add_f32 v[58:59], v[54:55], v[54:55] op_sel:[0,1] op_sel_hi:[1,0]
	v_cndmask_b32_e64 v54, 0, v92, s[12:13]
	v_add_f32_e32 v54, v54, v58
	v_add_f32_e32 v55, v84, v54
	v_add_f32_e32 v54, v83, v54
	v_exp_f32_e32 v59, v55
	v_add_f32_e32 v55, v78, v54
	v_add_f32_e32 v54, v80, v54
	v_add_f32_e32 v52, v52, v54
	v_add_f32_e32 v50, v50, v52
	v_exp_f32_e64 v52, -|v34|
	v_exp_f32_e32 v80, v50
	v_max_f32_e32 v50, v34, v34
	v_max_f32_e32 v50, 0, v50
	v_add_f32_e32 v52, 1.0, v52
	v_log_f32_e32 v52, v52
	s_and_b64 s[14:15], vcc, s[14:15]
	v_exp_f32_e32 v77, v56
	v_exp_f32_e32 v75, v60
	v_add_f32_e32 v50, v50, v52
	v_cndmask_b32_e64 v56, -v50, 0, s[14:15]
	v_sub_f32_e32 v34, v34, v50
	v_exp_f32_e64 v50, -|v35|
	v_cndmask_b32_e64 v81, v34, v238, s[14:15]
	v_max_f32_e32 v34, v35, v35
	v_max_f32_e32 v34, 0, v34
	v_add_f32_e32 v50, 1.0, v50
	v_log_f32_e32 v50, v50
	v_exp_f32_e32 v78, v55
	v_add_f32_e32 v55, v79, v54
	v_exp_f32_e32 v79, v55
	v_add_f32_e32 v50, v34, v50
	v_subrev_u32_e32 v34, 62, v67
	v_cmp_ge_i32_e64 s[14:15], v34, v138
	s_and_b64 s[14:15], vcc, s[14:15]
	v_sub_f32_e32 v35, v35, v50
	v_cndmask_b32_e64 v34, -v50, 0, s[14:15]
	v_exp_f32_e64 v50, -|v36|
	v_cndmask_b32_e64 v83, v35, v238, s[14:15]
	v_max_f32_e32 v35, v36, v36
	v_max_f32_e32 v35, 0, v35
	v_add_f32_e32 v50, 1.0, v50
	v_log_f32_e32 v50, v50
	v_add_f32_e32 v55, v91, v92
	v_add_f32_e32 v53, v70, v72
	v_add_f32_e32 v53, v51, v53
	v_add_f32_e32 v35, v35, v50
	v_subrev_u32_e32 v50, 61, v67
	v_cmp_ge_i32_e64 s[14:15], v50, v138
	s_and_b64 s[14:15], vcc, s[14:15]
	v_exp_f32_e64 v50, -|v39|
	v_cndmask_b32_e64 v60, -v35, 0, s[14:15]
	v_sub_f32_e32 v35, v36, v35
	v_exp_f32_e64 v36, -|v37|
	v_cndmask_b32_e64 v84, v35, v238, s[14:15]
	v_max_f32_e32 v35, v37, v37
	v_max_f32_e32 v35, 0, v35
	v_add_f32_e32 v36, 1.0, v36
	v_log_f32_e32 v36, v36
	v_add_f32_e32 v50, 1.0, v50
	v_log_f32_e32 v50, v50
	ds_bpermute_b32 v51, v82, v53
	v_add_f32_e32 v35, v35, v36
	v_subrev_u32_e32 v36, 60, v67
	v_cmp_ge_i32_e64 s[14:15], v36, v138
	s_and_b64 s[14:15], vcc, s[14:15]
	s_waitcnt lgkmcnt(0)
; __device__ __forceinline__ float fexp2(float x) { return __builtin_amdgcn_exp2f(x); }
; __device__ __forceinline__ float flog2(float x) { return __builtin_amdgcn_logf(x); }
; __device__ __forceinline__ void stick_block(f32x16& s, float& Rr, int t, int kbase, int h, bool diag) {
;     float u[16], gs[4], pg[4];
; #pragma unroll
;     for (int i = 0; i < 16; ++i) {
;         const float z = s[i];
;         const float sp = fmaxf(z, 0.f) + flog2(1.0f + fexp2(-fabsf(z)));
;         const int j = kbase + (i & 3) + 8 * (i >> 2) + 4 * h;
;         const bool valid = !diag || (j < t);
;         u[i] = valid ? -sp : 0.f;
;         s[i] = valid ? (z - sp) : -__builtin_inff();
;     }
	v_cndmask_b32_e64 v61, 0, v51, s[12:13]
	v_cndmask_b32_e64 v36, -v35, 0, s[14:15]
	v_sub_f32_e32 v35, v37, v35
	v_exp_f32_e64 v37, -|v38|
	v_cndmask_b32_e64 v85, v35, v238, s[14:15]
	v_max_f32_e32 v35, v38, v38
	v_max_f32_e32 v35, 0, v35
	v_add_f32_e32 v37, 1.0, v37
	v_log_f32_e32 v37, v37
	s_nop 0
	v_add_f32_e32 v37, v35, v37
	v_subrev_u32_e32 v35, 55, v67
	v_cmp_ge_i32_e64 s[14:15], v35, v138
	s_and_b64 s[14:15], vcc, s[14:15]
	s_nop 0
	v_cndmask_b32_e64 v35, -v37, 0, s[14:15]
	v_sub_f32_e32 v37, v38, v37
	v_cndmask_b32_e64 v38, v37, v238, s[14:15]
	v_max_f32_e32 v37, v39, v39
	v_max_f32_e32 v37, 0, v37
	v_add_f32_e32 v37, v37, v50
	v_subrev_u32_e32 v50, 54, v67
	v_cmp_ge_i32_e64 s[14:15], v50, v138
	v_exp_f32_e64 v50, -|v40|
	s_and_b64 s[14:15], vcc, s[14:15]
	v_cndmask_b32_e64 v86, -v37, 0, s[14:15]
	v_sub_f32_e32 v37, v39, v37
	v_add_f32_e32 v50, 1.0, v50
	v_log_f32_e32 v50, v50
	v_cndmask_b32_e64 v39, v37, v238, s[14:15]
	v_max_f32_e32 v37, v40, v40
	v_max_f32_e32 v37, 0, v37
	v_add_f32_e32 v37, v37, v50
	v_subrev_u32_e32 v50, 53, v67
	v_cmp_ge_i32_e64 s[14:15], v50, v138
	v_exp_f32_e64 v50, -|v41|
	s_and_b64 s[14:15], vcc, s[14:15]
	v_cndmask_b32_e64 v87, -v37, 0, s[14:15]
	v_sub_f32_e32 v37, v40, v37
	v_add_f32_e32 v50, 1.0, v50
	v_log_f32_e32 v50, v50
	v_cndmask_b32_e64 v40, v37, v238, s[14:15]
	v_max_f32_e32 v37, v41, v41
	v_max_f32_e32 v37, 0, v37
	v_add_f32_e32 v37, v37, v50
	v_subrev_u32_e32 v50, 52, v67
	v_cmp_ge_i32_e64 s[14:15], v50, v138
	v_exp_f32_e64 v50, -|v42|
	s_and_b64 s[14:15], vcc, s[14:15]
	v_cndmask_b32_e64 v88, -v37, 0, s[14:15]
	v_sub_f32_e32 v37, v41, v37
	v_add_f32_e32 v50, 1.0, v50
	v_log_f32_e32 v50, v50
	v_cndmask_b32_e64 v41, v37, v238, s[14:15]
	v_max_f32_e32 v37, v42, v42
	v_max_f32_e32 v37, 0, v37
	v_add_f32_e32 v37, v37, v50
	v_subrev_u32_e32 v50, 47, v67
	v_cmp_ge_i32_e64 s[14:15], v50, v138
	v_exp_f32_e64 v50, -|v43|
	s_and_b64 s[14:15], vcc, s[14:15]
	v_cndmask_b32_e64 v89, -v37, 0, s[14:15]
	v_sub_f32_e32 v37, v42, v37
	v_add_f32_e32 v50, 1.0, v50
	v_log_f32_e32 v50, v50
	v_cndmask_b32_e64 v42, v37, v238, s[14:15]
	v_max_f32_e32 v37, v43, v43
	v_max_f32_e32 v37, 0, v37
	v_add_f32_e32 v37, v37, v50
	v_subrev_u32_e32 v50, 46, v67
	v_cmp_ge_i32_e64 s[14:15], v50, v138
	v_exp_f32_e64 v50, -|v44|
	s_and_b64 s[14:15], vcc, s[14:15]
	v_cndmask_b32_e64 v90, -v37, 0, s[14:15]
	v_sub_f32_e32 v37, v43, v37
	v_add_f32_e32 v50, 1.0, v50
	v_log_f32_e32 v50, v50
	v_cndmask_b32_e64 v43, v37, v238, s[14:15]
	v_max_f32_e32 v37, v44, v44
	v_max_f32_e32 v37, 0, v37
	v_add_f32_e32 v37, v37, v50
	v_subrev_u32_e32 v50, 45, v67
	v_cmp_ge_i32_e64 s[14:15], v50, v138
	s_and_b64 s[14:15], vcc, s[14:15]
	v_add_f32_e32 v35, v35, v86
	v_cndmask_b32_e64 v91, -v37, 0, s[14:15]
	v_sub_f32_e32 v37, v44, v37
	v_exp_f32_e64 v44, -|v45|
	v_cndmask_b32_e64 v92, v37, v238, s[14:15]
	v_max_f32_e32 v37, v45, v45
	v_max_f32_e32 v37, 0, v37
	v_add_f32_e32 v44, 1.0, v44
	v_log_f32_e32 v44, v44
	s_nop 0
	v_add_f32_e32 v37, v37, v44
	v_subrev_u32_e32 v44, 44, v67
	v_cmp_ge_i32_e64 s[14:15], v44, v138
	v_exp_f32_e64 v44, -|v46|
	s_and_b64 s[14:15], vcc, s[14:15]
	v_cndmask_b32_e64 v93, -v37, 0, s[14:15]
	v_sub_f32_e32 v37, v45, v37
	v_exp_f32_e64 v45, -|v47|
	v_add_f32_e32 v44, 1.0, v44
	v_log_f32_e32 v44, v44
	v_cndmask_b32_e64 v94, v37, v238, s[14:15]
	v_max_f32_e32 v37, v46, v46
	v_add_f32_e32 v45, 1.0, v45
	v_max_f32_e32 v37, 0, v37
	v_log_f32_e32 v45, v45
	v_add_f32_e32 v37, v37, v44
	v_subrev_u32_e32 v44, 39, v67
	v_cmp_ge_i32_e64 s[14:15], v44, v138
	v_max_f32_e32 v44, v47, v47
	s_and_b64 s[14:15], vcc, s[14:15]
	v_max_f32_e32 v44, 0, v44
	v_cndmask_b32_e64 v52, -v37, 0, s[14:15]
	v_sub_f32_e32 v37, v46, v37
	v_add_f32_e32 v44, v44, v45
	v_subrev_u32_e32 v45, 38, v67
	v_cndmask_b32_e64 v37, v37, v238, s[14:15]
	v_cmp_ge_i32_e64 s[14:15], v45, v138
	v_exp_f32_e64 v45, -|v48|
	s_and_b64 s[14:15], vcc, s[14:15]
	v_cndmask_b32_e64 v50, -v44, 0, s[14:15]
	v_sub_f32_e32 v44, v47, v44
	v_add_f32_e32 v45, 1.0, v45
	v_log_f32_e32 v45, v45
	v_cndmask_b32_e64 v95, v44, v238, s[14:15]
	v_max_f32_e32 v44, v48, v48
	v_max_f32_e32 v44, 0, v44
	v_add_f32_e32 v44, v44, v45
	v_subrev_u32_e32 v45, 37, v67
	v_cmp_ge_i32_e64 s[14:15], v45, v138
	v_exp_f32_e64 v45, -|v49|
	s_and_b64 s[14:15], vcc, s[14:15]
	v_cndmask_b32_e64 v54, -v44, 0, s[14:15]
	v_sub_f32_e32 v44, v48, v44
	v_add_f32_e32 v45, 1.0, v45
	v_log_f32_e32 v45, v45
	v_cndmask_b32_e64 v96, v44, v238, s[14:15]
	v_max_f32_e32 v44, v49, v49
	v_max_f32_e32 v44, 0, v44
	v_add_f32_e32 v45, v44, v45
	v_subrev_u32_e32 v44, 36, v67
	v_cmp_ge_i32_e64 s[14:15], v44, v138
	s_and_b64 vcc, vcc, s[14:15]
	v_cndmask_b32_e64 v44, -v45, 0, vcc
	v_sub_f32_e32 v45, v49, v45
	v_cndmask_b32_e32 v67, v45, v238, vcc
	v_add_f32_e32 v45, v87, v88
	v_add_f32_e32 v57, v35, v45
	v_add_f32_e32 v45, v89, v90
	v_add_f32_e32 v46, v91, v93
	v_add_f32_e32 v89, v45, v46
	v_mov_b32_e32 v45, v58
	v_pk_add_f32 v[46:47], v[54:55], v[44:45]
	ds_bpermute_b32 v97, v82, v89
	v_add_f32_e32 v45, v61, v47
	v_add_f32_e32 v48, v73, v45
	v_add_f32_e32 v45, v72, v45
	v_exp_f32_e32 v55, v48
	v_add_f32_e32 v48, v71, v45
	v_add_f32_e32 v45, v70, v45
	v_exp_f32_e32 v58, v48
	v_add_f32_e32 v48, v69, v45
	v_exp_f32_e32 v69, v48
	v_add_f32_e32 v45, v68, v45
	v_pk_add_f32 v[48:49], v[52:53], v[50:51]
	v_add_f32_e32 v45, v66, v45
	v_pk_add_f32 v[46:47], v[48:49], v[46:47]
	v_exp_f32_e32 v66, v45
	ds_bpermute_b32 v45, v82, v46
	ds_bpermute_b32 v35, v82, v57
	s_waitcnt lgkmcnt(2)
; #define LAS __attribute__((address_space(3)))
; #define MFMA32(a, b, c) __builtin_amdgcn_mfma_f32_32x32x16_bf16((a), (b), (c), 0, 0, 0)
; __device__ __forceinline__ void stick_block(f32x16& s, float& Rr, int t, int kbase, int h, bool diag) {
;     ...
; #pragma unroll
;     for (int c = 0; c < 4; ++c) { gs[c] = (u[4 * c] + u[4 * c + 1]) + (u[4 * c + 2] + u[4 * c + 3]); pg[c] = __shfl_xor(gs[c], 32); }
;     float run = Rr;
; #pragma unroll
;     for (int c = 3; c >= 0; --c) {
;         float tl = run + ((h == 0) ? pg[c] : 0.f);
; #pragma unroll
;     ...
;         run += gs[c] + pg[c];
;     }
;     Rr = run;
; }
; __device__ __forceinline__ void pv_tile(LAS unsigned char* vt, const f32x16& s0, const f32x16& s1, int h, int lane, f32x16 (&o)[2]) {
; #pragma unroll
;     for (int st = 0; st < 2; ++st) {
;         const bf16x8 pb = pack8(s0, st);
; #pragma unroll
;         for (int db = 0; db < 2; ++db) o[db] = MFMA32(vfrag<64>(vt, 32 * db, 16 * st + 4 * h, lane), pb, o[db]);
;     }
; #pragma unroll
;     for (int st = 0; st < 2; ++st) {
;         const bf16x8 pb = pack8(s1, st);
; #pragma unroll
;         for (int db = 0; db < 2; ++db) o[db] = MFMA32(vfrag<64>(vt, 32 * db, 32 + 16 * st + 4 * h, lane), pb, o[db]);
;     }
; }
	v_add_f32_e32 v61, v89, v97
	s_waitcnt lgkmcnt(1)
	v_cndmask_b32_e64 v48, 0, v45, s[12:13]
	v_add_f32_e32 v48, v48, v47
	v_add_f32_e32 v44, v44, v48
	v_add_f32_e32 v49, v67, v48
	v_add_f32_e32 v48, v96, v44
	v_add_f32_e32 v44, v54, v44
	v_add_f32_e32 v51, v95, v44
	v_add_f32_e32 v44, v50, v44
	v_add_f32_e32 v37, v37, v44
	v_exp_f32_e32 v50, v37
	v_add_f32_e32 v37, v46, v45
	v_add_f32_e32 v37, v37, v47
	v_cndmask_b32_e64 v44, 0, v97, s[12:13]
	v_add_f32_e32 v44, v44, v37
	v_add_f32_e32 v45, v94, v44
	v_add_f32_e32 v44, v93, v44
	v_exp_f32_e32 v46, v45
	v_add_f32_e32 v45, v92, v44
	v_add_f32_e32 v44, v91, v44
	v_add_f32_e32 v43, v43, v44
	v_exp_f32_e32 v52, v43
	v_add_f32_e32 v43, v90, v44
	v_add_f32_e32 v42, v42, v43
	v_exp_f32_e32 v47, v45
	v_exp_f32_e32 v53, v42
	v_pk_add_f32 v[42:43], v[60:61], v[36:37]
	s_waitcnt lgkmcnt(0)
	v_pk_add_f32 v[44:45], v[56:57], v[34:35]
	v_cndmask_b32_e64 v54, 0, v35, s[12:13]
	v_pk_add_f32 v[44:45], v[44:45], v[42:43]
	ds_bpermute_b32 v35, v82, v44
	v_add_f32_e32 v37, v54, v43
	v_add_f32_e32 v41, v41, v37
	v_add_f32_e32 v37, v88, v37
	v_add_f32_e32 v40, v40, v37
	v_add_f32_e32 v37, v87, v37
	v_add_f32_e32 v39, v39, v37
	v_add_f32_e32 v37, v86, v37
	v_add_f32_e32 v37, v38, v37
	s_waitcnt lgkmcnt(0)
	v_cndmask_b32_e64 v38, 0, v35, s[12:13]
	v_add_f32_e32 v38, v38, v45
	v_add_f32_e32 v36, v36, v38
	v_add_f32_e32 v42, v85, v38
	v_add_f32_e32 v38, v84, v36
	v_exp_f32_e32 v42, v42
	v_exp_f32_e32 v38, v38
	v_exp_f32_e32 v41, v41
	v_exp_f32_e32 v40, v40
	v_exp_f32_e32 v39, v39
	v_exp_f32_e32 v37, v37
	v_add_f32_e32 v36, v60, v36
	v_add_f32_e32 v34, v34, v36
	v_add_f32_e32 v35, v44, v35
	v_add_f32_e32 v43, v83, v36
	v_add_f32_e32 v34, v81, v34
	v_add_f32_e32 v133, v35, v45
	v_cvt_pk_bf16_f32 v35, v38, v42
	v_add_u32_e32 v42, s45, v200
	v_exp_f32_e32 v43, v43
	v_exp_f32_e32 v34, v34
	v_cvt_pk_bf16_f32 v36, v37, v39
	v_cvt_pk_bf16_f32 v37, v40, v41
	ds_read_b64_tr_b16 v[70:71], v42 offset:36864
	ds_read_b64_tr_b16 v[72:73], v42 offset:38016
	ds_read_b64_tr_b16 v[82:83], v42 offset:36928
	ds_read_b64_tr_b16 v[84:85], v42 offset:38080
	ds_read_b64_tr_b16 v[86:87], v42 offset:39168
	ds_read_b64_tr_b16 v[88:89], v42 offset:40320
	v_cvt_pk_bf16_f32 v34, v34, v43
	v_exp_f32_e32 v49, v49
	v_exp_f32_e32 v48, v48
	s_waitcnt lgkmcnt(4)
	ds_read_b64_tr_b16 v[90:91], v42 offset:39232
	ds_read_b64_tr_b16 v[92:93], v42 offset:40384
	s_waitcnt lgkmcnt(6)
	v_mfma_f32_32x32x16_bf16 v[18:33], v[70:73], v[34:37], v[18:33]
	v_exp_f32_e32 v51, v51
	ds_read_b64_tr_b16 v[70:71], v42 offset:41472
	ds_read_b64_tr_b16 v[72:73], v42 offset:42624
	s_waitcnt lgkmcnt(6)
	v_mfma_f32_32x32x16_bf16 v[2:17], v[82:85], v[34:37], v[2:17]
	v_cvt_pk_bf16_f32 v34, v53, v52
	v_cvt_pk_bf16_f32 v35, v47, v46
	v_cvt_pk_bf16_f32 v36, v50, v51
	v_cvt_pk_bf16_f32 v37, v48, v49
	s_nop 0
	ds_read_b64_tr_b16 v[82:83], v42 offset:41536
	ds_read_b64_tr_b16 v[84:85], v42 offset:42688
	s_waitcnt lgkmcnt(6)
	v_mfma_f32_32x32x16_bf16 v[18:33], v[86:89], v[34:37], v[18:33]
	ds_read_b64_tr_b16 v[86:87], v42 offset:43776
	ds_read_b64_tr_b16 v[88:89], v42 offset:44928
	s_waitcnt lgkmcnt(6)
	v_mfma_f32_32x32x16_bf16 v[2:17], v[90:93], v[34:37], v[2:17]
	v_cvt_pk_bf16_f32 v34, v66, v69
	v_cvt_pk_bf16_f32 v35, v58, v55
	v_cvt_pk_bf16_f32 v36, v80, v79
	v_cvt_pk_bf16_f32 v37, v78, v59
	s_nop 0
	ds_read_b64_tr_b16 v[90:91], v42 offset:43840
	ds_read_b64_tr_b16 v[92:93], v42 offset:44992
	s_waitcnt lgkmcnt(6)
	v_mfma_f32_32x32x16_bf16 v[18:33], v[70:73], v[34:37], v[18:33]
	s_waitcnt lgkmcnt(4)
	v_mfma_f32_32x32x16_bf16 v[2:17], v[82:85], v[34:37], v[2:17]
	v_cvt_pk_bf16_f32 v34, v77, v76
	v_cvt_pk_bf16_f32 v35, v75, v74
	v_cvt_pk_bf16_f32 v36, v65, v64
	v_cvt_pk_bf16_f32 v37, v63, v62
	s_nop 0
	s_waitcnt lgkmcnt(2)
	v_mfma_f32_32x32x16_bf16 v[18:33], v[86:89], v[34:37], v[18:33]
	s_waitcnt lgkmcnt(0)
	v_mfma_f32_32x32x16_bf16 v[2:17], v[90:93], v[34:37], v[2:17]

; #define LAS __attribute__((address_space(3)))
; #define MFMA32(a, b, c) __builtin_amdgcn_mfma_f32_32x32x16_bf16((a), (b), (c), 0, 0, 0)
; __device__ __forceinline__ float fexp2(float x) { return __builtin_amdgcn_exp2f(x); }
; __device__ __forceinline__ float flog2(float x) { return __builtin_amdgcn_logf(x); }
; __device__ __forceinline__ void stick_block(f32x16& s, float& Rr, int t, int kbase, int h, bool diag) {
;     float u[16], gs[4], pg[4];
; #pragma unroll
;     for (int i = 0; i < 16; ++i) {
;         const float z = s[i];
;         const float sp = fmaxf(z, 0.f) + flog2(1.0f + fexp2(-fabsf(z)));
;         const int j = kbase + (i & 3) + 8 * (i >> 2) + 4 * h;
;         const bool valid = !diag || (j < t);
;         u[i] = valid ? -sp : 0.f;
;         s[i] = valid ? (z - sp) : -__builtin_inff();
;     }
; __device__ __forceinline__ void qk_tile(LAS unsigned char* ks, const bf16x8 (&qf)[4], int r, int h, f32x16& s0, f32x16& s1) {
;     bf16x8 kf[8];
; #pragma unroll
;     for (int kk = 0; kk < 4; ++kk) {
;         kf[2 * kk]     = *(const LAS bf16x8*)(ks + (r * KPITCH + 16 * kk + 8 * h) * 2);
;         kf[2 * kk + 1] = *(const LAS bf16x8*)(ks + ((32 + r) * KPITCH + 16 * kk + 8 * h) * 2);
;     }
; #pragma unroll
;     for (int i = 0; i < 16; ++i) { s0[i] = 0.f; s1[i] = 0.f; }
; #pragma unroll
;     for (int kk = 0; kk < 4; ++kk) { s0 = MFMA32(kf[2 * kk], qf[kk], s0); s1 = MFMA32(kf[2 * kk + 1], qf[kk], s1); }
; }
.LBB0_628:
	v_add_u32_e32 v132, s45, v206
	ds_read_b128 v[34:37], v132 offset:4608
	ds_read_b128 v[38:41], v132
	ds_read_b128 v[42:45], v132 offset:32
	ds_read_b128 v[46:49], v132 offset:4640
	ds_read_b128 v[50:53], v132 offset:64
	ds_read_b128 v[54:57], v132 offset:4672
	ds_read_b128 v[58:61], v132 offset:96
	ds_read_b128 v[62:65], v132 offset:4704
	s_waitcnt lgkmcnt(7)
	v_mfma_f32_32x32x16_bf16 v[82:97], v[34:37], v[98:101], 0
	v_cmp_ge_i32_e32 vcc, s36, v137
	s_waitcnt lgkmcnt(4)
	v_mfma_f32_32x32x16_bf16 v[82:97], v[46:49], v[102:105], v[82:97]
	v_mfma_f32_32x32x16_bf16 v[66:81], v[38:41], v[98:101], 0
	s_waitcnt lgkmcnt(2)
	v_mfma_f32_32x32x16_bf16 v[82:97], v[54:57], v[106:109], v[82:97]
	v_mfma_f32_32x32x16_bf16 v[66:81], v[42:45], v[102:105], v[66:81]
	s_waitcnt lgkmcnt(0)
	v_mfma_f32_32x32x16_bf16 v[82:97], v[62:65], v[110:113], v[82:97]
	v_mfma_f32_32x32x16_bf16 v[66:81], v[50:53], v[106:109], v[66:81]
	ds_read_b128 v[34:37], v132 offset:9216
	ds_read_b128 v[50:53], v132 offset:13824
	ds_read_b128 v[140:143], v132 offset:9248
	ds_read_b128 v[144:147], v132 offset:13856
	ds_read_b128 v[148:151], v132 offset:9280
	ds_read_b128 v[152:155], v132 offset:13888
	ds_read_b128 v[158:161], v132 offset:9312
	ds_read_b128 v[162:165], v132 offset:13920
	s_nop 2
	v_exp_f32_e64 v135, -|v82|
	v_max_f32_e32 v134, v82, v82
	v_max_f32_e32 v134, 0, v134
	v_add_f32_e32 v135, 1.0, v135
	v_log_f32_e32 v135, v135
	s_waitcnt lgkmcnt(7)
	v_mfma_f32_32x32x16_bf16 v[34:49], v[34:37], v[98:101], 0
	v_add_f32_e32 v135, v134, v135
	v_sub_f32_e32 v82, v82, v135
	s_waitcnt lgkmcnt(5)
	v_mfma_f32_32x32x16_bf16 v[34:49], v[140:143], v[102:105], v[34:49]
	v_add_u32_e32 v140, s36, v198
	v_subrev_u32_e32 v132, 31, v140
	v_cmp_ge_i32_e64 s[14:15], v132, v138
	v_exp_f32_e64 v132, -|v83|
	s_and_b64 s[14:15], vcc, s[14:15]
	v_cndmask_b32_e64 v142, v82, v238, s[14:15]
	v_max_f32_e32 v82, v83, v83
	v_add_f32_e32 v132, 1.0, v132
	v_log_f32_e32 v132, v132
	v_max_f32_e32 v82, 0, v82
	v_cndmask_b32_e64 v134, -v135, 0, s[14:15]
	v_mfma_f32_32x32x16_bf16 v[66:81], v[58:61], v[110:113], v[66:81]
	v_add_f32_e32 v132, v82, v132
	v_subrev_u32_e32 v82, 30, v140
	v_cmp_ge_i32_e64 s[14:15], v82, v138
	s_and_b64 s[14:15], vcc, s[14:15]
	v_sub_f32_e32 v83, v83, v132
	v_cndmask_b32_e64 v82, -v132, 0, s[14:15]
	v_exp_f32_e64 v132, -|v84|
	v_cndmask_b32_e64 v143, v83, v238, s[14:15]
	v_max_f32_e32 v83, v84, v84
	v_max_f32_e32 v83, 0, v83
	v_add_f32_e32 v132, 1.0, v132
	v_log_f32_e32 v132, v132
	v_mfma_f32_32x32x16_bf16 v[50:65], v[50:53], v[98:101], 0
	v_subrev_u32_e32 v141, 63, v140
	v_add_f32_e32 v83, v83, v132
	v_subrev_u32_e32 v132, 29, v140
	v_cmp_ge_i32_e64 s[14:15], v132, v138
	s_and_b64 s[14:15], vcc, s[14:15]
	s_nop 0
	v_cndmask_b32_e64 v132, -v83, 0, s[14:15]
	v_sub_f32_e32 v83, v84, v83
	v_exp_f32_e64 v84, -|v85|
	s_waitcnt lgkmcnt(4)
	v_mfma_f32_32x32x16_bf16 v[50:65], v[144:147], v[102:105], v[50:65]
	v_cndmask_b32_e64 v144, v83, v238, s[14:15]
	v_max_f32_e32 v83, v85, v85
	v_add_f32_e32 v84, 1.0, v84
	v_log_f32_e32 v84, v84
	v_max_f32_e32 v83, 0, v83
	v_add_f32_e32 v83, v83, v84
	v_subrev_u32_e32 v84, 28, v140
	v_cmp_ge_i32_e64 s[14:15], v84, v138
	s_and_b64 s[14:15], vcc, s[14:15]
	s_waitcnt lgkmcnt(3)
	v_mfma_f32_32x32x16_bf16 v[34:49], v[148:151], v[106:109], v[34:49]
	v_cndmask_b32_e64 v84, -v83, 0, s[14:15]
	v_sub_f32_e32 v83, v85, v83
	v_exp_f32_e64 v85, -|v86|
	v_cndmask_b32_e64 v145, v83, v238, s[14:15]
	v_max_f32_e32 v83, v86, v86
	v_max_f32_e32 v83, 0, v83
	v_add_f32_e32 v85, 1.0, v85
	v_log_f32_e32 v85, v85
	s_waitcnt lgkmcnt(2)
	v_mfma_f32_32x32x16_bf16 v[50:65], v[152:155], v[106:109], v[50:65]
	v_add_f32_e32 v85, v83, v85
	v_subrev_u32_e32 v83, 23, v140
	v_cmp_ge_i32_e64 s[14:15], v83, v138
	s_and_b64 s[14:15], vcc, s[14:15]
	s_nop 0
	v_cndmask_b32_e64 v83, -v85, 0, s[14:15]
	v_sub_f32_e32 v85, v86, v85
	v_exp_f32_e64 v86, -|v87|
	v_cndmask_b32_e64 v146, v85, v238, s[14:15]
	v_max_f32_e32 v85, v87, v87
	v_max_f32_e32 v85, 0, v85
	v_add_f32_e32 v86, 1.0, v86
	v_log_f32_e32 v86, v86
	s_waitcnt lgkmcnt(1)
	v_mfma_f32_32x32x16_bf16 v[34:49], v[158:161], v[110:113], v[34:49]
	v_add_f32_e32 v85, v85, v86
	v_subrev_u32_e32 v86, 22, v140
	v_cmp_ge_i32_e64 s[14:15], v86, v138
	v_exp_f32_e64 v86, -|v88|
	s_and_b64 s[14:15], vcc, s[14:15]
	v_cndmask_b32_e64 v147, -v85, 0, s[14:15]
	v_sub_f32_e32 v85, v87, v85
	v_add_f32_e32 v86, 1.0, v86
	v_log_f32_e32 v86, v86
	v_cndmask_b32_e64 v148, v85, v238, s[14:15]
	v_max_f32_e32 v85, v88, v88
	v_max_f32_e32 v85, 0, v85
	v_add_f32_e32 v85, v85, v86
	v_subrev_u32_e32 v86, 21, v140
	v_cmp_ge_i32_e64 s[14:15], v86, v138
	v_exp_f32_e64 v86, -|v89|
	s_and_b64 s[14:15], vcc, s[14:15]
	v_cndmask_b32_e64 v149, -v85, 0, s[14:15]
	v_sub_f32_e32 v85, v88, v85
	v_add_f32_e32 v86, 1.0, v86
	v_log_f32_e32 v86, v86
	v_cndmask_b32_e64 v150, v85, v238, s[14:15]
	v_max_f32_e32 v85, v89, v89
	v_max_f32_e32 v85, 0, v85
	v_add_f32_e32 v85, v85, v86
	v_subrev_u32_e32 v86, 20, v140
	v_cmp_ge_i32_e64 s[14:15], v86, v138
	v_exp_f32_e64 v86, -|v90|
	s_and_b64 s[14:15], vcc, s[14:15]
	v_cndmask_b32_e64 v151, -v85, 0, s[14:15]
	v_sub_f32_e32 v85, v89, v85
	v_add_f32_e32 v86, 1.0, v86
	v_log_f32_e32 v86, v86
	v_cndmask_b32_e64 v152, v85, v238, s[14:15]
	v_max_f32_e32 v85, v90, v90
	v_max_f32_e32 v85, 0, v85
	v_add_f32_e32 v85, v85, v86
	v_add_u32_e32 v86, -15, v140
	v_cmp_ge_i32_e64 s[14:15], v86, v138
	v_exp_f32_e64 v86, -|v91|
	s_and_b64 s[14:15], vcc, s[14:15]
	v_cndmask_b32_e64 v87, -v85, 0, s[14:15]
	v_sub_f32_e32 v85, v90, v85
	v_add_f32_e32 v86, 1.0, v86
	v_log_f32_e32 v86, v86
	v_cndmask_b32_e64 v153, v85, v238, s[14:15]
	v_max_f32_e32 v85, v91, v91
; __device__ __forceinline__ float fexp2(float x) { return __builtin_amdgcn_exp2f(x); }
; __device__ __forceinline__ float flog2(float x) { return __builtin_amdgcn_logf(x); }
; __device__ __forceinline__ void stick_block(f32x16& s, float& Rr, int t, int kbase, int h, bool diag) {
;     float u[16], gs[4], pg[4];
; #pragma unroll
;     for (int i = 0; i < 16; ++i) {
;         const float z = s[i];
;         const float sp = fmaxf(z, 0.f) + flog2(1.0f + fexp2(-fabsf(z)));
;         const int j = kbase + (i & 3) + 8 * (i >> 2) + 4 * h;
;         const bool valid = !diag || (j < t);
;         u[i] = valid ? -sp : 0.f;
;         s[i] = valid ? (z - sp) : -__builtin_inff();
;     }
; #pragma unroll
;     for (int c = 0; c < 4; ++c) { gs[c] = (u[4 * c] + u[4 * c + 1]) + (u[4 * c + 2] + u[4 * c + 3]); pg[c] = __shfl_xor(gs[c], 32); }
;     float run = Rr;
; #pragma unroll
;     for (int c = 3; c >= 0; --c) {
;         float tl = run + ((h == 0) ? pg[c] : 0.f);
; #pragma unroll
;     ...
;         run += gs[c] + pg[c];
;     }
;     Rr = run;
; }
	v_max_f32_e32 v85, 0, v85
	v_add_f32_e32 v85, v85, v86
	v_add_u32_e32 v86, -14, v140
	v_cmp_ge_i32_e64 s[14:15], v86, v138
	v_exp_f32_e64 v86, -|v92|
	s_and_b64 s[14:15], vcc, s[14:15]
	v_cndmask_b32_e64 v154, -v85, 0, s[14:15]
	v_sub_f32_e32 v85, v91, v85
	v_add_f32_e32 v86, 1.0, v86
	v_log_f32_e32 v86, v86
	v_cndmask_b32_e64 v155, v85, v238, s[14:15]
	v_max_f32_e32 v85, v92, v92
	v_max_f32_e32 v85, 0, v85
	v_add_f32_e32 v85, v85, v86
	v_add_u32_e32 v86, -13, v140
	v_cmp_ge_i32_e64 s[14:15], v86, v138
	v_exp_f32_e64 v86, -|v93|
	s_and_b64 s[14:15], vcc, s[14:15]
	v_cndmask_b32_e64 v158, -v85, 0, s[14:15]
	v_sub_f32_e32 v85, v92, v85
	v_add_f32_e32 v86, 1.0, v86
	v_log_f32_e32 v86, v86
	v_cndmask_b32_e64 v92, v85, v238, s[14:15]
	v_max_f32_e32 v85, v93, v93
	v_max_f32_e32 v85, 0, v85
	v_add_f32_e32 v85, v85, v86
	v_add_u32_e32 v86, -12, v140
	v_cmp_ge_i32_e64 s[14:15], v86, v138
	v_exp_f32_e64 v86, -|v94|
	v_exp_f32_e64 v89, -|v95|
	s_and_b64 s[14:15], vcc, s[14:15]
	v_cndmask_b32_e64 v159, -v85, 0, s[14:15]
	v_add_f32_e32 v86, 1.0, v86
	v_log_f32_e32 v86, v86
	v_sub_f32_e32 v85, v93, v85
	v_cndmask_b32_e64 v91, v85, v238, s[14:15]
	v_max_f32_e32 v85, v94, v94
	v_add_f32_e32 v89, 1.0, v89
	v_max_f32_e32 v85, 0, v85
	v_log_f32_e32 v89, v89
	v_add_f32_e32 v85, v85, v86
	v_add_u32_e32 v86, -7, v140
	v_exp_f32_e64 v93, -|v96|
	v_cmp_ge_i32_e64 s[14:15], v86, v138
	v_max_f32_e32 v86, v95, v95
	s_and_b64 s[14:15], vcc, s[14:15]
	v_max_f32_e32 v86, 0, v86
	v_cndmask_b32_e64 v88, -v85, 0, s[14:15]
	v_sub_f32_e32 v85, v94, v85
	v_add_f32_e32 v86, v86, v89
	v_add_u32_e32 v89, -6, v140
	v_cndmask_b32_e64 v85, v85, v238, s[14:15]
	v_cmp_ge_i32_e64 s[14:15], v89, v138
	v_add_f32_e32 v93, 1.0, v93
	s_and_b64 s[14:15], vcc, s[14:15]
	v_log_f32_e32 v93, v93
	v_cndmask_b32_e64 v90, -v86, 0, s[14:15]
	v_sub_f32_e32 v86, v95, v86
	v_exp_f32_e64 v95, -|v97|
	v_cndmask_b32_e64 v89, v86, v238, s[14:15]
	v_max_f32_e32 v86, v96, v96
	v_max_f32_e32 v86, 0, v86
	v_add_f32_e32 v86, v86, v93
	v_add_u32_e32 v93, -5, v140
	v_cmp_ge_i32_e64 s[14:15], v93, v138
	v_add_f32_e32 v95, 1.0, v95
	s_and_b64 s[14:15], vcc, s[14:15]
	v_log_f32_e32 v95, v95
	v_cndmask_b32_e64 v93, -v86, 0, s[14:15]
	v_sub_f32_e32 v86, v96, v86
	v_cndmask_b32_e64 v94, v86, v238, s[14:15]
	v_max_f32_e32 v86, v97, v97
	v_max_f32_e32 v86, 0, v86
	v_add_f32_e32 v86, v86, v95
	v_add_u32_e32 v95, -4, v140
	v_cmp_ge_i32_e64 s[14:15], v95, v138
	s_and_b64 s[14:15], vcc, s[14:15]
	v_add_f32_e32 v83, v83, v147
	v_cndmask_b32_e64 v95, -v86, 0, s[14:15]
	v_sub_f32_e32 v86, v97, v86
	v_and_b32_e32 v97, 64, v236
	v_cndmask_b32_e64 v96, v86, v238, s[14:15]
	v_xor_b32_e32 v86, 32, v236
	v_add_u32_e32 v97, 64, v97
	v_cmp_lt_i32_e64 s[14:15], v86, v97
	v_add_f32_e32 v97, v149, v151
	v_add_f32_e32 v135, v83, v97
	v_add_f32_e32 v87, v87, v154
	v_add_f32_e32 v97, v158, v159
	v_cndmask_b32_e64 v86, v236, v86, s[14:15]
	v_add_f32_e32 v97, v87, v97
	v_add_f32_e32 v87, v88, v90
	v_add_f32_e32 v88, v93, v95
	v_lshlrev_b32_e32 v86, 2, v86
	v_add_f32_e32 v161, v87, v88
	s_waitcnt lgkmcnt(0)
	v_mfma_f32_32x32x16_bf16 v[50:65], v[162:165], v[110:113], v[50:65]
	ds_bpermute_b32 v162, v86, v161
	ds_bpermute_b32 v160, v86, v97
	ds_bpermute_b32 v83, v86, v135
	v_cmp_ge_i32_e64 s[14:15], v141, v138
	s_and_b64 s[14:15], vcc, s[14:15]
	s_waitcnt lgkmcnt(2)
	v_cndmask_b32_e64 v87, 0, v162, s[12:13]
	v_add_f32_e32 v88, v133, v87
	v_add_f32_e32 v95, v95, v88
	v_add_f32_e32 v93, v93, v95
	v_add_f32_e32 v90, v90, v93
	v_add_f32_e32 v85, v85, v90
	v_exp_f32_e32 v90, v85
	v_add_f32_e32 v85, v161, v162
	v_add_f32_e32 v89, v89, v93
	v_add_f32_e32 v85, v133, v85
	s_waitcnt lgkmcnt(1)
	v_cndmask_b32_e64 v93, 0, v160, s[12:13]
	v_add_f32_e32 v93, v93, v85
	v_add_f32_e32 v91, v91, v93
	v_add_f32_e32 v93, v159, v93
	v_add_f32_e32 v133, v97, v160
	v_add_f32_e32 v87, v96, v88
	v_add_f32_e32 v88, v94, v95
	v_add_f32_e32 v94, v158, v93
	v_pk_add_f32 v[96:97], v[132:133], v[84:85]
	s_waitcnt lgkmcnt(0)
	v_pk_add_f32 v[134:135], v[134:135], v[82:83]
	v_add_f32_e32 v92, v92, v93
	v_add_f32_e32 v93, v155, v94
	v_add_f32_e32 v94, v154, v94
	v_pk_add_f32 v[154:155], v[134:135], v[96:97]
	v_cndmask_b32_e64 v95, 0, v83, s[12:13]
	ds_bpermute_b32 v83, v86, v154
	v_exp_f32_e64 v135, -|v66|
	v_add_f32_e32 v95, v95, v97
	v_add_f32_e32 v96, v151, v95
	v_add_f32_e32 v97, v149, v96
	s_waitcnt lgkmcnt(0)
; __device__ __forceinline__ float fexp2(float x) { return __builtin_amdgcn_exp2f(x); }
; __device__ __forceinline__ float flog2(float x) { return __builtin_amdgcn_logf(x); }
; __device__ __forceinline__ void stick_block(f32x16& s, float& Rr, int t, int kbase, int h, bool diag) {
;     float u[16], gs[4], pg[4];
; #pragma unroll
;     for (int i = 0; i < 16; ++i) {
;         const float z = s[i];
;         const float sp = fmaxf(z, 0.f) + flog2(1.0f + fexp2(-fabsf(z)));
;         const int j = kbase + (i & 3) + 8 * (i >> 2) + 4 * h;
;         const bool valid = !diag || (j < t);
;         u[i] = valid ? -sp : 0.f;
;         s[i] = valid ? (z - sp) : -__builtin_inff();
;     }
	v_cndmask_b32_e64 v133, 0, v83, s[12:13]
	v_add_f32_e32 v134, v133, v155
	v_add_f32_e32 v133, v145, v134
	v_add_f32_e32 v134, v84, v134
	v_add_f32_e32 v84, v144, v134
	v_add_f32_e32 v134, v132, v134
	v_add_f32_e32 v82, v82, v134
	v_add_f32_e32 v135, 1.0, v135
	v_add_f32_e32 v82, v142, v82
	v_log_f32_e32 v135, v135
	v_add_f32_e32 v132, v143, v134
	v_exp_f32_e32 v134, v82
	v_add_f32_e32 v82, v154, v83
	v_add_f32_e32 v83, v82, v155
	v_max_f32_e32 v82, v66, v66
	v_max_f32_e32 v82, 0, v82
	v_add_f32_e32 v82, v82, v135
	v_cndmask_b32_e64 v145, -v82, 0, s[14:15]
	v_sub_f32_e32 v66, v66, v82
	v_exp_f32_e64 v82, -|v67|
	v_cndmask_b32_e64 v135, v66, v238, s[14:15]
	v_max_f32_e32 v66, v67, v67
	v_max_f32_e32 v66, 0, v66
	v_add_f32_e32 v82, 1.0, v82
	v_log_f32_e32 v82, v82
	v_add_f32_e32 v85, v152, v95
	v_add_f32_e32 v95, v150, v96
	v_add_f32_e32 v96, v148, v97
	v_add_f32_e32 v66, v66, v82
	v_subrev_u32_e32 v82, 62, v140
	v_cmp_ge_i32_e64 s[14:15], v82, v138
	s_and_b64 s[14:15], vcc, s[14:15]
	v_add_f32_e32 v97, v147, v97
	v_cndmask_b32_e64 v141, -v66, 0, s[14:15]
	v_sub_f32_e32 v66, v67, v66
	v_exp_f32_e64 v67, -|v68|
	v_cndmask_b32_e64 v142, v66, v238, s[14:15]
	v_max_f32_e32 v66, v68, v68
	v_max_f32_e32 v66, 0, v66
	v_add_f32_e32 v67, 1.0, v67
	v_log_f32_e32 v67, v67
	v_add_f32_e32 v97, v146, v97
	v_add_f32_e32 v94, v153, v94
	v_exp_f32_e64 v155, -|v81|
	v_add_f32_e32 v66, v66, v67
	v_subrev_u32_e32 v67, 61, v140
	v_cmp_ge_i32_e64 s[14:15], v67, v138
	v_exp_f32_e64 v67, -|v69|
	s_and_b64 s[14:15], vcc, s[14:15]
	v_cndmask_b32_e64 v143, -v66, 0, s[14:15]
	v_sub_f32_e32 v66, v68, v66
	v_add_f32_e32 v67, 1.0, v67
	v_log_f32_e32 v67, v67
	v_cndmask_b32_e64 v144, v66, v238, s[14:15]
	v_max_f32_e32 v66, v69, v69
	v_max_f32_e32 v66, 0, v66
	v_add_f32_e32 v66, v66, v67
	v_subrev_u32_e32 v67, 60, v140
	v_cmp_ge_i32_e64 s[14:15], v67, v138
	v_exp_f32_e64 v67, -|v70|
	s_and_b64 s[14:15], vcc, s[14:15]
	v_cndmask_b32_e64 v146, -v66, 0, s[14:15]
	v_sub_f32_e32 v66, v69, v66
	v_add_f32_e32 v67, 1.0, v67
	v_log_f32_e32 v67, v67
	v_exp_f32_e64 v68, -|v71|
	v_cndmask_b32_e64 v147, v66, v238, s[14:15]
	v_max_f32_e32 v66, v70, v70
	v_max_f32_e32 v66, 0, v66
	v_add_f32_e32 v67, v66, v67
	v_subrev_u32_e32 v66, 55, v140
	v_cmp_ge_i32_e64 s[14:15], v66, v138
	v_add_f32_e32 v68, 1.0, v68
	s_and_b64 s[14:15], vcc, s[14:15]
	v_log_f32_e32 v68, v68
	v_cndmask_b32_e64 v66, -v67, 0, s[14:15]
	v_sub_f32_e32 v67, v70, v67
	v_exp_f32_e64 v69, -|v72|
	v_cndmask_b32_e64 v148, v67, v238, s[14:15]
	v_max_f32_e32 v67, v71, v71
	v_max_f32_e32 v67, 0, v67
	v_add_f32_e32 v67, v67, v68
	v_subrev_u32_e32 v68, 54, v140
	v_cmp_ge_i32_e64 s[14:15], v68, v138
	v_add_f32_e32 v69, 1.0, v69
	s_and_b64 s[14:15], vcc, s[14:15]
	v_log_f32_e32 v69, v69
	v_cndmask_b32_e64 v68, -v67, 0, s[14:15]
	v_sub_f32_e32 v67, v71, v67
	v_cndmask_b32_e64 v149, v67, v238, s[14:15]
	v_max_f32_e32 v67, v72, v72
	v_max_f32_e32 v67, 0, v67
	v_add_f32_e32 v67, v67, v69
	v_subrev_u32_e32 v69, 53, v140
	v_cmp_ge_i32_e64 s[14:15], v69, v138
	v_exp_f32_e64 v69, -|v73|
	s_and_b64 s[14:15], vcc, s[14:15]
	v_cndmask_b32_e64 v82, -v67, 0, s[14:15]
	v_sub_f32_e32 v67, v72, v67
	v_add_f32_e32 v69, 1.0, v69
	v_log_f32_e32 v69, v69
	v_cndmask_b32_e64 v72, v67, v238, s[14:15]
	v_max_f32_e32 v67, v73, v73
	v_max_f32_e32 v67, 0, v67
	v_add_f32_e32 v67, v67, v69
	v_subrev_u32_e32 v69, 52, v140
	v_cmp_ge_i32_e64 s[14:15], v69, v138
	v_exp_f32_e64 v69, -|v74|
	s_and_b64 s[14:15], vcc, s[14:15]
	v_cndmask_b32_e64 v70, -v67, 0, s[14:15]
	v_sub_f32_e32 v67, v73, v67
	v_add_f32_e32 v69, 1.0, v69
	v_log_f32_e32 v69, v69
	v_exp_f32_e64 v71, -|v75|
	v_cndmask_b32_e64 v73, v67, v238, s[14:15]
	v_max_f32_e32 v67, v74, v74
	v_max_f32_e32 v67, 0, v67
	v_add_f32_e32 v67, v67, v69
	v_subrev_u32_e32 v69, 47, v140
	v_cmp_ge_i32_e64 s[14:15], v69, v138
	v_add_f32_e32 v71, 1.0, v71
	s_and_b64 s[14:15], vcc, s[14:15]
	v_log_f32_e32 v71, v71
	v_cndmask_b32_e64 v69, -v67, 0, s[14:15]
	v_sub_f32_e32 v67, v74, v67
	v_cndmask_b32_e64 v150, v67, v238, s[14:15]
	v_max_f32_e32 v67, v75, v75
	v_max_f32_e32 v67, 0, v67
	v_add_f32_e32 v67, v67, v71
	v_subrev_u32_e32 v71, 46, v140
	v_cmp_ge_i32_e64 s[14:15], v71, v138
	v_exp_f32_e64 v71, -|v76|
	s_and_b64 s[14:15], vcc, s[14:15]
	v_cndmask_b32_e64 v151, -v67, 0, s[14:15]
	v_sub_f32_e32 v67, v75, v67
	v_add_f32_e32 v71, 1.0, v71
	v_log_f32_e32 v71, v71
	v_cndmask_b32_e64 v152, v67, v238, s[14:15]
	v_max_f32_e32 v67, v76, v76
	v_max_f32_e32 v67, 0, v67
	v_add_f32_e32 v67, v67, v71
	v_subrev_u32_e32 v71, 45, v140
	v_cmp_ge_i32_e64 s[14:15], v71, v138
	v_exp_f32_e64 v71, -|v77|
	s_and_b64 s[14:15], vcc, s[14:15]
	v_cndmask_b32_e64 v153, -v67, 0, s[14:15]
	v_sub_f32_e32 v67, v76, v67
	v_add_f32_e32 v71, 1.0, v71
	v_log_f32_e32 v71, v71
	v_cndmask_b32_e64 v76, v67, v238, s[14:15]
	v_max_f32_e32 v67, v77, v77
	v_max_f32_e32 v67, 0, v67
	v_add_f32_e32 v67, v67, v71
	v_subrev_u32_e32 v71, 44, v140
	v_cmp_ge_i32_e64 s[14:15], v71, v138
	v_exp_f32_e64 v71, -|v78|
	s_and_b64 s[14:15], vcc, s[14:15]
	v_cndmask_b32_e64 v154, -v67, 0, s[14:15]
	v_sub_f32_e32 v67, v77, v67
	v_add_f32_e32 v71, 1.0, v71
	v_log_f32_e32 v71, v71
	v_exp_f32_e64 v75, -|v79|
	v_cndmask_b32_e64 v77, v67, v238, s[14:15]
	v_max_f32_e32 v67, v78, v78
	v_max_f32_e32 v67, 0, v67
	v_add_f32_e32 v67, v67, v71
	v_subrev_u32_e32 v71, 39, v140
	v_cmp_ge_i32_e64 s[14:15], v71, v138
	v_add_f32_e32 v75, 1.0, v75
	s_and_b64 s[14:15], vcc, s[14:15]
	v_log_f32_e32 v75, v75
	v_cndmask_b32_e64 v71, -v67, 0, s[14:15]
	v_sub_f32_e32 v67, v78, v67
	v_cndmask_b32_e64 v74, v67, v238, s[14:15]
	v_max_f32_e32 v67, v79, v79
	v_max_f32_e32 v67, 0, v67
	v_add_f32_e32 v67, v67, v75
	v_subrev_u32_e32 v75, 38, v140
	v_cmp_ge_i32_e64 s[14:15], v75, v138
	s_and_b64 s[14:15], vcc, s[14:15]
	v_add_f32_e32 v155, 1.0, v155
	v_cndmask_b32_e64 v75, -v67, 0, s[14:15]
	v_sub_f32_e32 v67, v79, v67
	v_exp_f32_e64 v79, -|v80|
	v_cndmask_b32_e64 v78, v67, v238, s[14:15]
	v_max_f32_e32 v67, v80, v80
	v_max_f32_e32 v67, 0, v67
	v_add_f32_e32 v79, 1.0, v79
	v_log_f32_e32 v79, v79
	v_log_f32_e32 v155, v155
	v_add_f32_e32 v71, v71, v75
	v_exp_f32_e32 v85, v85
	v_add_f32_e32 v67, v67, v79
	v_subrev_u32_e32 v79, 37, v140
	v_cmp_ge_i32_e64 s[14:15], v79, v138
	s_and_b64 s[14:15], vcc, s[14:15]
	v_exp_f32_e32 v95, v95
	v_cndmask_b32_e64 v79, -v67, 0, s[14:15]
	v_sub_f32_e32 v67, v80, v67
	v_cndmask_b32_e64 v80, v67, v238, s[14:15]
	v_max_f32_e32 v67, v81, v81
	v_max_f32_e32 v67, 0, v67
	v_add_f32_e32 v67, v67, v155
	v_subrev_u32_e32 v155, 36, v140
	v_cmp_ge_i32_e64 s[14:15], v155, v138
	s_and_b64 vcc, vcc, s[14:15]
	v_cndmask_b32_e64 v155, -v67, 0, vcc
	v_add_f32_e32 v159, v79, v155
	v_add_f32_e32 v71, v71, v159
	ds_bpermute_b32 v159, v86, v71
	v_sub_f32_e32 v67, v81, v67
	v_cndmask_b32_e32 v81, v67, v238, vcc
	v_add_f32_e32 v67, v145, v141
	v_add_f32_e32 v145, v143, v146
	v_add_f32_e32 v145, v67, v145
	v_add_f32_e32 v67, v69, v151
	v_add_f32_e32 v69, v153, v154
	v_add_f32_e32 v67, v67, v69
	s_waitcnt lgkmcnt(0)
; #define LAS __attribute__((address_space(3)))
; #define MFMA32(a, b, c) __builtin_amdgcn_mfma_f32_32x32x16_bf16((a), (b), (c), 0, 0, 0)
; __device__ __forceinline__ void stick_block(f32x16& s, float& Rr, int t, int kbase, int h, bool diag) {
;     ...
; #pragma unroll
;     for (int c = 0; c < 4; ++c) { gs[c] = (u[4 * c] + u[4 * c + 1]) + (u[4 * c + 2] + u[4 * c + 3]); pg[c] = __shfl_xor(gs[c], 32); }
;     float run = Rr;
; #pragma unroll
;     for (int c = 3; c >= 0; --c) {
;         float tl = run + ((h == 0) ? pg[c] : 0.f);
; #pragma unroll
;     ...
;         run += gs[c] + pg[c];
;     }
;     Rr = run;
; }
; __device__ __forceinline__ void pv_tile(LAS unsigned char* vt, const f32x16& s0, const f32x16& s1, int h, int lane, f32x16 (&o)[2]) {
; #pragma unroll
;     for (int st = 0; st < 2; ++st) {
;         const bf16x8 pb = pack8(s0, st);
; #pragma unroll
;         for (int db = 0; db < 2; ++db) o[db] = MFMA32(vfrag<64>(vt, 32 * db, 16 * st + 4 * h, lane), pb, o[db]);
;     }
; #pragma unroll
;     for (int st = 0; st < 2; ++st) {
;         const bf16x8 pb = pack8(s1, st);
; #pragma unroll
;         for (int db = 0; db < 2; ++db) o[db] = MFMA32(vfrag<64>(vt, 32 * db, 32 + 16 * st + 4 * h, lane), pb, o[db]);
;     }
; }
	v_cndmask_b32_e64 v160, 0, v159, s[12:13]
	ds_bpermute_b32 v69, v86, v67
	v_add_f32_e32 v160, v83, v160
	v_add_f32_e32 v155, v155, v160
	v_add_f32_e32 v79, v79, v155
	v_add_f32_e32 v75, v75, v79
	v_add_f32_e32 v74, v74, v75
	v_add_f32_e32 v71, v71, v159
	v_add_f32_e32 v81, v81, v160
	v_exp_f32_e32 v160, v74
	v_pk_add_f32 v[74:75], v[82:83], v[70:71]
	s_waitcnt lgkmcnt(0)
	v_pk_add_f32 v[66:67], v[66:67], v[68:69]
	v_add_f32_e32 v78, v78, v79
	v_pk_add_f32 v[66:67], v[66:67], v[74:75]
	v_add_f32_e32 v80, v80, v155
	v_exp_f32_e32 v155, v78
	v_cndmask_b32_e64 v78, 0, v69, s[12:13]
	ds_bpermute_b32 v69, v86, v66
	ds_bpermute_b32 v158, v86, v145
	v_add_f32_e32 v71, v78, v75
	v_add_f32_e32 v74, v77, v71
	v_add_f32_e32 v71, v154, v71
	v_exp_f32_e32 v83, v74
	v_add_f32_e32 v74, v76, v71
	v_add_f32_e32 v71, v153, v71
	v_exp_f32_e32 v154, v74
	v_add_f32_e32 v74, v152, v71
	v_exp_f32_e32 v152, v74
	s_waitcnt lgkmcnt(1)
	v_cndmask_b32_e64 v74, 0, v69, s[12:13]
	v_add_f32_e32 v66, v66, v69
	v_add_f32_e32 v74, v74, v67
	v_add_f32_e32 v67, v66, v67
	s_waitcnt lgkmcnt(0)
	v_cndmask_b32_e64 v66, 0, v158, s[12:13]
	v_add_f32_e32 v70, v70, v74
	v_add_f32_e32 v66, v66, v67
	v_add_f32_e32 v72, v72, v70
	v_add_f32_e32 v70, v82, v70
	v_add_f32_e32 v69, v147, v66
	v_add_f32_e32 v66, v146, v66
	v_add_f32_e32 v73, v73, v74
	v_exp_f32_e32 v76, v72
	v_add_f32_e32 v72, v149, v70
	v_add_f32_e32 v68, v68, v70
	v_exp_f32_e32 v70, v69
	v_add_f32_e32 v69, v144, v66
	v_exp_f32_e32 v75, v73
	v_exp_f32_e32 v73, v69
	v_add_f32_e32 v66, v143, v66
	v_add_f32_e32 v69, v142, v66
	v_add_f32_e32 v66, v141, v66
	v_add_f32_e32 v68, v148, v68
	v_add_f32_e32 v66, v135, v66
	v_cvt_pk_bf16_f32 v73, v73, v70
	v_add_u32_e32 v70, s45, v200
	v_exp_f32_e32 v74, v72
	v_exp_f32_e32 v68, v68
	v_exp_f32_e32 v72, v69
	v_exp_f32_e32 v66, v66
	v_cvt_pk_bf16_f32 v75, v76, v75
	ds_read_b64_tr_b16 v[146:147], v70 offset:36864
	ds_read_b64_tr_b16 v[148:149], v70 offset:38016
	ds_read_b64_tr_b16 v[162:163], v70 offset:36928
	ds_read_b64_tr_b16 v[164:165], v70 offset:38080
	ds_read_b64_tr_b16 v[166:167], v70 offset:39168
	ds_read_b64_tr_b16 v[168:169], v70 offset:40320
	v_cvt_pk_bf16_f32 v74, v68, v74
	v_cvt_pk_bf16_f32 v72, v66, v72
	v_add_f32_e32 v71, v151, v71
	v_add_f32_e32 v71, v150, v71
	s_waitcnt lgkmcnt(4)
	ds_read_b64_tr_b16 v[170:171], v70 offset:39232
	ds_read_b64_tr_b16 v[172:173], v70 offset:40384
	s_waitcnt lgkmcnt(6)
	v_mfma_f32_32x32x16_bf16 v[18:33], v[146:149], v[72:75], v[18:33]
	v_exp_f32_e32 v81, v81
	v_exp_f32_e32 v80, v80
	v_exp_f32_e32 v71, v71
	v_exp_f32_e32 v96, v96
	v_exp_f32_e32 v97, v97
	v_exp_f32_e32 v133, v133
	ds_read_b64_tr_b16 v[146:147], v70 offset:41472
	ds_read_b64_tr_b16 v[148:149], v70 offset:42624
	s_waitcnt lgkmcnt(6)
	v_mfma_f32_32x32x16_bf16 v[2:17], v[162:165], v[72:75], v[2:17]
	v_cvt_pk_bf16_f32 v72, v71, v152
	v_cvt_pk_bf16_f32 v73, v154, v83
	v_cvt_pk_bf16_f32 v74, v160, v155
	v_cvt_pk_bf16_f32 v75, v80, v81
	v_exp_f32_e32 v84, v84
	v_exp_f32_e32 v132, v132
	ds_read_b64_tr_b16 v[162:163], v70 offset:41536
	ds_read_b64_tr_b16 v[164:165], v70 offset:42688
	s_waitcnt lgkmcnt(6)
	v_mfma_f32_32x32x16_bf16 v[18:33], v[166:169], v[72:75], v[18:33]
	v_exp_f32_e64 v71, -|v50|
	v_add_u32_e32 v66, 0xffffffa1, v140
	v_exp_f32_e32 v87, v87
	v_exp_f32_e32 v88, v88
	v_exp_f32_e32 v89, v89
	v_exp_f32_e32 v91, v91
	ds_read_b64_tr_b16 v[166:167], v70 offset:43776
	ds_read_b64_tr_b16 v[168:169], v70 offset:44928
	s_waitcnt lgkmcnt(6)
	v_mfma_f32_32x32x16_bf16 v[2:17], v[170:173], v[72:75], v[2:17]
	v_cvt_pk_bf16_f32 v72, v134, v132
	v_cvt_pk_bf16_f32 v73, v84, v133
	v_cvt_pk_bf16_f32 v74, v97, v96
	v_cvt_pk_bf16_f32 v75, v95, v85
	v_exp_f32_e32 v92, v92
	v_exp_f32_e32 v93, v93
	ds_read_b64_tr_b16 v[170:171], v70 offset:43840
	ds_read_b64_tr_b16 v[172:173], v70 offset:44992
	s_waitcnt lgkmcnt(6)
	v_mfma_f32_32x32x16_bf16 v[18:33], v[146:149], v[72:75], v[18:33]
	v_exp_f32_e32 v94, v94
	v_add_f32_e32 v71, 1.0, v71
	v_cmp_ge_i32_e64 s[14:15], v66, v138
	v_exp_f32_e64 v66, -|v51|
	v_log_f32_e32 v71, v71
	v_max_f32_e32 v68, v50, v50
	s_waitcnt lgkmcnt(4)
	v_mfma_f32_32x32x16_bf16 v[2:17], v[162:165], v[72:75], v[2:17]
	v_cvt_pk_bf16_f32 v72, v94, v93
	v_cvt_pk_bf16_f32 v73, v92, v91
	v_cvt_pk_bf16_f32 v74, v90, v89
	v_cvt_pk_bf16_f32 v75, v88, v87
	v_max_f32_e32 v68, 0, v68
	v_add_f32_e32 v66, 1.0, v66
	s_waitcnt lgkmcnt(2)
	v_mfma_f32_32x32x16_bf16 v[18:33], v[166:169], v[72:75], v[18:33]
	v_cmp_gt_i32_e32 vcc, s44, v137
	v_add_f32_e32 v68, v68, v71
	v_log_f32_e32 v66, v66
	s_and_b64 s[14:15], vcc, s[14:15]
	v_sub_f32_e32 v50, v50, v68
	v_cndmask_b32_e64 v71, v50, v238, s[14:15]
	v_max_f32_e32 v50, v51, v51
	v_max_f32_e32 v50, 0, v50
	v_add_f32_e32 v50, v50, v66
	v_add_u32_e32 v66, 0xffffffa2, v140
	s_waitcnt lgkmcnt(0)
; __device__ __forceinline__ float fexp2(float x) { return __builtin_amdgcn_exp2f(x); }
; __device__ __forceinline__ float flog2(float x) { return __builtin_amdgcn_logf(x); }
; __device__ __forceinline__ void stick_block(f32x16& s, float& Rr, int t, int kbase, int h, bool diag) {
;     float u[16], gs[4], pg[4];
; #pragma unroll
;     for (int i = 0; i < 16; ++i) {
;         const float z = s[i];
;         const float sp = fmaxf(z, 0.f) + flog2(1.0f + fexp2(-fabsf(z)));
;         const int j = kbase + (i & 3) + 8 * (i >> 2) + 4 * h;
;         const bool valid = !diag || (j < t);
;         u[i] = valid ? -sp : 0.f;
;         s[i] = valid ? (z - sp) : -__builtin_inff();
;     }
	v_mfma_f32_32x32x16_bf16 v[2:17], v[170:173], v[72:75], v[2:17]
	v_cndmask_b32_e64 v78, -v68, 0, s[14:15]
	v_cmp_ge_i32_e64 s[14:15], v66, v138
	s_and_b64 s[14:15], vcc, s[14:15]
	v_add_f32_e32 v69, v145, v158
	v_cndmask_b32_e64 v72, -v50, 0, s[14:15]
	v_sub_f32_e32 v50, v51, v50
	v_exp_f32_e64 v51, -|v52|
	v_cndmask_b32_e64 v73, v50, v238, s[14:15]
	v_max_f32_e32 v50, v52, v52
	v_max_f32_e32 v50, 0, v50
	v_add_f32_e32 v51, 1.0, v51
	v_log_f32_e32 v51, v51
	v_add_u32_e32 v82, 0xffffff81, v140
	v_add_f32_e32 v50, v50, v51
	v_add_u32_e32 v51, 0xffffffa3, v140
	v_cmp_ge_i32_e64 s[14:15], v51, v138
	v_exp_f32_e64 v51, -|v53|
	s_and_b64 s[14:15], vcc, s[14:15]
	v_cndmask_b32_e64 v74, -v50, 0, s[14:15]
	v_sub_f32_e32 v50, v52, v50
	v_add_f32_e32 v51, 1.0, v51
	v_log_f32_e32 v51, v51
	v_cndmask_b32_e64 v75, v50, v238, s[14:15]
	v_max_f32_e32 v50, v53, v53
	v_max_f32_e32 v50, 0, v50
	v_add_f32_e32 v50, v50, v51
	v_add_u32_e32 v51, 0xffffffa4, v140
	v_cmp_ge_i32_e64 s[14:15], v51, v138
	v_exp_f32_e64 v51, -|v54|
	s_and_b64 s[14:15], vcc, s[14:15]
	v_cndmask_b32_e64 v76, -v50, 0, s[14:15]
	v_sub_f32_e32 v50, v53, v50
	v_add_f32_e32 v51, 1.0, v51
	v_log_f32_e32 v51, v51
	v_exp_f32_e64 v52, -|v55|
	v_cndmask_b32_e64 v77, v50, v238, s[14:15]
	v_max_f32_e32 v50, v54, v54
	v_max_f32_e32 v50, 0, v50
	v_add_f32_e32 v50, v50, v51
	v_add_u32_e32 v51, 0xffffffa9, v140
	v_cmp_ge_i32_e64 s[14:15], v51, v138
	v_add_f32_e32 v52, 1.0, v52
	s_and_b64 s[14:15], vcc, s[14:15]
	v_log_f32_e32 v52, v52
	v_cndmask_b32_e64 v79, -v50, 0, s[14:15]
	v_sub_f32_e32 v50, v54, v50
	v_cndmask_b32_e64 v51, v50, v238, s[14:15]
	v_max_f32_e32 v50, v55, v55
	v_max_f32_e32 v50, 0, v50
	v_add_f32_e32 v50, v50, v52
	v_add_u32_e32 v52, 0xffffffaa, v140
	v_cmp_ge_i32_e64 s[14:15], v52, v138
	v_exp_f32_e64 v52, -|v56|
	s_and_b64 s[14:15], vcc, s[14:15]
	v_cndmask_b32_e64 v53, -v50, 0, s[14:15]
	v_sub_f32_e32 v50, v55, v50
	v_add_f32_e32 v52, 1.0, v52
	v_log_f32_e32 v52, v52
	v_cndmask_b32_e64 v80, v50, v238, s[14:15]
	v_max_f32_e32 v50, v56, v56
	v_max_f32_e32 v50, 0, v50
	v_add_f32_e32 v50, v50, v52
	v_add_u32_e32 v52, 0xffffffab, v140
	v_cmp_ge_i32_e64 s[14:15], v52, v138
	v_exp_f32_e64 v52, -|v57|
	s_and_b64 s[14:15], vcc, s[14:15]
	v_cndmask_b32_e64 v81, -v50, 0, s[14:15]
	v_sub_f32_e32 v50, v56, v50
	v_add_f32_e32 v52, 1.0, v52
	v_log_f32_e32 v52, v52
	v_cndmask_b32_e64 v83, v50, v238, s[14:15]
	v_max_f32_e32 v50, v57, v57
	v_max_f32_e32 v50, 0, v50
	v_add_f32_e32 v50, v50, v52
	v_add_u32_e32 v52, 0xffffffac, v140
	v_cmp_ge_i32_e64 s[14:15], v52, v138
	v_exp_f32_e64 v52, -|v58|
	s_and_b64 s[14:15], vcc, s[14:15]
	v_cndmask_b32_e64 v84, -v50, 0, s[14:15]
	v_sub_f32_e32 v50, v57, v50
	v_add_f32_e32 v52, 1.0, v52
	v_log_f32_e32 v52, v52
	v_cndmask_b32_e64 v85, v50, v238, s[14:15]
	v_max_f32_e32 v50, v58, v58
	v_max_f32_e32 v50, 0, v50
	v_add_f32_e32 v50, v50, v52
	v_add_u32_e32 v52, 0xffffffb1, v140
	v_cmp_ge_i32_e64 s[14:15], v52, v138
	v_exp_f32_e64 v52, -|v59|
	s_and_b64 s[14:15], vcc, s[14:15]
	v_cndmask_b32_e64 v68, -v50, 0, s[14:15]
	v_sub_f32_e32 v50, v58, v50
	v_add_f32_e32 v52, 1.0, v52
	v_log_f32_e32 v52, v52
	v_cndmask_b32_e64 v87, v50, v238, s[14:15]
	v_max_f32_e32 v50, v59, v59
	v_max_f32_e32 v50, 0, v50
	v_add_f32_e32 v50, v50, v52
	v_add_u32_e32 v52, 0xffffffb2, v140
	v_cmp_ge_i32_e64 s[14:15], v52, v138
	v_exp_f32_e64 v52, -|v60|
	s_and_b64 s[14:15], vcc, s[14:15]
	v_cndmask_b32_e64 v66, -v50, 0, s[14:15]
	v_sub_f32_e32 v50, v59, v50
	v_add_f32_e32 v52, 1.0, v52
	v_log_f32_e32 v52, v52
	v_cndmask_b32_e64 v88, v50, v238, s[14:15]
	v_max_f32_e32 v50, v60, v60
	v_max_f32_e32 v50, 0, v50
	v_add_f32_e32 v50, v50, v52
	v_add_u32_e32 v52, 0xffffffb3, v140
	v_cmp_ge_i32_e64 s[14:15], v52, v138
	v_exp_f32_e64 v52, -|v61|
	s_and_b64 s[14:15], vcc, s[14:15]
	v_cndmask_b32_e64 v54, -v50, 0, s[14:15]
	v_sub_f32_e32 v50, v60, v50
	v_add_f32_e32 v52, 1.0, v52
	v_log_f32_e32 v52, v52
	v_cndmask_b32_e64 v89, v50, v238, s[14:15]
	v_max_f32_e32 v50, v61, v61
	v_max_f32_e32 v50, 0, v50
	v_add_f32_e32 v50, v50, v52
	v_add_u32_e32 v52, 0xffffffb4, v140
	v_cmp_ge_i32_e64 s[14:15], v52, v138
	v_exp_f32_e64 v52, -|v62|
	s_and_b64 s[14:15], vcc, s[14:15]
	v_cndmask_b32_e64 v56, -v50, 0, s[14:15]
	v_sub_f32_e32 v50, v61, v50
	v_add_f32_e32 v52, 1.0, v52
	v_log_f32_e32 v52, v52
	v_cndmask_b32_e64 v90, v50, v238, s[14:15]
	v_max_f32_e32 v50, v62, v62
	v_max_f32_e32 v50, 0, v50
	v_add_f32_e32 v50, v50, v52
	v_add_u32_e32 v52, 0xffffffb9, v140
	v_cmp_ge_i32_e64 s[14:15], v52, v138
	v_exp_f32_e64 v52, -|v63|
	s_and_b64 s[14:15], vcc, s[14:15]
	v_cndmask_b32_e64 v55, -v50, 0, s[14:15]
	v_sub_f32_e32 v50, v62, v50
	v_add_f32_e32 v52, 1.0, v52
	v_log_f32_e32 v52, v52
	v_cndmask_b32_e64 v91, v50, v238, s[14:15]
	v_max_f32_e32 v50, v63, v63
	v_max_f32_e32 v50, 0, v50
	v_add_f32_e32 v50, v50, v52
	v_add_u32_e32 v52, 0xffffffba, v140
	v_cmp_ge_i32_e64 s[14:15], v52, v138
	v_exp_f32_e64 v52, -|v64|
	s_and_b64 s[14:15], vcc, s[14:15]
	v_cndmask_b32_e64 v92, -v50, 0, s[14:15]
	v_sub_f32_e32 v50, v63, v50
	v_add_f32_e32 v52, 1.0, v52
	v_log_f32_e32 v52, v52
	v_cndmask_b32_e64 v93, v50, v238, s[14:15]
	v_max_f32_e32 v50, v64, v64
	v_max_f32_e32 v50, 0, v50
	v_add_f32_e32 v50, v50, v52
	v_add_u32_e32 v52, 0xffffffbb, v140
	v_cmp_ge_i32_e64 s[14:15], v52, v138
	v_exp_f32_e64 v52, -|v65|
	s_and_b64 s[14:15], vcc, s[14:15]
	v_cndmask_b32_e64 v94, -v50, 0, s[14:15]
	v_sub_f32_e32 v50, v64, v50
	v_add_f32_e32 v52, 1.0, v52
	v_log_f32_e32 v52, v52
	v_cndmask_b32_e64 v63, v50, v238, s[14:15]
	v_max_f32_e32 v50, v65, v65
	v_max_f32_e32 v50, 0, v50
	v_add_f32_e32 v50, v50, v52
	v_add_u32_e32 v52, 0xffffffbc, v140
	v_cmp_ge_i32_e64 s[14:15], v52, v138
	s_and_b64 s[14:15], vcc, s[14:15]
	v_add_f32_e32 v57, v79, v53
	v_cndmask_b32_e64 v64, -v50, 0, s[14:15]
	v_add_f32_e32 v58, v81, v84
	v_add_f32_e32 v95, v57, v58
	v_add_f32_e32 v55, v55, v92
	v_add_f32_e32 v57, v94, v64
	v_add_f32_e32 v55, v55, v57
	ds_bpermute_b32 v57, v86, v55
	v_pk_add_f32 v[58:59], v[68:69], v[66:67]
	v_sub_f32_e32 v50, v65, v50
	v_cndmask_b32_e64 v62, v50, v238, s[14:15]
	ds_bpermute_b32 v96, v86, v95
	s_waitcnt lgkmcnt(1)
; __device__ __forceinline__ float fexp2(float x) { return __builtin_amdgcn_exp2f(x); }
; __device__ __forceinline__ float flog2(float x) { return __builtin_amdgcn_logf(x); }
; __device__ __forceinline__ void stick_block(f32x16& s, float& Rr, int t, int kbase, int h, bool diag) {
;     float u[16], gs[4], pg[4];
; #pragma unroll
;     for (int i = 0; i < 16; ++i) {
;         const float z = s[i];
;         const float sp = fmaxf(z, 0.f) + flog2(1.0f + fexp2(-fabsf(z)));
;         const int j = kbase + (i & 3) + 8 * (i >> 2) + 4 * h;
;         const bool valid = !diag || (j < t);
;         u[i] = valid ? -sp : 0.f;
;         s[i] = valid ? (z - sp) : -__builtin_inff();
;     }
; #pragma unroll
;     for (int c = 0; c < 4; ++c) { gs[c] = (u[4 * c] + u[4 * c + 1]) + (u[4 * c + 2] + u[4 * c + 3]); pg[c] = __shfl_xor(gs[c], 32); }
;     float run = Rr;
; #pragma unroll
;     for (int c = 3; c >= 0; --c) {
;         float tl = run + ((h == 0) ? pg[c] : 0.f);
; #pragma unroll
;     ...
;         run += gs[c] + pg[c];
;     }
;     Rr = run;
; }
	v_pk_add_f32 v[60:61], v[54:55], v[56:57]
	v_cndmask_b32_e64 v65, 0, v57, s[12:13]
	v_pk_add_f32 v[60:61], v[58:59], v[60:61]
	ds_bpermute_b32 v55, v86, v60
	v_add_f32_e32 v57, v59, v65
	v_add_f32_e32 v58, v62, v57
	v_add_f32_e32 v57, v64, v57
	v_exp_f32_e32 v62, v58
	v_add_f32_e32 v58, v63, v57
	v_add_f32_e32 v57, v94, v57
	v_exp_f32_e32 v63, v58
	v_add_f32_e32 v58, v93, v57
	v_add_f32_e32 v57, v92, v57
	v_add_f32_e32 v57, v91, v57
	v_exp_f32_e32 v65, v57
	s_waitcnt lgkmcnt(0)
	v_cndmask_b32_e64 v57, 0, v55, s[12:13]
	v_add_f32_e32 v57, v57, v61
	v_add_f32_e32 v56, v56, v57
	v_add_f32_e32 v54, v54, v56
	v_exp_f32_e32 v64, v58
	v_add_f32_e32 v58, v90, v57
	v_add_f32_e32 v57, v89, v56
	v_add_f32_e32 v56, v88, v54
	v_add_f32_e32 v54, v66, v54
	v_add_f32_e32 v54, v87, v54
	v_exp_f32_e32 v66, v54
	v_add_f32_e32 v54, v60, v55
	v_add_f32_e32 v54, v54, v61
	v_cndmask_b32_e64 v55, 0, v96, s[12:13]
	v_add_f32_e32 v55, v55, v54
	v_exp_f32_e32 v69, v56
	v_add_f32_e32 v56, v85, v55
	v_add_f32_e32 v55, v84, v55
	v_add_f32_e32 v50, v78, v72
	v_exp_f32_e32 v78, v56
	v_add_f32_e32 v56, v83, v55
	v_add_f32_e32 v55, v81, v55
	v_add_f32_e32 v53, v53, v55
	v_add_f32_e32 v51, v51, v53
	v_exp_f32_e64 v53, -|v34|
	v_exp_f32_e32 v81, v51
	v_max_f32_e32 v51, v34, v34
	v_max_f32_e32 v51, 0, v51
	v_add_f32_e32 v53, 1.0, v53
	v_log_f32_e32 v53, v53
	v_cmp_ge_i32_e64 s[14:15], v82, v138
	s_and_b64 s[14:15], vcc, s[14:15]
	v_exp_f32_e32 v67, v58
	v_add_f32_e32 v51, v51, v53
	v_cndmask_b32_e64 v58, -v51, 0, s[14:15]
	v_sub_f32_e32 v34, v34, v51
	v_exp_f32_e64 v51, -|v35|
	v_cndmask_b32_e64 v82, v34, v238, s[14:15]
	v_max_f32_e32 v34, v35, v35
	v_max_f32_e32 v34, 0, v34
	v_add_f32_e32 v51, 1.0, v51
	v_log_f32_e32 v51, v51
	v_exp_f32_e32 v79, v56
	v_add_f32_e32 v56, v80, v55
	v_exp_f32_e32 v80, v56
	v_add_f32_e32 v51, v34, v51
	v_add_u32_e32 v34, 0xffffff82, v140
	v_cmp_ge_i32_e64 s[14:15], v34, v138
	s_and_b64 s[14:15], vcc, s[14:15]
	v_sub_f32_e32 v35, v35, v51
	v_cndmask_b32_e64 v34, -v51, 0, s[14:15]
	v_exp_f32_e64 v51, -|v36|
	v_cndmask_b32_e64 v83, v35, v238, s[14:15]
	v_max_f32_e32 v35, v36, v36
	v_max_f32_e32 v35, 0, v35
	v_add_f32_e32 v51, 1.0, v51
	v_log_f32_e32 v51, v51
	v_add_f32_e32 v56, v95, v96
	v_exp_f32_e32 v68, v57
	v_add_f32_e32 v52, v74, v76
	v_add_f32_e32 v35, v35, v51
	v_add_u32_e32 v51, 0xffffff83, v140
	v_cmp_ge_i32_e64 s[14:15], v51, v138
	s_and_b64 s[14:15], vcc, s[14:15]
	v_exp_f32_e64 v51, -|v39|
	v_cndmask_b32_e64 v60, -v35, 0, s[14:15]
	v_sub_f32_e32 v35, v36, v35
	v_exp_f32_e64 v36, -|v37|
	v_cndmask_b32_e64 v84, v35, v238, s[14:15]
	v_max_f32_e32 v35, v37, v37
	v_max_f32_e32 v35, 0, v35
	v_add_f32_e32 v36, 1.0, v36
	v_log_f32_e32 v36, v36
	v_add_f32_e32 v51, 1.0, v51
	v_log_f32_e32 v51, v51
	v_add_f32_e32 v52, v50, v52
	v_add_f32_e32 v35, v35, v36
	v_add_u32_e32 v36, 0xffffff84, v140
	v_cmp_ge_i32_e64 s[14:15], v36, v138
	s_and_b64 s[14:15], vcc, s[14:15]
	ds_bpermute_b32 v50, v86, v52
	v_cndmask_b32_e64 v36, -v35, 0, s[14:15]
	v_sub_f32_e32 v35, v37, v35
	v_exp_f32_e64 v37, -|v38|
	v_cndmask_b32_e64 v85, v35, v238, s[14:15]
	v_max_f32_e32 v35, v38, v38
	v_max_f32_e32 v35, 0, v35
	v_add_f32_e32 v37, 1.0, v37
	v_log_f32_e32 v37, v37
	s_waitcnt lgkmcnt(0)
	v_cndmask_b32_e64 v61, 0, v50, s[12:13]
	v_add_f32_e32 v37, v35, v37
	v_add_u32_e32 v35, 0xffffff89, v140
	v_cmp_ge_i32_e64 s[14:15], v35, v138
	s_and_b64 s[14:15], vcc, s[14:15]
	s_nop 0
	v_cndmask_b32_e64 v35, -v37, 0, s[14:15]
	v_sub_f32_e32 v37, v38, v37
	v_cndmask_b32_e64 v38, v37, v238, s[14:15]
	v_max_f32_e32 v37, v39, v39
	v_max_f32_e32 v37, 0, v37
	v_add_f32_e32 v37, v37, v51
	v_add_u32_e32 v51, 0xffffff8a, v140
	v_cmp_ge_i32_e64 s[14:15], v51, v138
	v_exp_f32_e64 v51, -|v40|
	s_and_b64 s[14:15], vcc, s[14:15]
	v_cndmask_b32_e64 v87, -v37, 0, s[14:15]
	v_sub_f32_e32 v37, v39, v37
	v_add_f32_e32 v51, 1.0, v51
	v_log_f32_e32 v51, v51
	v_cndmask_b32_e64 v39, v37, v238, s[14:15]
	v_max_f32_e32 v37, v40, v40
	v_max_f32_e32 v37, 0, v37
	v_add_f32_e32 v37, v37, v51
	v_add_u32_e32 v51, 0xffffff8b, v140
	v_cmp_ge_i32_e64 s[14:15], v51, v138
	v_exp_f32_e64 v51, -|v41|
	s_and_b64 s[14:15], vcc, s[14:15]
	v_cndmask_b32_e64 v88, -v37, 0, s[14:15]
	v_sub_f32_e32 v37, v40, v37
	v_add_f32_e32 v51, 1.0, v51
	v_log_f32_e32 v51, v51
	v_cndmask_b32_e64 v40, v37, v238, s[14:15]
	v_max_f32_e32 v37, v41, v41
	v_max_f32_e32 v37, 0, v37
	v_add_f32_e32 v37, v37, v51
	v_add_u32_e32 v51, 0xffffff8c, v140
	v_cmp_ge_i32_e64 s[14:15], v51, v138
	v_exp_f32_e64 v51, -|v42|
	s_and_b64 s[14:15], vcc, s[14:15]
	v_cndmask_b32_e64 v89, -v37, 0, s[14:15]
	v_sub_f32_e32 v37, v41, v37
	v_add_f32_e32 v51, 1.0, v51
	v_log_f32_e32 v51, v51
	v_cndmask_b32_e64 v41, v37, v238, s[14:15]
	v_max_f32_e32 v37, v42, v42
	v_max_f32_e32 v37, 0, v37
	v_add_f32_e32 v37, v37, v51
	v_add_u32_e32 v51, 0xffffff91, v140
	v_cmp_ge_i32_e64 s[14:15], v51, v138
	v_exp_f32_e64 v51, -|v43|
	s_and_b64 s[14:15], vcc, s[14:15]
	v_cndmask_b32_e64 v90, -v37, 0, s[14:15]
	v_sub_f32_e32 v37, v42, v37
	v_add_f32_e32 v51, 1.0, v51
	v_log_f32_e32 v51, v51
	v_cndmask_b32_e64 v42, v37, v238, s[14:15]
	v_max_f32_e32 v37, v43, v43
	v_max_f32_e32 v37, 0, v37
	v_add_f32_e32 v37, v37, v51
	v_add_u32_e32 v51, 0xffffff92, v140
	v_cmp_ge_i32_e64 s[14:15], v51, v138
	v_exp_f32_e64 v51, -|v44|
	s_and_b64 s[14:15], vcc, s[14:15]
	v_cndmask_b32_e64 v91, -v37, 0, s[14:15]
	v_sub_f32_e32 v37, v43, v37
	v_add_f32_e32 v51, 1.0, v51
	v_log_f32_e32 v51, v51
	v_cndmask_b32_e64 v43, v37, v238, s[14:15]
	v_max_f32_e32 v37, v44, v44
	v_max_f32_e32 v37, 0, v37
	v_add_f32_e32 v37, v37, v51
	v_add_u32_e32 v51, 0xffffff93, v140
	v_cmp_ge_i32_e64 s[14:15], v51, v138
; #define LAS __attribute__((address_space(3)))
; #define MFMA32(a, b, c) __builtin_amdgcn_mfma_f32_32x32x16_bf16((a), (b), (c), 0, 0, 0)
; __device__ __forceinline__ void stick_block(f32x16& s, float& Rr, int t, int kbase, int h, bool diag) {
;     ...
; #pragma unroll
;     for (int c = 0; c < 4; ++c) { gs[c] = (u[4 * c] + u[4 * c + 1]) + (u[4 * c + 2] + u[4 * c + 3]); pg[c] = __shfl_xor(gs[c], 32); }
;     float run = Rr;
; #pragma unroll
;     for (int c = 3; c >= 0; --c) {
;         float tl = run + ((h == 0) ? pg[c] : 0.f);
; #pragma unroll
;     ...
;         run += gs[c] + pg[c];
;     }
;     Rr = run;
; }
; __device__ __forceinline__ void pv_tile(LAS unsigned char* vt, const f32x16& s0, const f32x16& s1, int h, int lane, f32x16 (&o)[2]) {
; #pragma unroll
;     for (int st = 0; st < 2; ++st) {
;         const bf16x8 pb = pack8(s0, st);
; #pragma unroll
;         for (int db = 0; db < 2; ++db) o[db] = MFMA32(vfrag<64>(vt, 32 * db, 16 * st + 4 * h, lane), pb, o[db]);
;     }
; #pragma unroll
;     for (int st = 0; st < 2; ++st) {
;         const bf16x8 pb = pack8(s1, st);
; #pragma unroll
;         for (int db = 0; db < 2; ++db) o[db] = MFMA32(vfrag<64>(vt, 32 * db, 32 + 16 * st + 4 * h, lane), pb, o[db]);
;     }
; }
	s_and_b64 s[14:15], vcc, s[14:15]
	v_add_f32_e32 v35, v35, v87
	v_cndmask_b32_e64 v92, -v37, 0, s[14:15]
	v_sub_f32_e32 v37, v44, v37
	v_exp_f32_e64 v44, -|v45|
	v_cndmask_b32_e64 v93, v37, v238, s[14:15]
	v_max_f32_e32 v37, v45, v45
	v_max_f32_e32 v37, 0, v37
	v_add_f32_e32 v44, 1.0, v44
	v_log_f32_e32 v44, v44
	s_nop 0
	v_add_f32_e32 v37, v37, v44
	v_add_u32_e32 v44, 0xffffff94, v140
	v_cmp_ge_i32_e64 s[14:15], v44, v138
	v_exp_f32_e64 v44, -|v46|
	s_and_b64 s[14:15], vcc, s[14:15]
	v_cndmask_b32_e64 v94, -v37, 0, s[14:15]
	v_sub_f32_e32 v37, v45, v37
	v_exp_f32_e64 v45, -|v47|
	v_add_f32_e32 v44, 1.0, v44
	v_log_f32_e32 v44, v44
	v_cndmask_b32_e64 v95, v37, v238, s[14:15]
	v_max_f32_e32 v37, v46, v46
	v_add_f32_e32 v45, 1.0, v45
	v_max_f32_e32 v37, 0, v37
	v_log_f32_e32 v45, v45
	v_add_f32_e32 v37, v37, v44
	v_add_u32_e32 v44, 0xffffff99, v140
	v_cmp_ge_i32_e64 s[14:15], v44, v138
	v_max_f32_e32 v44, v47, v47
	s_and_b64 s[14:15], vcc, s[14:15]
	v_max_f32_e32 v44, 0, v44
	v_cndmask_b32_e64 v53, -v37, 0, s[14:15]
	v_sub_f32_e32 v37, v46, v37
	v_add_f32_e32 v44, v44, v45
	v_add_u32_e32 v45, 0xffffff9a, v140
	v_cndmask_b32_e64 v37, v37, v238, s[14:15]
	v_cmp_ge_i32_e64 s[14:15], v45, v138
	v_exp_f32_e64 v45, -|v48|
	s_and_b64 s[14:15], vcc, s[14:15]
	v_cndmask_b32_e64 v51, -v44, 0, s[14:15]
	v_sub_f32_e32 v44, v47, v44
	v_add_f32_e32 v45, 1.0, v45
	v_log_f32_e32 v45, v45
	v_cndmask_b32_e64 v96, v44, v238, s[14:15]
	v_max_f32_e32 v44, v48, v48
	v_max_f32_e32 v44, 0, v44
	v_add_f32_e32 v44, v44, v45
	v_add_u32_e32 v45, 0xffffff9b, v140
	v_cmp_ge_i32_e64 s[14:15], v45, v138
	v_exp_f32_e64 v45, -|v49|
	s_and_b64 s[14:15], vcc, s[14:15]
	v_cndmask_b32_e64 v57, -v44, 0, s[14:15]
	v_sub_f32_e32 v44, v48, v44
	v_add_f32_e32 v45, 1.0, v45
	v_log_f32_e32 v45, v45
	v_cndmask_b32_e64 v48, v44, v238, s[14:15]
	v_max_f32_e32 v44, v49, v49
	v_max_f32_e32 v44, 0, v44
	v_add_f32_e32 v44, v44, v45
	v_add_u32_e32 v45, 0xffffff9c, v140
	v_cmp_ge_i32_e64 s[14:15], v45, v138
	s_and_b64 vcc, vcc, s[14:15]
	v_cndmask_b32_e64 v55, -v44, 0, vcc
	v_sub_f32_e32 v44, v49, v44
	v_cndmask_b32_e32 v49, v44, v238, vcc
	v_add_f32_e32 v44, v88, v89
	v_add_f32_e32 v59, v35, v44
	v_add_f32_e32 v44, v90, v91
	v_add_f32_e32 v45, v92, v94
	v_add_f32_e32 v90, v44, v45
	v_pk_add_f32 v[44:45], v[56:57], v[54:55]
	ds_bpermute_b32 v97, v86, v90
	v_add_f32_e32 v46, v61, v44
	v_add_f32_e32 v47, v77, v46
	v_add_f32_e32 v46, v76, v46
	v_exp_f32_e32 v54, v47
	v_add_f32_e32 v47, v75, v46
	v_add_f32_e32 v46, v74, v46
	v_exp_f32_e32 v56, v47
	v_add_f32_e32 v47, v73, v46
	v_add_f32_e32 v46, v72, v46
	v_add_f32_e32 v46, v71, v46
	v_exp_f32_e32 v73, v47
	v_exp_f32_e32 v71, v46
	v_pk_add_f32 v[46:47], v[52:53], v[50:51]
	ds_bpermute_b32 v35, v86, v59
	v_pk_add_f32 v[44:45], v[46:47], v[44:45]
	ds_bpermute_b32 v46, v86, v45
	s_waitcnt lgkmcnt(2)
	v_add_f32_e32 v61, v90, v97
	s_waitcnt lgkmcnt(0)
	v_cndmask_b32_e64 v47, 0, v46, s[12:13]
	v_add_f32_e32 v47, v44, v47
	v_add_f32_e32 v49, v49, v47
	v_add_f32_e32 v47, v55, v47
	v_add_f32_e32 v48, v48, v47
	v_add_f32_e32 v47, v57, v47
	v_add_f32_e32 v50, v96, v47
	v_add_f32_e32 v47, v51, v47
	v_add_f32_e32 v37, v37, v47
	v_exp_f32_e32 v47, v37
	v_add_f32_e32 v37, v45, v46
	v_add_f32_e32 v37, v44, v37
	v_cndmask_b32_e64 v44, 0, v97, s[12:13]
	v_add_f32_e32 v44, v44, v37
	v_add_f32_e32 v45, v95, v44
	v_add_f32_e32 v44, v94, v44
	v_exp_f32_e32 v46, v45
	v_add_f32_e32 v45, v93, v44
	v_add_f32_e32 v44, v92, v44
	v_add_f32_e32 v43, v43, v44
	v_exp_f32_e32 v52, v43
	v_add_f32_e32 v43, v91, v44
	v_add_f32_e32 v42, v42, v43
	v_exp_f32_e32 v51, v45
	v_exp_f32_e32 v53, v42
	v_pk_add_f32 v[42:43], v[60:61], v[36:37]
	v_pk_add_f32 v[44:45], v[58:59], v[34:35]
	v_cndmask_b32_e64 v55, 0, v35, s[12:13]
	v_pk_add_f32 v[44:45], v[44:45], v[42:43]
	ds_bpermute_b32 v35, v86, v44
	v_add_f32_e32 v37, v55, v43
	v_add_f32_e32 v41, v41, v37
	v_add_f32_e32 v37, v89, v37
	v_add_f32_e32 v40, v40, v37
	v_add_f32_e32 v37, v88, v37
	v_add_f32_e32 v39, v39, v37
	v_add_f32_e32 v37, v87, v37
	v_add_f32_e32 v37, v38, v37
	s_waitcnt lgkmcnt(0)
	v_cndmask_b32_e64 v38, 0, v35, s[12:13]
	v_add_f32_e32 v38, v38, v45
	v_add_f32_e32 v36, v36, v38
	v_add_f32_e32 v42, v85, v38
	v_add_f32_e32 v38, v84, v36
	v_exp_f32_e32 v41, v41
	v_exp_f32_e32 v40, v40
	v_exp_f32_e32 v39, v39
	v_exp_f32_e32 v37, v37
	v_exp_f32_e32 v42, v42
	v_exp_f32_e32 v38, v38
	v_add_f32_e32 v36, v60, v36
	v_add_f32_e32 v34, v34, v36
	v_add_f32_e32 v43, v83, v36
	v_add_f32_e32 v34, v82, v34
	v_add_f32_e32 v35, v44, v35
	v_exp_f32_e32 v43, v43
	v_exp_f32_e32 v34, v34
	v_add_f32_e32 v133, v35, v45
	v_cvt_pk_bf16_f32 v35, v38, v42
	v_cvt_pk_bf16_f32 v36, v37, v39
	v_cvt_pk_bf16_f32 v37, v40, v41
	ds_read_b64_tr_b16 v[58:59], v70 offset:46080
	ds_read_b64_tr_b16 v[60:61], v70 offset:47232
	ds_read_b64_tr_b16 v[74:75], v70 offset:46144
	ds_read_b64_tr_b16 v[76:77], v70 offset:47296
	ds_read_b64_tr_b16 v[82:83], v70 offset:48384
	ds_read_b64_tr_b16 v[84:85], v70 offset:49536
	v_cvt_pk_bf16_f32 v34, v34, v43
	v_exp_f32_e32 v49, v49
	v_exp_f32_e32 v48, v48
	s_waitcnt lgkmcnt(4)
	ds_read_b64_tr_b16 v[86:87], v70 offset:48448
	ds_read_b64_tr_b16 v[88:89], v70 offset:49600
	s_waitcnt lgkmcnt(6)
	v_mfma_f32_32x32x16_bf16 v[18:33], v[58:61], v[34:37], v[18:33]
	v_exp_f32_e32 v50, v50
	ds_read_b64_tr_b16 v[58:59], v70 offset:50688
	ds_read_b64_tr_b16 v[60:61], v70 offset:51840
	s_waitcnt lgkmcnt(6)
	v_mfma_f32_32x32x16_bf16 v[2:17], v[74:77], v[34:37], v[2:17]
	v_cvt_pk_bf16_f32 v34, v53, v52
	v_cvt_pk_bf16_f32 v35, v51, v46
	v_cvt_pk_bf16_f32 v36, v47, v50
	v_cvt_pk_bf16_f32 v37, v48, v49
	s_nop 0
	ds_read_b64_tr_b16 v[74:75], v70 offset:50752
	ds_read_b64_tr_b16 v[76:77], v70 offset:51904
	s_waitcnt lgkmcnt(6)
	v_mfma_f32_32x32x16_bf16 v[18:33], v[82:85], v[34:37], v[18:33]
	ds_read_b64_tr_b16 v[82:83], v70 offset:52992
	ds_read_b64_tr_b16 v[84:85], v70 offset:54144
	s_waitcnt lgkmcnt(6)
	v_mfma_f32_32x32x16_bf16 v[2:17], v[86:89], v[34:37], v[2:17]
	v_cvt_pk_bf16_f32 v34, v71, v73
	v_cvt_pk_bf16_f32 v35, v56, v54
	v_cvt_pk_bf16_f32 v36, v81, v80
	v_cvt_pk_bf16_f32 v37, v79, v78
	s_nop 0
	ds_read_b64_tr_b16 v[86:87], v70 offset:53056
	ds_read_b64_tr_b16 v[88:89], v70 offset:54208
	s_waitcnt lgkmcnt(6)
	v_mfma_f32_32x32x16_bf16 v[18:33], v[58:61], v[34:37], v[18:33]
	s_waitcnt lgkmcnt(4)
	v_mfma_f32_32x32x16_bf16 v[2:17], v[74:77], v[34:37], v[2:17]
	v_cvt_pk_bf16_f32 v34, v66, v69
	v_cvt_pk_bf16_f32 v35, v68, v67
	v_cvt_pk_bf16_f32 v36, v65, v64
	v_cvt_pk_bf16_f32 v37, v63, v62
	s_nop 0
	s_waitcnt lgkmcnt(2)
	v_mfma_f32_32x32x16_bf16 v[18:33], v[82:85], v[34:37], v[18:33]
	s_waitcnt lgkmcnt(0)
	v_mfma_f32_32x32x16_bf16 v[2:17], v[86:89], v[34:37], v[2:17]
	s_or_b64 exec, exec, s[18:19]
	s_andn2_b64 vcc, exec, s[58:59]
	s_mov_b64 s[18:19], -1
	s_cbranch_vccz .LBB0_626
